# C loops: far-tile bias preloaded to VGPRs; waves 4-7 barrier shifted to before PV (K tiles DMA'd 2 ahead) so the two waves of a SIMD run out of phase
# speedup vs baseline: 1.1233x; 1.0138x over previous
; __device__ __forceinline__ int v_st(int k, int c) { const int kk = (k & ~0xC) | ((k & 4) << 1) | ((k & 8) >> 1); return ((kk >> 3) * 4 + (c >> 5)) * 512 + ((kk & 7) * 32 + (c & 31)) * 2; }
; __device__ __forceinline__ int v_rd_base(int lane) { return ((lane & 3) << 3) | (((lane >> 2) & 3) << 6) | (((lane >> 4) & 1) << 5) | (((lane >> 5) & 1) << 8); }
; #define SLOAD(i, k0) do { sr_[i].vs0 = *reinterpret_cast<const bf16x8*>(&Vh[(size_t)((k0) + sr) * LDQK + sc]); sr_[i].vs1 = *reinterpret_cast<const bf16x8*>(&Vh[(size_t)((k0) + 32 + sr) * LDQK + sc]); \
;     sr_[i].ks0 = *reinterpret_cast<const bf16x8*>(&Kh[(size_t)((k0) + sr) * LDQK + sc]); sr_[i].ks1 = *reinterpret_cast<const bf16x8*>(&Kh[(size_t)((k0) + 32 + sr) * LDQK + sc]); } while (0)
; #define SWAIT() asm volatile("s_waitcnt vmcnt(4)" ::: "memory")
; #define PSM(P0, P1, MN, AL, J) partialSM<MODE>(P0, P1, m_reg, MN, AL, relq + 64 * (J), relwmin + 64 * (J), relwmax + 64 * (J), lut)
; template <int MODE>
; __device__ __forceinline__ void partialSM(f32x16& p0, f32x16& p1, float& m_reg, float& mn, float& alpha, int relh, int relw_min, int relw_max, const float* lut) {
;     ...
;       if (relw_max <= -128) { nearT = false; cfar = lut[0]; }
;       else if (relw_min >= 128) { nearT = false; cfar = lut[258]; }
; template <int MODE>
; __device__ __forceinline__ void attn_body(const bf16_t* __restrict__ Qb, const bf16_t* __restrict__ Kh, const bf16_t* __restrict__ Vh, int NT, int krel0,
;                                           char* lds, const float* __restrict__ lutg, const AttnEpi& E) {
;     ...
;   const int sr = tid >> 4, sc = (tid & 15) * 8, vst0 = v_st(sr, sc), vst1 = v_st(32 + sr, sc);
;   const int vb0 = (int)(uintptr_t)V_lds + v_rd_base(lane);
;   struct { bf16x8 vs0, vs1, ks0, ks1; } sr_[2];
;     ...
;   const int relq = krel0 - (wid * 32 + r32) + 4 * hi, relwmin = krel0 - (wid * 32 + 31), relwmax = krel0 + 63 - wid * 32;
;     ...
;   f32x16 pA0, pA1, pB0, pB1; float mnA, mnB, alA, alB; bf16x8 pa0, pa1, pa2, pa3;
;   constexpr int SE = 0, SO = 1;
;   SLOAD(SE, 0); SLOAD(SO, 64); asm volatile("s_waitcnt vmcnt(4)" ::: "memory"); SWRITE(0, SE); __syncthreads();
;   qkt<ND0, DOFF>(pA0, pA1, K_lds, qr, r32, hi); PSM(pA0, pA1, mnA, alA, 0);
;   if (2 < NT) SLOAD(SE, 2 * 64);
;   SWAIT(); SWRITE(SHM_V, SO);
;   int op = 0, oq = SHM_V, ow = 2 * SHM_V;
;   for (int j = 1; j + 1 < NT; j += 2) {
;     __syncthreads();
.LBB0_131:
	s_or_b64 exec, exec, s[64:65]
	v_add_u32_e32 v0, 0xa0, v50
	s_movk_i32 s64, 0x1200
	s_nop 3
	v_mad_i64_i32 v[2:3], s[6:7], v0, s64, 0
	v_add_u32_e32 v0, 0x80, v50
	v_or_b32_e32 v2, v2, v51
	v_mad_i64_i32 v[6:7], s[6:7], v0, s64, 0
	v_lshlrev_b64 v[2:3], 1, v[2:3]
	v_or_b32_e32 v6, v6, v51
	v_lshl_add_u64 v[4:5], s[58:59], 0, v[2:3]
	v_lshlrev_b64 v[6:7], 1, v[6:7]
	v_lshl_add_u64 v[2:3], s[0:1], 0, v[2:3]
	v_lshl_add_u64 v[8:9], s[58:59], 0, v[6:7]
	global_load_dwordx4 v[150:153], v[4:5], off
	global_load_dwordx4 v[146:149], v[8:9], off
	v_lshl_add_u64 v[4:5], s[0:1], 0, v[6:7]
	global_load_dwordx4 v[158:161], v[2:3], off
	global_load_dwordx4 v[154:157], v[4:5], off
	v_and_b32_e32 v0, 63, v188
	v_lshlrev_b32_e32 v3, 4, v0
	v_lshlrev_b32_e32 v2, 3, v0
	v_and_b32_e32 v3, 0xc0, v3
	v_lshlrev_b32_e32 v4, 1, v0
	v_and_or_b32 v3, v2, 24, v3
	v_and_b32_e32 v4, 32, v4
	v_and_b32_e32 v2, 0x100, v2
	s_cmp_lg_u32 0, -1
	v_or3_b32 v2, v3, v4, v2
	s_cselect_b32 s6, 0, 0
	v_add_u32_e32 v218, s6, v2
	v_and_b32_e32 v2, 0x3fffffc0, v188
	v_add_u32_e32 v3, s75, v211
	v_ashrrev_i32_e32 v51, 31, v50
	v_lshl_add_u32 v2, v2, 2, s89
	s_waitcnt vmcnt(4)
	s_waitcnt vmcnt(7)
	ds_write_b128 v56, v[34:37] offset:16384
	s_waitcnt vmcnt(5)
	ds_write_b128 v57, v[38:41] offset:16384
	ds_write_b128 v3, v[42:45]
	v_add_u32_e32 v3, s75, v212
	s_waitcnt vmcnt(4)
	ds_write_b128 v3, v[46:49]
	v_cmp_gt_u32_e64 s[6:7], 32, v0
	v_lshl_add_u32 v209, v52, 2, v2
	v_lshl_add_u32 v208, v54, 2, v2
	v_sub_u32_e32 v0, v54, v52
	v_lshl_add_u64 v[2:3], v[50:51], 0, s[2:3]
	s_movk_i32 s66, 0x2400
	v_sub_u32_e32 v222, v0, v53
	v_mad_u64_u32 v[4:5], s[64:65], v2, s66, 0
	v_and_b32_e32 v0, 15, v188
	v_mad_i32_i24 v3, v3, s66, v5
	v_or_b32_e32 v2, s82, v4
	v_lshlrev_b32_e32 v0, 4, v0
	v_readlane_b32 s64, v254, 14
	v_lshl_add_u64 v[2:3], v[2:3], 0, v[0:1]
	v_readlane_b32 s65, v254, 15
	v_mov_b32_e32 v14, v1
	v_mov_b32_e32 v15, v1
	v_sub_u32_e32 v220, 0, v55
	v_sub_u32_e32 v221, 0, v53
	v_lshl_add_u64 v[190:191], s[64:65], 0, v[2:3]
	v_mov_b32_e32 v0, v1
	v_mov_b32_e32 v2, v1
	v_mov_b32_e32 v3, v1
	v_mov_b32_e32 v4, v1
	v_mov_b32_e32 v5, v1
	v_mov_b32_e32 v6, v1
	v_mov_b32_e32 v7, v1
	v_mov_b32_e32 v8, v1
	v_mov_b32_e32 v9, v1
	v_mov_b32_e32 v10, v1
	v_mov_b32_e32 v11, v1
	v_mov_b32_e32 v12, v1
	v_mov_b32_e32 v13, v1
	v_mov_b64_e32 v[64:65], v[14:15]
	v_mov_b64_e32 v[48:49], v[14:15]
	v_mov_b64_e32 v[32:33], v[14:15]
	v_mov_b64_e32 v[62:63], v[12:13]
	v_mov_b64_e32 v[60:61], v[10:11]
	v_mov_b64_e32 v[58:59], v[8:9]
	v_mov_b64_e32 v[56:57], v[6:7]
	v_mov_b64_e32 v[54:55], v[4:5]
	v_mov_b64_e32 v[52:53], v[2:3]
	v_mov_b64_e32 v[50:51], v[0:1]
	v_mov_b64_e32 v[46:47], v[12:13]
	v_mov_b64_e32 v[44:45], v[10:11]
	v_mov_b64_e32 v[42:43], v[8:9]
	v_mov_b64_e32 v[40:41], v[6:7]
	v_mov_b64_e32 v[38:39], v[4:5]
	v_mov_b64_e32 v[36:37], v[2:3]
	v_mov_b64_e32 v[34:35], v[0:1]
	v_mov_b64_e32 v[30:31], v[12:13]
	v_mov_b64_e32 v[28:29], v[10:11]
	v_mov_b64_e32 v[26:27], v[8:9]
	v_mov_b64_e32 v[24:25], v[6:7]
	v_mov_b64_e32 v[22:23], v[4:5]
	v_mov_b64_e32 v[20:21], v[2:3]
	v_mov_b64_e32 v[18:19], v[0:1]
	v_mov_b64_e32 v[16:17], v[14:15]
	s_mov_b32 s80, 0
	s_mov_b32 s81, 2
	s_movk_i32 s83, 0x2400
	s_mov_b32 s74, s82
	v_mov_b32_e32 v210, 0
	s_movk_i32 s82, 0x4000
	s_mov_b32 s64, 0x8000
	v_mov_b64_e32 v[14:15], v[12:13]
	v_mov_b64_e32 v[12:13], v[10:11]
	v_mov_b64_e32 v[10:11], v[8:9]
	v_mov_b64_e32 v[8:9], v[6:7]
	v_mov_b64_e32 v[6:7], v[4:5]
	v_mov_b64_e32 v[4:5], v[2:3]
	v_mov_b64_e32 v[2:3], v[0:1]
	s_waitcnt vmcnt(0)
	v_readfirstlane_b32 s31, v179
	s_nop 3
	s_lshr_b32 s31, s31, 6
	s_lshl_b32 s30, s31, 11
	v_and_b32_e32 v150, 63, v179
	v_bfe_u32 v151, v150, 2, 3
	s_lshl_b32 s29, s31, 3
	v_or_b32_e32 v151, s29, v151
	v_and_b32_e32 v152, 4, v151
	v_lshlrev_b32_e32 v152, 1, v152
	v_and_b32_e32 v153, 8, v151
	v_lshrrev_b32_e32 v153, 1, v153
	v_and_b32_e32 v151, 0xfffffff3, v151
	v_or3_b32 v151, v151, v152, v153
	v_mul_u32_u24_e32 v151, 0x2400, v151
	v_lshrrev_b32_e32 v152, 5, v150
	v_lshlrev_b32_e32 v152, 6, v152
	v_and_b32_e32 v153, 3, v150
	v_lshlrev_b32_e32 v153, 4, v153
	v_add3_u32 v248, v151, v152, v153
	v_add_u32_e32 v249, 0x80, v248
	v_lshrrev_b32_e32 v151, 4, v150
	v_add_u32_e32 v151, s29, v151
	v_and_b32_e32 v152, 15, v150
	v_and_b32_e32 v153, 15, v151
	v_xor_b32_e32 v153, v152, v153
	v_mul_u32_u24_e32 v154, 0x2400, v151
	v_lshl_add_u32 v250, v153, 4, v154
	v_add_u32_e32 v151, 4, v151
	v_and_b32_e32 v153, 15, v151
	v_xor_b32_e32 v153, v152, v153
	v_mul_u32_u24_e32 v154, 0x2400, v151
	v_lshl_add_u32 v251, v153, 4, v154
	v_readfirstlane_b32 s26, v190
	v_readfirstlane_b32 s27, v191
	s_mul_i32 s29, s31, 0x9000
	s_add_u32 s29, s29, 0x168000
	s_sub_u32 s26, s26, s29
	s_subb_u32 s27, s27, 0
	s_sub_u32 s28, s26, 0x200
	s_subb_u32 s29, s27, 0
	s_add_i32 m0, s64, s30
	s_add_i32 m0, m0, 0xc000
	s_nop 0
	global_load_lds_dwordx4 v250, s[28:29]
	s_add_i32 m0, m0, 0x400
	s_nop 0
	global_load_lds_dwordx4 v251, s[28:29]
	s_add_u32 s28, s28, 0x90000
	s_addc_u32 s29, s29, 0
	s_waitcnt lgkmcnt(0)
	s_barrier
	v_mov_b32_e32 v160, s76
	ds_read_b32 v160, v160
	v_mov_b32_e32 v161, s41
	ds_read_b32 v161, v161
	s_waitcnt lgkmcnt(0)
.LBB0_132:
	v_readfirstlane_b32 s20, v221
	v_readfirstlane_b32 s21, v220
	s_nop 3
	s_add_i32 s22, s20, s77
	s_addk_i32 s22, 0x7f
	s_add_i32 s23, s21, s77
	s_addk_i32 s23, 0x40
	s_add_i32 s24, s22, 64
	s_add_i32 s25, s23, 64
	s_mov_b32 s79, s64
	s_cmp_lt_u32 s31, 4
	s_cbranch_scc0 .Ldp_6
	s_waitcnt vmcnt(0) lgkmcnt(0)
	s_barrier
; #define SBAR() __builtin_amdgcn_sched_barrier(0)
; __device__ __forceinline__ void finishSM(f32x16& p0, f32x16& p1, float alpha, float& l_reg, bf16x8& pa0, bf16x8& pa1, bf16x8& pa2, bf16x8& pa3) {
; #pragma unroll
;   for (int r = 0; r < 16; ++r) p1[r] = __builtin_amdgcn_exp2f(p1[r]);
;   float ps = 0;
; #pragma unroll
;   for (int r = 0; r < 16; ++r) ps += p0[r];
; #pragma unroll
;   for (int r = 0; r < 16; ++r) ps += p1[r];
;   { auto rr = __builtin_amdgcn_permlane32_swap(__float_as_uint(ps), __float_as_uint(ps), false, false);
;     ps = __uint_as_float(rr[0]) + __uint_as_float(rr[1]); }
;   l_reg = l_reg * alpha + ps;
;     ...
;   PK4(p0, 0, pa0); PK4(p0, 8, pa1); PK4(p1, 0, pa2); PK4(p1, 8, pa3);
;     ...
; }
; template <int ND0, int DOFF>
; __device__ __forceinline__ void qkt(f32x16& p0, f32x16& p1, const char* Ks, const bf16x8* qr, int r32, int hi) {
;   p0 = f32x16{}; p1 = f32x16{};
; #pragma unroll
;   for (int d0 = 0; d0 < ND0; ++d0) { const int cb = ((d0 + DOFF) * 16 + hi * 8) * 2;
;     bf16x8 b0 = *reinterpret_cast<const bf16x8*>(Ks + KSWZ(r32, cb));
;     bf16x8 b1 = *reinterpret_cast<const bf16x8*>(Ks + KSWZ(32 + r32, cb));
;     p0 = __builtin_amdgcn_mfma_f32_32x32x16_bf16(b0, qr[d0], p0, 0, 0, 0);
;     p1 = __builtin_amdgcn_mfma_f32_32x32x16_bf16(b1, qr[d0], p1, 0, 0, 0); }
; }
; __device__ __forceinline__ int v_st(int k, int c) { const int kk = (k & ~0xC) | ((k & 4) << 1) | ((k & 8) >> 1); return ((kk >> 3) * 4 + (c >> 5)) * 512 + ((kk & 7) * 32 + (c & 31)) * 2; }
; __device__ __forceinline__ int v_rd_base(int lane) { return ((lane & 3) << 3) | (((lane >> 2) & 3) << 6) | (((lane >> 4) & 1) << 5) | (((lane >> 5) & 1) << 8); }
; template <int OFF> __device__ __forceinline__ s16x4 tr_read(int vb) {
;   s16x4 r; asm volatile("ds_read_b64_tr_b16 %0, %1 offset:%2" : "=&v"(r) : "v"(vb), "i"(OFF) : "memory"); return r;
; }
; template <int D0> __device__ __forceinline__ void pv_one(f32x16& od, int vb, bf16x8 pa0, bf16x8 pa1, bf16x8 pa2, bf16x8 pa3) {
;   const s16x4 l0 = tr_read<v_rd_off(D0, 0, 0)>(vb), h0 = tr_read<v_rd_off(D0, 0, 1)>(vb), l1 = tr_read<v_rd_off(D0, 1, 0)>(vb), h1 = tr_read<v_rd_off(D0, 1, 1)>(vb);
;   const s16x4 l2 = tr_read<v_rd_off(D0, 2, 0)>(vb), h2 = tr_read<v_rd_off(D0, 2, 1)>(vb), l3 = tr_read<v_rd_off(D0, 3, 0)>(vb), h3 = tr_read<v_rd_off(D0, 3, 1)>(vb);
;   asm volatile("s_waitcnt lgkmcnt(0)" ::: "memory"); SBAR();
.Ldp_6:
	s_add_i32 s64, s82, 0
	v_add_u32_e32 v0, s64, v213
	ds_read_b128 v[98:101], v0 offset:49152
	ds_read_b128 v[102:105], v0 offset:57344
	v_add_u32_e32 v0, s64, v214
	ds_read_b128 v[162:165], v0 offset:49152
	ds_read_b128 v[166:169], v0 offset:57344
	v_add_u32_e32 v0, s64, v215
	s_waitcnt lgkmcnt(3)
	v_mfma_f32_32x32x16_bf16 v[114:129], v[98:101], v[142:145], 0
	s_waitcnt lgkmcnt(2)
	v_mfma_f32_32x32x16_bf16 v[98:113], v[102:105], v[142:145], 0
	s_waitcnt lgkmcnt(1)
	v_mfma_f32_32x32x16_bf16 v[114:129], v[162:165], v[138:141], v[114:129]
	s_waitcnt lgkmcnt(0)
	v_mfma_f32_32x32x16_bf16 v[98:113], v[166:169], v[138:141], v[98:113]
	ds_read_b128 v[162:165], v0 offset:49152
	ds_read_b128 v[166:169], v0 offset:57344
	v_add_u32_e32 v0, s64, v216
	s_waitcnt lgkmcnt(1)
	v_mfma_f32_32x32x16_bf16 v[114:129], v[162:165], v[134:137], v[114:129]
	s_waitcnt lgkmcnt(0)
	v_mfma_f32_32x32x16_bf16 v[98:113], v[166:169], v[134:137], v[98:113]
	ds_read_b128 v[162:165], v0 offset:49152
	ds_read_b128 v[166:169], v0 offset:57344
	v_exp_f32_e32 v0, v82
	v_exp_f32_e32 v82, v83
	v_exp_f32_e32 v83, v84
	v_exp_f32_e32 v84, v85
	v_exp_f32_e32 v85, v86
	v_exp_f32_e32 v86, v87
	v_exp_f32_e32 v87, v88
	v_exp_f32_e32 v88, v89
	v_exp_f32_e32 v89, v90
	v_exp_f32_e32 v90, v91
	v_exp_f32_e32 v91, v92
	v_exp_f32_e32 v92, v93
	v_exp_f32_e32 v93, v94
	v_exp_f32_e32 v94, v95
	v_exp_f32_e32 v95, v96
	v_exp_f32_e32 v96, v97
	v_add_f32_e32 v97, v67, v66
	v_add_f32_e32 v97, v68, v97
	v_add_f32_e32 v97, v69, v97
	v_add_f32_e32 v97, v70, v97
	v_add_f32_e32 v97, v71, v97
	v_add_f32_e32 v97, v72, v97
	v_add_f32_e32 v97, v73, v97
	v_add_f32_e32 v97, v74, v97
	v_add_f32_e32 v97, v75, v97
	v_add_f32_e32 v97, v76, v97
	v_add_f32_e32 v97, v77, v97
	v_add_f32_e32 v97, v78, v97
	v_add_f32_e32 v97, v79, v97
	v_add_f32_e32 v97, v80, v97
	v_add_f32_e32 v97, v81, v97
	v_add_f32_e32 v97, v0, v97
	v_add_f32_e32 v97, v82, v97
	v_add_f32_e32 v97, v83, v97
	v_add_f32_e32 v97, v84, v97
	v_add_f32_e32 v97, v85, v97
	v_add_f32_e32 v97, v86, v97
	v_add_f32_e32 v97, v87, v97
	v_add_f32_e32 v97, v88, v97
	v_add_f32_e32 v97, v89, v97
	v_add_f32_e32 v97, v90, v97
	s_waitcnt lgkmcnt(1)
	v_mfma_f32_32x32x16_bf16 v[114:129], v[162:165], v[130:133], v[114:129]
	v_add_f32_e32 v97, v91, v97
	v_add_f32_e32 v97, v92, v97
	v_add_f32_e32 v97, v93, v97
	v_add_f32_e32 v97, v94, v97
	v_add_f32_e32 v97, v95, v97
	v_add_f32_e32 v223, v96, v97
	v_mov_b32_e32 v224, v223
	s_waitcnt lgkmcnt(0)
	v_mfma_f32_32x32x16_bf16 v[98:113], v[166:169], v[130:133], v[98:113]
	v_cvt_pk_bf16_f32 v66, v66, v67
	v_cvt_pk_bf16_f32 v67, v68, v69
	v_cvt_pk_bf16_f32 v68, v70, v71
	v_cvt_pk_bf16_f32 v69, v72, v73
	v_cvt_pk_bf16_f32 v70, v74, v75
	v_cvt_pk_bf16_f32 v71, v76, v77
	v_cvt_pk_bf16_f32 v72, v78, v79
	v_cvt_pk_bf16_f32 v73, v80, v81
	v_cvt_pk_bf16_f32 v74, v0, v82
	v_cvt_pk_bf16_f32 v75, v83, v84
	v_cvt_pk_bf16_f32 v76, v85, v86
	v_cvt_pk_bf16_f32 v77, v87, v88
	v_cvt_pk_bf16_f32 v78, v89, v90
	v_cvt_pk_bf16_f32 v79, v91, v92
	v_cvt_pk_bf16_f32 v80, v93, v94
	v_cvt_pk_bf16_f32 v81, v95, v96
	v_permlane32_swap_b32_e32 v223, v224
	v_permlane32_swap_b32_e32 v66, v68
	v_permlane32_swap_b32_e32 v67, v69
	v_permlane32_swap_b32_e32 v70, v72
	v_permlane32_swap_b32_e32 v71, v73
	v_permlane32_swap_b32_e32 v74, v76
	v_permlane32_swap_b32_e32 v75, v77
	v_permlane32_swap_b32_e32 v78, v80
	v_permlane32_swap_b32_e32 v79, v81
	s_cmp_lt_u32 s31, 4
	s_cbranch_scc1 .Ldp_5
	s_waitcnt vmcnt(0) lgkmcnt(0)
	s_barrier
.Ldp_5:
	s_add_i32 m0, s79, s30
	s_nop 0
	global_load_lds_dwordx4 v248, s[26:27]
	s_add_i32 m0, m0, 0x400
	s_nop 0
	global_load_lds_dwordx4 v249, s[26:27]
	s_add_i32 m0, s80, s30
	s_add_i32 m0, m0, 0xc000
	s_nop 0
	global_load_lds_dwordx4 v250, s[28:29]
	s_add_i32 m0, m0, 0x400
	s_nop 0
	global_load_lds_dwordx4 v251, s[28:29]
	s_add_u32 s26, s26, 0x90000
	s_addc_u32 s27, s27, 0
	s_add_u32 s28, s28, 0x90000
	s_addc_u32 s29, s29, 0
	v_add_u32_e32 v0, s80, v218
	ds_read_b64_tr_b16 v[82:83], v0 offset:0
	ds_read_b64_tr_b16 v[84:85], v0 offset:0x800
	ds_read_b64_tr_b16 v[86:87], v0 offset:0x1000
	ds_read_b64_tr_b16 v[88:89], v0 offset:0x1800
	ds_read_b64_tr_b16 v[90:91], v0 offset:0x2000
	ds_read_b64_tr_b16 v[92:93], v0 offset:0x2800
	ds_read_b64_tr_b16 v[94:95], v0 offset:0x3000
	ds_read_b64_tr_b16 v[96:97], v0 offset:0x3800
	s_waitcnt lgkmcnt(0)
	s_nop 0
	v_mfma_f32_32x32x16_bf16 v[50:65], v[66:69], v[82:85], v[50:65]
	ds_read_b64_tr_b16 v[82:83], v0 offset:0x200
	ds_read_b64_tr_b16 v[84:85], v0 offset:0xa00
	v_mfma_f32_32x32x16_bf16 v[50:65], v[70:73], v[86:89], v[50:65]
	ds_read_b64_tr_b16 v[86:87], v0 offset:0x1200
	ds_read_b64_tr_b16 v[88:89], v0 offset:0x1a00
	v_mfma_f32_32x32x16_bf16 v[50:65], v[74:77], v[90:93], v[50:65]
	ds_read_b64_tr_b16 v[90:91], v0 offset:0x2200
	ds_read_b64_tr_b16 v[92:93], v0 offset:0x2a00
	v_mfma_f32_32x32x16_bf16 v[50:65], v[78:81], v[94:97], v[50:65]
	ds_read_b64_tr_b16 v[94:95], v0 offset:0x3200
	ds_read_b64_tr_b16 v[96:97], v0 offset:0x3a00
	s_waitcnt lgkmcnt(0)
	v_mfma_f32_32x32x16_bf16 v[34:49], v[66:69], v[82:85], v[34:49]
	ds_read_b64_tr_b16 v[82:83], v0 offset:0x400
	ds_read_b64_tr_b16 v[84:85], v0 offset:0xc00
	v_mfma_f32_32x32x16_bf16 v[34:49], v[70:73], v[86:89], v[34:49]
	ds_read_b64_tr_b16 v[86:87], v0 offset:0x1400
	ds_read_b64_tr_b16 v[88:89], v0 offset:0x1c00
	v_mfma_f32_32x32x16_bf16 v[34:49], v[74:77], v[90:93], v[34:49]
	ds_read_b64_tr_b16 v[90:91], v0 offset:0x2400
	ds_read_b64_tr_b16 v[92:93], v0 offset:0x2c00
	v_mfma_f32_32x32x16_bf16 v[34:49], v[78:81], v[94:97], v[34:49]
	ds_read_b64_tr_b16 v[94:95], v0 offset:0x3400
	ds_read_b64_tr_b16 v[96:97], v0 offset:0x3c00
	s_waitcnt lgkmcnt(0)
	v_mfma_f32_32x32x16_bf16 v[18:33], v[66:69], v[82:85], v[18:33]
	ds_read_b64_tr_b16 v[82:83], v0 offset:0x600
	ds_read_b64_tr_b16 v[84:85], v0 offset:0xe00
	v_mfma_f32_32x32x16_bf16 v[18:33], v[70:73], v[86:89], v[18:33]
	ds_read_b64_tr_b16 v[86:87], v0 offset:0x1600
	ds_read_b64_tr_b16 v[88:89], v0 offset:0x1e00
	v_mfma_f32_32x32x16_bf16 v[18:33], v[74:77], v[90:93], v[18:33]
	ds_read_b64_tr_b16 v[90:91], v0 offset:0x2600
	ds_read_b64_tr_b16 v[92:93], v0 offset:0x2e00
	v_mfma_f32_32x32x16_bf16 v[18:33], v[78:81], v[94:97], v[18:33]
	ds_read_b64_tr_b16 v[94:95], v0 offset:0x3600
	ds_read_b64_tr_b16 v[96:97], v0 offset:0x3e00
	s_waitcnt lgkmcnt(0)
	v_mfma_f32_32x32x16_bf16 v[2:17], v[66:69], v[82:85], v[2:17]
	s_cmp_gt_i32 s95, s22
	s_cselect_b64 s[64:65], -1, 0
	s_cmp_lt_i32 s15, s22
	s_cselect_b64 vcc, -1, 0
	v_mov_b32_e32 v229, v160
	v_mfma_f32_32x32x16_bf16 v[2:17], v[70:73], v[86:89], v[2:17]
	v_mfma_f32_32x32x16_bf16 v[2:17], v[74:77], v[90:93], v[2:17]
	v_mfma_f32_32x32x16_bf16 v[2:17], v[78:81], v[94:97], v[2:17]
	s_and_saveexec_b64 s[66:67], vcc
	s_cbranch_execz .LBB0_136
; template <int MODE>
; __device__ __forceinline__ void partialSM(f32x16& p0, f32x16& p1, float& m_reg, float& mn, float& alpha, int relh, int relw_min, int relw_max, const float* lut) {
;     ...
;     if (nearT) {
; #pragma unroll
;       for (int r = 0; r < 16; ++r) { const int i0 = relh + (r & 3) + 8 * (r >> 2);
;         const int a0 = min(max(i0, -129), 129) + 129, a1 = min(max(i0 + 32, -129), 129) + 129;
;         p0[r] = fmaf(p0[r], C, lut[a0]); p1[r] = fmaf(p1[r], C, lut[a1]); }
;     } else {
; #pragma unroll
;       for (int r = 0; r < 16; ++r) { p0[r] = fmaf(p0[r], C, cfar); p1[r] = fmaf(p1[r], C, cfar); }
;     }
;     float pmax = p0[0];
; #pragma unroll
;     for (int r = 1; r < 16; ++r) pmax = fmaxf(pmax, p0[r]);
; #pragma unroll
;     for (int r = 0; r < 16; ++r) pmax = fmaxf(pmax, p1[r]);
	s_cmp_gt_i32 s91, s23
	s_cselect_b64 vcc, -1, 0
	s_mov_b64 s[70:71], -1
	s_and_saveexec_b64 s[68:69], vcc
	s_cbranch_execz .LBB0_135
	v_add_u32_e32 v227, s77, v222
	v_add_u32_e32 v66, 64, v227
	v_add_u32_e32 v68, 0x41, v227
	v_add_u32_e32 v70, 0x42, v227
	v_add_u32_e32 v72, 0x43, v227
	v_med3_i32 v67, v66, s39, v198
	v_med3_i32 v66, v66, s33, v199
	v_med3_i32 v69, v68, s39, v198
	v_med3_i32 v68, v68, s33, v199
	v_med3_i32 v71, v70, s39, v198
	v_med3_i32 v70, v70, s33, v199
	v_med3_i32 v73, v72, s39, v198
	v_med3_i32 v72, v72, s33, v199
	v_lshl_add_u32 v67, v67, 2, s76
	v_lshl_add_u32 v66, v66, 2, s76
	v_lshl_add_u32 v69, v69, 2, s76
	v_lshl_add_u32 v68, v68, 2, s76
	v_lshl_add_u32 v70, v70, 2, s76
	v_lshl_add_u32 v72, v72, 2, s76
	v_lshl_add_u32 v71, v71, 2, s76
	v_lshl_add_u32 v73, v73, 2, s76
	ds_read_b32 v194, v67 offset:516
	ds_read_b32 v66, v66 offset:644
	ds_read_b32 v195, v69 offset:516
	ds_read_b32 v67, v68 offset:644
	ds_read_b32 v229, v71 offset:516
	ds_read_b32 v68, v70 offset:644
	ds_read_b32 v230, v73 offset:516
	ds_read_b32 v69, v72 offset:644
	v_add_u32_e32 v70, 0x48, v227
	v_add_u32_e32 v72, 0x49, v227
	v_add_u32_e32 v74, 0x4a, v227
	v_add_u32_e32 v76, 0x4b, v227
	v_med3_i32 v71, v70, s39, v198
	v_med3_i32 v70, v70, s33, v199
	v_med3_i32 v73, v72, s39, v198
	v_med3_i32 v72, v72, s33, v199
	v_med3_i32 v75, v74, s39, v198
	v_med3_i32 v74, v74, s33, v199
	v_med3_i32 v77, v76, s39, v198
	v_med3_i32 v76, v76, s33, v199
	v_lshl_add_u32 v71, v71, 2, s76
	v_lshl_add_u32 v70, v70, 2, s76
	v_lshl_add_u32 v73, v73, 2, s76
	v_lshl_add_u32 v72, v72, 2, s76
	v_lshl_add_u32 v74, v74, 2, s76
	v_lshl_add_u32 v76, v76, 2, s76
	v_lshl_add_u32 v75, v75, 2, s76
	v_lshl_add_u32 v77, v77, 2, s76
	ds_read_b32 v231, v71 offset:516
	ds_read_b32 v70, v70 offset:644
	ds_read_b32 v232, v73 offset:516
	ds_read_b32 v71, v72 offset:644
	ds_read_b32 v233, v75 offset:516
	ds_read_b32 v72, v74 offset:644
	ds_read_b32 v234, v77 offset:516
	ds_read_b32 v73, v76 offset:644
	v_add_u32_e32 v74, 0x50, v227
	v_add_u32_e32 v76, 0x51, v227
	v_add_u32_e32 v78, 0x52, v227
	v_add_u32_e32 v80, 0x53, v227
	v_med3_i32 v75, v74, s39, v198
	v_med3_i32 v74, v74, s33, v199
	v_med3_i32 v77, v76, s39, v198
	v_med3_i32 v76, v76, s33, v199
	v_med3_i32 v79, v78, s39, v198
	v_med3_i32 v78, v78, s33, v199
	v_med3_i32 v81, v80, s39, v198
	v_med3_i32 v80, v80, s33, v199
	v_lshl_add_u32 v75, v75, 2, s76
	v_lshl_add_u32 v74, v74, 2, s76
	v_lshl_add_u32 v77, v77, 2, s76
	v_lshl_add_u32 v76, v76, 2, s76
	v_lshl_add_u32 v78, v78, 2, s76
	v_lshl_add_u32 v80, v80, 2, s76
	v_lshl_add_u32 v79, v79, 2, s76
	v_lshl_add_u32 v81, v81, 2, s76
	ds_read_b32 v235, v75 offset:516
	ds_read_b32 v74, v74 offset:644
	ds_read_b32 v236, v77 offset:516
	ds_read_b32 v75, v76 offset:644
	ds_read_b32 v237, v79 offset:516
	ds_read_b32 v76, v78 offset:644
	ds_read_b32 v238, v81 offset:516
	ds_read_b32 v77, v80 offset:644
	v_add_u32_e32 v78, 0x58, v227
	v_add_u32_e32 v80, 0x59, v227
	v_add_u32_e32 v82, 0x5a, v227
	v_med3_i32 v79, v78, s39, v198
	v_med3_i32 v78, v78, s33, v199
	v_med3_i32 v81, v80, s39, v198
	v_med3_i32 v80, v80, s33, v199
	v_med3_i32 v83, v82, s39, v198
	v_med3_i32 v82, v82, s33, v199
	v_add_u32_e32 v84, 0x5b, v227
	s_waitcnt lgkmcnt(14)
	v_fmac_f32_e32 v194, 0x3e38aa3b, v114
	v_fmac_f32_e32 v195, 0x3e38aa3b, v115
	v_lshl_add_u32 v79, v79, 2, s76
	v_lshl_add_u32 v78, v78, 2, s76
	v_lshl_add_u32 v81, v81, 2, s76
	v_lshl_add_u32 v80, v80, 2, s76
	v_lshl_add_u32 v82, v82, 2, s76
	v_med3_i32 v85, v84, s39, v198
	v_med3_i32 v84, v84, s33, v199
	v_fmac_f32_e32 v229, 0x3e38aa3b, v116
	v_fmac_f32_e32 v230, 0x3e38aa3b, v117
	v_lshl_add_u32 v83, v83, 2, s76
	v_lshl_add_u32 v85, v85, 2, s76
	v_lshl_add_u32 v84, v84, 2, s76
	ds_read_b32 v239, v79 offset:516
	ds_read_b32 v78, v78 offset:644
	ds_read_b32 v240, v81 offset:516
	ds_read_b32 v79, v80 offset:644
	ds_read_b32 v241, v83 offset:516
	ds_read_b32 v80, v82 offset:644
	ds_read_b32 v242, v85 offset:516
	ds_read_b32 v81, v84 offset:644
	v_max_f32_e32 v82, v194, v195
	v_fmac_f32_e32 v231, 0x3e38aa3b, v118
	s_waitcnt lgkmcnt(14)
	v_fmac_f32_e32 v232, 0x3e38aa3b, v119
	v_max3_f32 v82, v82, v229, v230
	v_fmac_f32_e32 v233, 0x3e38aa3b, v120
	v_fmac_f32_e32 v234, 0x3e38aa3b, v121
	v_max3_f32 v82, v82, v231, v232
	v_fmac_f32_e32 v235, 0x3e38aa3b, v122
	s_waitcnt lgkmcnt(13)
	v_fmac_f32_e32 v236, 0x3e38aa3b, v123
	v_max3_f32 v82, v82, v233, v234
	s_waitcnt lgkmcnt(11)
	v_fmac_f32_e32 v237, 0x3e38aa3b, v124
	s_waitcnt lgkmcnt(9)
	v_fmac_f32_e32 v238, 0x3e38aa3b, v125
	v_max3_f32 v82, v82, v235, v236
	s_waitcnt lgkmcnt(7)
	v_fmac_f32_e32 v239, 0x3e38aa3b, v126
	s_waitcnt lgkmcnt(5)
	v_fmac_f32_e32 v240, 0x3e38aa3b, v127
	v_max3_f32 v82, v82, v237, v238
	s_waitcnt lgkmcnt(3)
	v_fmac_f32_e32 v241, 0x3e38aa3b, v128
	s_waitcnt lgkmcnt(1)
; template <int MODE>
; __device__ __forceinline__ void partialSM(f32x16& p0, f32x16& p1, float& m_reg, float& mn, float& alpha, int relh, int relw_min, int relw_max, const float* lut) {
;     ...
;       if (!nearT) {
;         float pmax = p0[0];
; #pragma unroll
;         for (int r = 1; r < 16; ++r) pmax = fmaxf(pmax, p0[r]);
; #pragma unroll
;         for (int r = 0; r < 16; ++r) pmax = fmaxf(pmax, p1[r]);
;         { auto rr = __builtin_amdgcn_permlane32_swap(__float_as_uint(pmax), __float_as_uint(pmax), false, false);
;           pmax = fmaxf(__uint_as_float(rr[0]), __uint_as_float(rr[1])); }
;         const float tmax = fmaf(pmax, C, cfar);
;         if (__builtin_expect(__all(tmax - m_reg <= THR2), 1)) { mn = m_reg; alpha = 1.f; }
;         else { mn = fmaxf(m_reg, tmax); alpha = __builtin_amdgcn_exp2f(m_reg - mn); m_reg = mn; }
;         const float off = cfar - mn;
; #pragma unroll
;         for (int r = 0; r < 16; ++r) p0[r] = fmaf(p0[r], C, off);
; #pragma unroll
;         for (int r = 0; r < 16; ++r) p1[r] = fmaf(p1[r], C, off);
; #pragma unroll
;         for (int r = 0; r < 16; ++r) p0[r] = __builtin_amdgcn_exp2f(p0[r]);
;     ...
;     { auto rr = __builtin_amdgcn_permlane32_swap(__float_as_uint(pmax), __float_as_uint(pmax), false, false);
;       pmax = fmaxf(__uint_as_float(rr[0]), __uint_as_float(rr[1])); }
;     if (__builtin_expect(__all(pmax - m_reg <= THR2), 1)) { mn = m_reg; alpha = 1.f; }
;     else { mn = fmaxf(m_reg, pmax); alpha = __builtin_amdgcn_exp2f(m_reg - mn); m_reg = mn; }
; #pragma unroll
;     for (int r = 0; r < 16; ++r) p0[r] = __builtin_amdgcn_exp2f(p0[r] - mn);
; #pragma unroll
;     for (int r = 0; r < 16; ++r) p1[r] = p1[r] - mn;
	v_fmac_f32_e32 v242, 0x3e38aa3b, v129
	v_max3_f32 v82, v82, v239, v240
	v_max3_f32 v84, v82, v241, v242
	v_pk_fma_f32 v[82:83], v[98:99], s[48:49], v[66:67] op_sel_hi:[1,0,1]
	v_pk_fma_f32 v[86:87], v[102:103], s[48:49], v[70:71] op_sel_hi:[1,0,1]
	v_max3_f32 v66, v84, v82, v83
	v_pk_fma_f32 v[84:85], v[100:101], s[48:49], v[68:69] op_sel_hi:[1,0,1]
	v_pk_fma_f32 v[88:89], v[104:105], s[48:49], v[72:73] op_sel_hi:[1,0,1]
	v_max3_f32 v66, v66, v84, v85
	v_max3_f32 v66, v66, v86, v87
	v_max3_f32 v66, v66, v88, v89
	v_pk_fma_f32 v[90:91], v[106:107], s[48:49], v[74:75] op_sel_hi:[1,0,1]
	v_pk_fma_f32 v[92:93], v[108:109], s[48:49], v[76:77] op_sel_hi:[1,0,1]
	v_max3_f32 v66, v66, v90, v91
	v_max3_f32 v66, v66, v92, v93
	v_pk_fma_f32 v[94:95], v[110:111], s[48:49], v[78:79] op_sel_hi:[1,0,1]
	s_waitcnt lgkmcnt(0)
	v_pk_fma_f32 v[96:97], v[112:113], s[48:49], v[80:81] op_sel_hi:[1,0,1]
	v_max3_f32 v66, v66, v94, v95
	v_max3_f32 v66, v66, v96, v97
	v_mov_b32_e32 v67, v66
	s_nop 1
	v_permlane32_swap_b32_e32 v66, v67
	v_max_f32_e32 v66, v66, v67
	v_sub_f32_e32 v67, v66, v219
	v_cmp_ge_f32_e32 vcc, s94, v67
	v_max_f32_e32 v66, v219, v66
	v_sub_f32_e32 v67, v219, v66
	v_exp_f32_e32 v67, v67
	s_cmp_eq_u64 vcc, exec
	s_cselect_b64 vcc, -1, 0
	v_cndmask_b32_e32 v228, v66, v219, vcc
	v_cndmask_b32_e64 v226, v67, 1.0, vcc
	v_sub_f32_e32 v66, v194, v228
	v_sub_f32_e32 v67, v195, v228
	v_sub_f32_e32 v68, v229, v228
	v_sub_f32_e32 v69, v230, v228
	v_sub_f32_e32 v70, v231, v228
	v_sub_f32_e32 v71, v232, v228
	v_sub_f32_e32 v72, v233, v228
	v_sub_f32_e32 v73, v234, v228
	v_sub_f32_e32 v74, v235, v228
	v_sub_f32_e32 v75, v236, v228
	v_sub_f32_e32 v76, v237, v228
	v_sub_f32_e32 v77, v238, v228
	v_sub_f32_e32 v78, v239, v228
	v_sub_f32_e32 v79, v240, v228
	v_sub_f32_e32 v80, v241, v228
	v_sub_f32_e32 v81, v242, v228
	v_exp_f32_e32 v66, v66
	v_exp_f32_e32 v67, v67
	v_exp_f32_e32 v68, v68
	v_exp_f32_e32 v69, v69
	v_exp_f32_e32 v70, v70
	v_exp_f32_e32 v71, v71
	v_exp_f32_e32 v72, v72
	v_exp_f32_e32 v73, v73
	v_exp_f32_e32 v74, v74
	v_exp_f32_e32 v75, v75
	v_exp_f32_e32 v76, v76
	v_exp_f32_e32 v77, v77
	v_exp_f32_e32 v78, v78
	v_exp_f32_e32 v79, v79
	v_exp_f32_e32 v80, v80
	v_exp_f32_e32 v81, v81
	v_sub_f32_e32 v97, v97, v228
	v_sub_f32_e32 v96, v96, v228
	v_sub_f32_e32 v95, v95, v228
	v_sub_f32_e32 v94, v94, v228
	v_sub_f32_e32 v93, v93, v228
	v_sub_f32_e32 v92, v92, v228
	v_sub_f32_e32 v91, v91, v228
	v_sub_f32_e32 v90, v90, v228
	v_sub_f32_e32 v89, v89, v228
	v_sub_f32_e32 v88, v88, v228
	v_sub_f32_e32 v87, v87, v228
	v_sub_f32_e32 v86, v86, v228
	v_sub_f32_e32 v85, v85, v228
	v_sub_f32_e32 v84, v84, v228
	v_sub_f32_e32 v83, v83, v228
	v_sub_f32_e32 v82, v82, v228
	s_xor_b64 s[70:71], exec, -1
.LBB0_135:
	s_or_b64 exec, exec, s[68:69]
	s_andn2_b64 s[64:65], s[64:65], exec
	s_and_b64 s[68:69], s[70:71], exec
	v_mov_b32_e32 v229, v161
	s_or_b64 s[64:65], s[64:65], s[68:69]
.LBB0_136:
	s_or_b64 exec, exec, s[66:67]
	s_and_saveexec_b64 s[66:67], s[64:65]
	s_cbranch_execz .LBB0_138
	v_mov_b32_e32 v66, v229
	v_mov_b32_e32 v228, v219
	v_sub_f32_e32 v66, v66, v228
	v_fmamk_f32 v67, v114, 0x3e38aa3b, v66
	v_mov_b32_e32 v114, v66
	v_mov_b32_e32 v226, 1.0
	v_fmamk_f32 v68, v115, 0x3e38aa3b, v66
	v_fmamk_f32 v69, v116, 0x3e38aa3b, v66
	v_fmamk_f32 v70, v117, 0x3e38aa3b, v66
	v_fmamk_f32 v71, v118, 0x3e38aa3b, v66
	v_fmamk_f32 v72, v119, 0x3e38aa3b, v66
	v_fmamk_f32 v73, v120, 0x3e38aa3b, v66
	v_fmamk_f32 v74, v121, 0x3e38aa3b, v66
	v_fmamk_f32 v75, v122, 0x3e38aa3b, v66
	v_fmamk_f32 v76, v123, 0x3e38aa3b, v66
	v_fmamk_f32 v77, v124, 0x3e38aa3b, v66
	v_fmamk_f32 v78, v125, 0x3e38aa3b, v66
	v_fmamk_f32 v79, v126, 0x3e38aa3b, v66
	v_fmamk_f32 v80, v127, 0x3e38aa3b, v66
	v_fmamk_f32 v81, v128, 0x3e38aa3b, v66
	v_fmac_f32_e32 v114, 0x3e38aa3b, v129
	v_fmamk_f32 v97, v113, 0x3e38aa3b, v66
	v_fmamk_f32 v96, v112, 0x3e38aa3b, v66
	v_fmamk_f32 v95, v111, 0x3e38aa3b, v66
	v_fmamk_f32 v94, v110, 0x3e38aa3b, v66
	v_fmamk_f32 v93, v109, 0x3e38aa3b, v66
	v_fmamk_f32 v92, v108, 0x3e38aa3b, v66
	v_fmamk_f32 v91, v107, 0x3e38aa3b, v66
	v_fmamk_f32 v90, v106, 0x3e38aa3b, v66
	v_fmamk_f32 v89, v105, 0x3e38aa3b, v66
	v_fmamk_f32 v88, v104, 0x3e38aa3b, v66
	v_fmamk_f32 v87, v103, 0x3e38aa3b, v66
	v_fmamk_f32 v86, v102, 0x3e38aa3b, v66
	v_fmamk_f32 v85, v101, 0x3e38aa3b, v66
	v_fmamk_f32 v84, v100, 0x3e38aa3b, v66
	v_fmamk_f32 v83, v99, 0x3e38aa3b, v66
	v_fmamk_f32 v82, v98, 0x3e38aa3b, v66
	v_exp_f32_e32 v66, v67
	v_exp_f32_e32 v67, v68
	v_exp_f32_e32 v68, v69
	v_exp_f32_e32 v69, v70
	v_exp_f32_e32 v70, v71
	v_exp_f32_e32 v71, v72
	v_exp_f32_e32 v72, v73
	v_exp_f32_e32 v73, v74
	v_exp_f32_e32 v74, v75
	v_exp_f32_e32 v75, v76
	v_exp_f32_e32 v76, v77
	v_exp_f32_e32 v77, v78
	v_exp_f32_e32 v78, v79
	v_exp_f32_e32 v79, v80
	v_exp_f32_e32 v80, v81
	v_exp_f32_e32 v81, v114

; __device__ __forceinline__ void finishSM(f32x16& p0, f32x16& p1, float alpha, float& l_reg, bf16x8& pa0, bf16x8& pa1, bf16x8& pa2, bf16x8& pa3) {
; #pragma unroll
;   for (int r = 0; r < 16; ++r) p1[r] = __builtin_amdgcn_exp2f(p1[r]);
;   float ps = 0;
; #pragma unroll
;   for (int r = 0; r < 16; ++r) ps += p0[r];
; #pragma unroll
;   for (int r = 0; r < 16; ++r) ps += p1[r];
;   { auto rr = __builtin_amdgcn_permlane32_swap(__float_as_uint(ps), __float_as_uint(ps), false, false);
;     ps = __uint_as_float(rr[0]) + __uint_as_float(rr[1]); }
;   l_reg = l_reg * alpha + ps;
;     ...
;   PK4(p0, 0, pa0); PK4(p0, 8, pa1); PK4(p1, 0, pa2); PK4(p1, 8, pa3);
;     ...
; }
; template <int ND0, int DOFF>
; __device__ __forceinline__ void qkt(f32x16& p0, f32x16& p1, const char* Ks, const bf16x8* qr, int r32, int hi) {
;   p0 = f32x16{}; p1 = f32x16{};
; #pragma unroll
;   for (int d0 = 0; d0 < ND0; ++d0) { const int cb = ((d0 + DOFF) * 16 + hi * 8) * 2;
;     bf16x8 b0 = *reinterpret_cast<const bf16x8*>(Ks + KSWZ(r32, cb));
;     bf16x8 b1 = *reinterpret_cast<const bf16x8*>(Ks + KSWZ(32 + r32, cb));
;     p0 = __builtin_amdgcn_mfma_f32_32x32x16_bf16(b0, qr[d0], p0, 0, 0, 0);
;     p1 = __builtin_amdgcn_mfma_f32_32x32x16_bf16(b1, qr[d0], p1, 0, 0, 0); }
; }
; __device__ __forceinline__ int v_st(int k, int c) { const int kk = (k & ~0xC) | ((k & 4) << 1) | ((k & 8) >> 1); return ((kk >> 3) * 4 + (c >> 5)) * 512 + ((kk & 7) * 32 + (c & 31)) * 2; }
; __device__ __forceinline__ int v_rd_base(int lane) { return ((lane & 3) << 3) | (((lane >> 2) & 3) << 6) | (((lane >> 4) & 1) << 5) | (((lane >> 5) & 1) << 8); }
; template <int OFF> __device__ __forceinline__ s16x4 tr_read(int vb) {
;   s16x4 r; asm volatile("ds_read_b64_tr_b16 %0, %1 offset:%2" : "=&v"(r) : "v"(vb), "i"(OFF) : "memory"); return r;
; template <int MODE>
; __device__ __forceinline__ void attn_body(const bf16_t* __restrict__ Qb, const bf16_t* __restrict__ Kh, const bf16_t* __restrict__ Vh, int NT, int krel0,
;                                           char* lds, const float* __restrict__ lutg, const AttnEpi& E) {
;     ...
;     __syncthreads();
;     SBAR(); qkt<ND0, DOFF>(pA0, pA1, K_lds + oq, qr, r32, hi);
;     finishSM(pB0, pB1, alB, l_reg, pa0, pa1, pa2, pa3); SBAR();
;     if (j + 3 < NT) SLOAD(SE, (j + 3) * 64); SBAR();
;     pv_d0(o, vb0 + op, pa0, pa1, pa2, pa3); PSM(pA0, pA1, mnA, alA, j + 1);
;     SWAIT(); SWRITE(ow, SO);
.LBB0_142:
	s_cmp_lt_u32 s31, 4
	s_cbranch_scc0 .Ldp_4
	s_waitcnt vmcnt(0) lgkmcnt(0)
	s_barrier
.Ldp_4:
	v_add_u32_e32 v102, s66, v213
	ds_read_b128 v[98:101], v102 offset:49152
	ds_read_b128 v[102:105], v102 offset:57344
	v_add_u32_e32 v194, s66, v214
	ds_read_b128 v[230:233], v194 offset:49152
	ds_read_b128 v[234:237], v194 offset:57344
	v_add_u32_e32 v194, s66, v215
	s_waitcnt lgkmcnt(3)
	v_mfma_f32_32x32x16_bf16 v[114:129], v[98:101], v[142:145], 0
	v_exp_f32_e32 v82, v82
	v_exp_f32_e32 v83, v83
	v_exp_f32_e32 v84, v84
	v_exp_f32_e32 v85, v85
	v_exp_f32_e32 v86, v86
	v_exp_f32_e32 v87, v87
	v_exp_f32_e32 v88, v88
	s_waitcnt lgkmcnt(2)
	v_mfma_f32_32x32x16_bf16 v[98:113], v[102:105], v[142:145], 0
	v_exp_f32_e32 v89, v89
	v_exp_f32_e32 v90, v90
	v_exp_f32_e32 v91, v91
	v_exp_f32_e32 v92, v92
	v_exp_f32_e32 v93, v93
	v_exp_f32_e32 v94, v94
	v_exp_f32_e32 v95, v95
	s_waitcnt lgkmcnt(1)
	v_mfma_f32_32x32x16_bf16 v[114:129], v[230:233], v[138:141], v[114:129]
	v_exp_f32_e32 v96, v96
	v_exp_f32_e32 v97, v97
	s_waitcnt lgkmcnt(0)
	v_mfma_f32_32x32x16_bf16 v[98:113], v[234:237], v[138:141], v[98:113]
	ds_read_b128 v[230:233], v194 offset:49152
	ds_read_b128 v[234:237], v194 offset:57344
	v_add_u32_e32 v194, s66, v216
	s_waitcnt lgkmcnt(1)
	v_mfma_f32_32x32x16_bf16 v[114:129], v[230:233], v[134:137], v[114:129]
	s_waitcnt lgkmcnt(0)
	v_mfma_f32_32x32x16_bf16 v[98:113], v[234:237], v[134:137], v[98:113]
	ds_read_b128 v[230:233], v194 offset:49152
	ds_read_b128 v[234:237], v194 offset:57344
	v_add_f32_e32 v194, v67, v66
	v_add_f32_e32 v194, v68, v194
	v_add_f32_e32 v194, v69, v194
	v_add_f32_e32 v194, v70, v194
	v_add_f32_e32 v194, v71, v194
	v_add_f32_e32 v194, v72, v194
	v_add_f32_e32 v194, v73, v194
	v_add_f32_e32 v194, v74, v194
	v_add_f32_e32 v194, v75, v194
	v_add_f32_e32 v194, v76, v194
	v_add_f32_e32 v194, v77, v194
	v_add_f32_e32 v194, v78, v194
	v_add_f32_e32 v194, v79, v194
	v_add_f32_e32 v194, v80, v194
	v_add_f32_e32 v194, v81, v194
	v_add_f32_e32 v194, v82, v194
	v_add_f32_e32 v194, v83, v194
	v_add_f32_e32 v194, v84, v194
	v_add_f32_e32 v194, v85, v194
	v_add_f32_e32 v194, v86, v194
	v_add_f32_e32 v194, v87, v194
	v_add_f32_e32 v194, v88, v194
	v_add_f32_e32 v194, v89, v194
	v_add_f32_e32 v194, v90, v194
	v_add_f32_e32 v194, v91, v194
	s_waitcnt lgkmcnt(1)
	v_mfma_f32_32x32x16_bf16 v[114:129], v[230:233], v[130:133], v[114:129]
	v_add_f32_e32 v194, v92, v194
	v_add_f32_e32 v194, v93, v194
	v_add_f32_e32 v194, v94, v194
	v_add_f32_e32 v194, v95, v194
	v_add_f32_e32 v194, v96, v194
	v_add_f32_e32 v229, v97, v194
	v_mov_b32_e32 v230, v229
	s_waitcnt lgkmcnt(0)
	v_mfma_f32_32x32x16_bf16 v[98:113], v[234:237], v[130:133], v[98:113]
	v_cvt_pk_bf16_f32 v66, v66, v67
	v_cvt_pk_bf16_f32 v67, v68, v69
	v_cvt_pk_bf16_f32 v68, v70, v71
	v_cvt_pk_bf16_f32 v69, v72, v73
	v_cvt_pk_bf16_f32 v70, v74, v75
	v_cvt_pk_bf16_f32 v71, v76, v77
	v_cvt_pk_bf16_f32 v72, v78, v79
	v_cvt_pk_bf16_f32 v73, v80, v81
	v_cvt_pk_bf16_f32 v74, v82, v83
	v_cvt_pk_bf16_f32 v75, v84, v85
	v_cvt_pk_bf16_f32 v76, v86, v87
	v_cvt_pk_bf16_f32 v77, v88, v89
	v_cvt_pk_bf16_f32 v78, v90, v91
	v_cvt_pk_bf16_f32 v79, v92, v93
	v_cvt_pk_bf16_f32 v80, v94, v95
	v_cvt_pk_bf16_f32 v81, v96, v97
	v_permlane32_swap_b32_e32 v229, v230
	v_permlane32_swap_b32_e32 v66, v68
	v_permlane32_swap_b32_e32 v67, v69
	v_permlane32_swap_b32_e32 v70, v72
	v_permlane32_swap_b32_e32 v71, v73
	v_permlane32_swap_b32_e32 v74, v76
	v_permlane32_swap_b32_e32 v75, v77
	v_permlane32_swap_b32_e32 v78, v80
	v_permlane32_swap_b32_e32 v79, v81
	s_add_i32 s81, s81, 2
	s_cmp_ge_u32 s81, s11
	s_cselect_b64 s[64:65], -1, 0
	s_cmp_lt_u32 s31, 4
	s_cbranch_scc1 .Ldp_3
	s_waitcnt vmcnt(0) lgkmcnt(0)
	s_barrier
.Ldp_3:
	s_add_i32 m0, s80, s30
	s_nop 0
	global_load_lds_dwordx4 v248, s[26:27]
	s_add_i32 m0, m0, 0x400
	s_nop 0
	global_load_lds_dwordx4 v249, s[26:27]
	s_add_i32 m0, s82, s30
	s_add_i32 m0, m0, 0xc000
	s_nop 0
	global_load_lds_dwordx4 v250, s[28:29]
	s_add_i32 m0, m0, 0x400
	s_nop 0
	global_load_lds_dwordx4 v251, s[28:29]
	s_add_u32 s26, s26, 0x90000
	s_addc_u32 s27, s27, 0
	s_add_u32 s28, s28, 0x90000
	s_addc_u32 s29, s29, 0
.LBB0_144:
	v_add_u32_e32 v194, s82, v218
	ds_read_b64_tr_b16 v[82:83], v194 offset:0
	ds_read_b64_tr_b16 v[84:85], v194 offset:0x800
	ds_read_b64_tr_b16 v[86:87], v194 offset:0x1000
	ds_read_b64_tr_b16 v[88:89], v194 offset:0x1800
	ds_read_b64_tr_b16 v[90:91], v194 offset:0x2000
	ds_read_b64_tr_b16 v[92:93], v194 offset:0x2800
	ds_read_b64_tr_b16 v[94:95], v194 offset:0x3000
	ds_read_b64_tr_b16 v[96:97], v194 offset:0x3800
	s_waitcnt lgkmcnt(0)
	s_nop 0
	v_mfma_f32_32x32x16_bf16 v[50:65], v[66:69], v[82:85], v[50:65]
	ds_read_b64_tr_b16 v[82:83], v194 offset:0x200
	ds_read_b64_tr_b16 v[84:85], v194 offset:0xa00
	v_mfma_f32_32x32x16_bf16 v[50:65], v[70:73], v[86:89], v[50:65]
	ds_read_b64_tr_b16 v[86:87], v194 offset:0x1200
	ds_read_b64_tr_b16 v[88:89], v194 offset:0x1a00
	v_mfma_f32_32x32x16_bf16 v[50:65], v[74:77], v[90:93], v[50:65]
	ds_read_b64_tr_b16 v[90:91], v194 offset:0x2200
	ds_read_b64_tr_b16 v[92:93], v194 offset:0x2a00
	v_mfma_f32_32x32x16_bf16 v[50:65], v[78:81], v[94:97], v[50:65]
	ds_read_b64_tr_b16 v[94:95], v194 offset:0x3200
	ds_read_b64_tr_b16 v[96:97], v194 offset:0x3a00
	s_waitcnt lgkmcnt(0)
	v_mfma_f32_32x32x16_bf16 v[34:49], v[66:69], v[82:85], v[34:49]
	ds_read_b64_tr_b16 v[82:83], v194 offset:0x400
	ds_read_b64_tr_b16 v[84:85], v194 offset:0xc00
	v_mfma_f32_32x32x16_bf16 v[34:49], v[70:73], v[86:89], v[34:49]
	ds_read_b64_tr_b16 v[86:87], v194 offset:0x1400
	ds_read_b64_tr_b16 v[88:89], v194 offset:0x1c00
	v_mfma_f32_32x32x16_bf16 v[34:49], v[74:77], v[90:93], v[34:49]
	ds_read_b64_tr_b16 v[90:91], v194 offset:0x2400
	ds_read_b64_tr_b16 v[92:93], v194 offset:0x2c00
	v_mfma_f32_32x32x16_bf16 v[34:49], v[78:81], v[94:97], v[34:49]
	ds_read_b64_tr_b16 v[94:95], v194 offset:0x3400
	ds_read_b64_tr_b16 v[96:97], v194 offset:0x3c00
	s_waitcnt lgkmcnt(0)
; template <int MODE>
; __device__ __forceinline__ void partialSM(f32x16& p0, f32x16& p1, float& m_reg, float& mn, float& alpha, int relh, int relw_min, int relw_max, const float* lut) {
;     ...
;     if (nearT) {
; #pragma unroll
;       for (int r = 0; r < 16; ++r) { const int i0 = relh + (r & 3) + 8 * (r >> 2);
;         const int a0 = min(max(i0, -129), 129) + 129, a1 = min(max(i0 + 32, -129), 129) + 129;
;         p0[r] = fmaf(p0[r], C, lut[a0]); p1[r] = fmaf(p1[r], C, lut[a1]); }
;     } else {
; #pragma unroll
;       for (int r = 0; r < 16; ++r) { p0[r] = fmaf(p0[r], C, cfar); p1[r] = fmaf(p1[r], C, cfar); }
;     }
;     float pmax = p0[0];
; #pragma unroll
;     for (int r = 1; r < 16; ++r) pmax = fmaxf(pmax, p0[r]);
; #pragma unroll
;     for (int r = 0; r < 16; ++r) pmax = fmaxf(pmax, p1[r]);
; template <int D0> __device__ __forceinline__ void pv_one(f32x16& od, int vb, bf16x8 pa0, bf16x8 pa1, bf16x8 pa2, bf16x8 pa3) {
;     ...
;   od = __builtin_amdgcn_mfma_f32_32x32x16_bf16(pa3, PK(l3, h3), od, 0, 0, 0);
;     ...
; }
; __device__ __forceinline__ void pv_d0(f32x16* o, int vb, bf16x8 pa0, bf16x8 pa1, bf16x8 pa2, bf16x8 pa3) {
;   pv_one<0>(o[0], vb, pa0, pa1, pa2, pa3); pv_one<1>(o[1], vb, pa0, pa1, pa2, pa3); pv_one<2>(o[2], vb, pa0, pa1, pa2, pa3); pv_one<3>(o[3], vb, pa0, pa1, pa2, pa3);
	v_mfma_f32_32x32x16_bf16 v[18:33], v[66:69], v[82:85], v[18:33]
	ds_read_b64_tr_b16 v[82:83], v194 offset:0x600
	ds_read_b64_tr_b16 v[84:85], v194 offset:0xe00
	v_mfma_f32_32x32x16_bf16 v[18:33], v[70:73], v[86:89], v[18:33]
	ds_read_b64_tr_b16 v[86:87], v194 offset:0x1600
	ds_read_b64_tr_b16 v[88:89], v194 offset:0x1e00
	v_mfma_f32_32x32x16_bf16 v[18:33], v[74:77], v[90:93], v[18:33]
	ds_read_b64_tr_b16 v[90:91], v194 offset:0x2600
	ds_read_b64_tr_b16 v[92:93], v194 offset:0x2e00
	v_mfma_f32_32x32x16_bf16 v[18:33], v[78:81], v[94:97], v[18:33]
	ds_read_b64_tr_b16 v[94:95], v194 offset:0x3600
	ds_read_b64_tr_b16 v[96:97], v194 offset:0x3e00
	s_waitcnt lgkmcnt(0)
	v_mfma_f32_32x32x16_bf16 v[2:17], v[66:69], v[82:85], v[2:17]
	s_cmp_gt_i32 s95, s24
	s_cselect_b64 s[66:67], -1, 0
	s_cmp_lt_i32 s15, s24
	s_cselect_b64 vcc, -1, 0
	v_mov_b32_e32 v231, v160
	v_mfma_f32_32x32x16_bf16 v[2:17], v[70:73], v[86:89], v[2:17]
	v_mfma_f32_32x32x16_bf16 v[2:17], v[74:77], v[90:93], v[2:17]
	v_mfma_f32_32x32x16_bf16 v[2:17], v[78:81], v[94:97], v[2:17]
	s_and_saveexec_b64 s[68:69], vcc
	s_cbranch_execz .LBB0_148
	s_cmp_gt_i32 s91, s25
	s_cselect_b64 vcc, -1, 0
	s_mov_b64 s[72:73], -1
	s_and_saveexec_b64 s[70:71], vcc
	s_cbranch_execz .LBB0_147
	v_add_u32_e32 v227, s77, v222
	v_add_u32_e32 v66, 0x80, v227
	v_add_u32_e32 v68, 0x81, v227
	v_add_u32_e32 v70, 0x82, v227
	v_add_u32_e32 v72, 0x83, v227
	v_med3_i32 v67, v66, s39, v198
	v_med3_i32 v66, v66, s33, v199
	v_med3_i32 v69, v68, s39, v198
	v_med3_i32 v68, v68, s33, v199
	v_med3_i32 v71, v70, s39, v198
	v_med3_i32 v70, v70, s33, v199
	v_med3_i32 v73, v72, s39, v198
	v_med3_i32 v72, v72, s33, v199
	v_lshl_add_u32 v67, v67, 2, s76
	v_lshl_add_u32 v66, v66, 2, s76
	v_lshl_add_u32 v69, v69, 2, s76
	v_lshl_add_u32 v68, v68, 2, s76
	v_lshl_add_u32 v70, v70, 2, s76
	v_lshl_add_u32 v72, v72, 2, s76
	v_lshl_add_u32 v71, v71, 2, s76
	v_lshl_add_u32 v73, v73, 2, s76
	ds_read_b32 v194, v67 offset:516
	ds_read_b32 v66, v66 offset:644
	ds_read_b32 v195, v69 offset:516
	ds_read_b32 v67, v68 offset:644
	ds_read_b32 v231, v71 offset:516
	ds_read_b32 v68, v70 offset:644
	ds_read_b32 v232, v73 offset:516
	ds_read_b32 v69, v72 offset:644
	v_add_u32_e32 v70, 0x88, v227
	v_add_u32_e32 v72, 0x89, v227
	v_add_u32_e32 v74, 0x8a, v227
	v_add_u32_e32 v76, 0x8b, v227
	v_med3_i32 v71, v70, s39, v198
	v_med3_i32 v70, v70, s33, v199
	v_med3_i32 v73, v72, s39, v198
	v_med3_i32 v72, v72, s33, v199
	v_med3_i32 v75, v74, s39, v198
	v_med3_i32 v74, v74, s33, v199
	v_med3_i32 v77, v76, s39, v198
	v_med3_i32 v76, v76, s33, v199
	v_lshl_add_u32 v71, v71, 2, s76
	v_lshl_add_u32 v70, v70, 2, s76
	v_lshl_add_u32 v73, v73, 2, s76
	v_lshl_add_u32 v72, v72, 2, s76
	v_lshl_add_u32 v74, v74, 2, s76
	v_lshl_add_u32 v76, v76, 2, s76
	v_lshl_add_u32 v75, v75, 2, s76
	v_lshl_add_u32 v77, v77, 2, s76
	ds_read_b32 v233, v71 offset:516
	ds_read_b32 v70, v70 offset:644
	ds_read_b32 v234, v73 offset:516
	ds_read_b32 v71, v72 offset:644
	ds_read_b32 v235, v75 offset:516
	ds_read_b32 v72, v74 offset:644
	ds_read_b32 v236, v77 offset:516
	ds_read_b32 v73, v76 offset:644
	v_add_u32_e32 v74, 0x90, v227
	v_add_u32_e32 v76, 0x91, v227
	v_add_u32_e32 v78, 0x92, v227
	v_add_u32_e32 v80, 0x93, v227
	v_med3_i32 v75, v74, s39, v198
	v_med3_i32 v74, v74, s33, v199
	v_med3_i32 v77, v76, s39, v198
	v_med3_i32 v76, v76, s33, v199
	v_med3_i32 v79, v78, s39, v198
	v_med3_i32 v78, v78, s33, v199
	v_med3_i32 v81, v80, s39, v198
	v_med3_i32 v80, v80, s33, v199
	v_lshl_add_u32 v75, v75, 2, s76
	v_lshl_add_u32 v74, v74, 2, s76
	v_lshl_add_u32 v77, v77, 2, s76
	v_lshl_add_u32 v76, v76, 2, s76
	v_lshl_add_u32 v78, v78, 2, s76
	v_lshl_add_u32 v80, v80, 2, s76
	v_lshl_add_u32 v79, v79, 2, s76
	v_lshl_add_u32 v81, v81, 2, s76
	ds_read_b32 v237, v75 offset:516
	ds_read_b32 v74, v74 offset:644
	ds_read_b32 v238, v77 offset:516
	ds_read_b32 v75, v76 offset:644
	ds_read_b32 v239, v79 offset:516
	ds_read_b32 v76, v78 offset:644
	ds_read_b32 v240, v81 offset:516
	ds_read_b32 v77, v80 offset:644
	v_add_u32_e32 v78, 0x98, v227
	v_add_u32_e32 v80, 0x99, v227
	v_add_u32_e32 v82, 0x9a, v227
	v_med3_i32 v79, v78, s39, v198
	v_med3_i32 v78, v78, s33, v199
	v_med3_i32 v81, v80, s39, v198
	v_med3_i32 v80, v80, s33, v199
	v_med3_i32 v83, v82, s39, v198
	v_med3_i32 v82, v82, s33, v199
	v_add_u32_e32 v84, 0x9b, v227
	s_waitcnt lgkmcnt(14)
	v_fmac_f32_e32 v194, 0x3e38aa3b, v114
	v_fmac_f32_e32 v195, 0x3e38aa3b, v115
	v_lshl_add_u32 v79, v79, 2, s76
	v_lshl_add_u32 v78, v78, 2, s76
	v_lshl_add_u32 v81, v81, 2, s76
	v_lshl_add_u32 v80, v80, 2, s76
	v_lshl_add_u32 v82, v82, 2, s76
	v_med3_i32 v85, v84, s39, v198
	v_med3_i32 v84, v84, s33, v199
	v_fmac_f32_e32 v231, 0x3e38aa3b, v116
	v_fmac_f32_e32 v232, 0x3e38aa3b, v117
	v_lshl_add_u32 v83, v83, 2, s76
	v_lshl_add_u32 v85, v85, 2, s76
	v_lshl_add_u32 v84, v84, 2, s76
	ds_read_b32 v227, v79 offset:516
	ds_read_b32 v78, v78 offset:644
	ds_read_b32 v241, v81 offset:516
	ds_read_b32 v79, v80 offset:644
	ds_read_b32 v242, v83 offset:516
	ds_read_b32 v80, v82 offset:644
	ds_read_b32 v243, v85 offset:516
	ds_read_b32 v81, v84 offset:644
	v_max_f32_e32 v82, v194, v195
	v_fmac_f32_e32 v233, 0x3e38aa3b, v118
	s_waitcnt lgkmcnt(14)
	v_fmac_f32_e32 v234, 0x3e38aa3b, v119
	v_max3_f32 v82, v82, v231, v232
	v_fmac_f32_e32 v235, 0x3e38aa3b, v120
	v_fmac_f32_e32 v236, 0x3e38aa3b, v121
	v_max3_f32 v82, v82, v233, v234
	v_fmac_f32_e32 v237, 0x3e38aa3b, v122
	s_waitcnt lgkmcnt(13)
; template <int MODE>
; __device__ __forceinline__ void partialSM(f32x16& p0, f32x16& p1, float& m_reg, float& mn, float& alpha, int relh, int relw_min, int relw_max, const float* lut) {
;     ...
;       if (!nearT) {
;         float pmax = p0[0];
; #pragma unroll
;         for (int r = 1; r < 16; ++r) pmax = fmaxf(pmax, p0[r]);
; #pragma unroll
;         for (int r = 0; r < 16; ++r) pmax = fmaxf(pmax, p1[r]);
;         { auto rr = __builtin_amdgcn_permlane32_swap(__float_as_uint(pmax), __float_as_uint(pmax), false, false);
;           pmax = fmaxf(__uint_as_float(rr[0]), __uint_as_float(rr[1])); }
;         const float tmax = fmaf(pmax, C, cfar);
;         if (__builtin_expect(__all(tmax - m_reg <= THR2), 1)) { mn = m_reg; alpha = 1.f; }
;         else { mn = fmaxf(m_reg, tmax); alpha = __builtin_amdgcn_exp2f(m_reg - mn); m_reg = mn; }
;         const float off = cfar - mn;
; #pragma unroll
;         for (int r = 0; r < 16; ++r) p0[r] = fmaf(p0[r], C, off);
; #pragma unroll
;         for (int r = 0; r < 16; ++r) p1[r] = fmaf(p1[r], C, off);
; #pragma unroll
;         for (int r = 0; r < 16; ++r) p0[r] = __builtin_amdgcn_exp2f(p0[r]);
;     ...
;     { auto rr = __builtin_amdgcn_permlane32_swap(__float_as_uint(pmax), __float_as_uint(pmax), false, false);
;       pmax = fmaxf(__uint_as_float(rr[0]), __uint_as_float(rr[1])); }
;     if (__builtin_expect(__all(pmax - m_reg <= THR2), 1)) { mn = m_reg; alpha = 1.f; }
;     else { mn = fmaxf(m_reg, pmax); alpha = __builtin_amdgcn_exp2f(m_reg - mn); m_reg = mn; }
; #pragma unroll
;     for (int r = 0; r < 16; ++r) p0[r] = __builtin_amdgcn_exp2f(p0[r] - mn);
; #pragma unroll
;     for (int r = 0; r < 16; ++r) p1[r] = p1[r] - mn;
	v_fmac_f32_e32 v238, 0x3e38aa3b, v123
	v_max3_f32 v82, v82, v235, v236
	s_waitcnt lgkmcnt(11)
	v_fmac_f32_e32 v239, 0x3e38aa3b, v124
	s_waitcnt lgkmcnt(9)
	v_fmac_f32_e32 v240, 0x3e38aa3b, v125
	v_max3_f32 v82, v82, v237, v238
	s_waitcnt lgkmcnt(7)
	v_fmac_f32_e32 v227, 0x3e38aa3b, v126
	s_waitcnt lgkmcnt(5)
	v_fmac_f32_e32 v241, 0x3e38aa3b, v127
	v_max3_f32 v82, v82, v239, v240
	s_waitcnt lgkmcnt(3)
	v_fmac_f32_e32 v242, 0x3e38aa3b, v128
	s_waitcnt lgkmcnt(1)
	v_fmac_f32_e32 v243, 0x3e38aa3b, v129
	v_max3_f32 v82, v82, v227, v241
	v_max3_f32 v84, v82, v242, v243
	v_pk_fma_f32 v[82:83], v[98:99], s[48:49], v[66:67] op_sel_hi:[1,0,1]
	v_pk_fma_f32 v[86:87], v[102:103], s[48:49], v[70:71] op_sel_hi:[1,0,1]
	v_max3_f32 v66, v84, v82, v83
	v_pk_fma_f32 v[84:85], v[100:101], s[48:49], v[68:69] op_sel_hi:[1,0,1]
	v_pk_fma_f32 v[88:89], v[104:105], s[48:49], v[72:73] op_sel_hi:[1,0,1]
	v_max3_f32 v66, v66, v84, v85
	v_max3_f32 v66, v66, v86, v87
	v_max3_f32 v66, v66, v88, v89
	v_pk_fma_f32 v[90:91], v[106:107], s[48:49], v[74:75] op_sel_hi:[1,0,1]
	v_pk_fma_f32 v[92:93], v[108:109], s[48:49], v[76:77] op_sel_hi:[1,0,1]
	v_max3_f32 v66, v66, v90, v91
	v_max3_f32 v66, v66, v92, v93
	v_pk_fma_f32 v[94:95], v[110:111], s[48:49], v[78:79] op_sel_hi:[1,0,1]
	s_waitcnt lgkmcnt(0)
	v_pk_fma_f32 v[96:97], v[112:113], s[48:49], v[80:81] op_sel_hi:[1,0,1]
	v_max3_f32 v66, v66, v94, v95
	v_max3_f32 v66, v66, v96, v97
	v_mov_b32_e32 v67, v66
	s_nop 1
	v_permlane32_swap_b32_e32 v66, v67
	v_max_f32_e32 v66, v66, v67
	v_sub_f32_e32 v67, v66, v228
	v_cmp_ge_f32_e32 vcc, s94, v67
	v_max_f32_e32 v66, v228, v66
	v_sub_f32_e32 v67, v228, v66
	v_exp_f32_e32 v67, v67
	s_cmp_eq_u64 vcc, exec
	s_cselect_b64 vcc, -1, 0
	v_cndmask_b32_e32 v219, v66, v228, vcc
	v_cndmask_b32_e64 v225, v67, 1.0, vcc
	v_sub_f32_e32 v66, v194, v219
	v_sub_f32_e32 v67, v195, v219
	v_sub_f32_e32 v68, v231, v219
	v_sub_f32_e32 v69, v232, v219
	v_sub_f32_e32 v70, v233, v219
	v_sub_f32_e32 v71, v234, v219
	v_sub_f32_e32 v72, v235, v219
	v_sub_f32_e32 v73, v236, v219
	v_sub_f32_e32 v74, v237, v219
	v_sub_f32_e32 v75, v238, v219
	v_sub_f32_e32 v76, v239, v219
	v_sub_f32_e32 v77, v240, v219
	v_sub_f32_e32 v78, v227, v219
	v_sub_f32_e32 v79, v241, v219
	v_sub_f32_e32 v80, v242, v219
	v_sub_f32_e32 v81, v243, v219
	v_exp_f32_e32 v66, v66
	v_exp_f32_e32 v67, v67
	v_exp_f32_e32 v68, v68
	v_exp_f32_e32 v69, v69
	v_exp_f32_e32 v70, v70
	v_exp_f32_e32 v71, v71
	v_exp_f32_e32 v72, v72
	v_exp_f32_e32 v73, v73
	v_exp_f32_e32 v74, v74
	v_exp_f32_e32 v75, v75
	v_exp_f32_e32 v76, v76
	v_exp_f32_e32 v77, v77
	v_exp_f32_e32 v78, v78
	v_exp_f32_e32 v79, v79
	v_exp_f32_e32 v80, v80
	v_exp_f32_e32 v81, v81
	v_sub_f32_e32 v97, v97, v219
	v_sub_f32_e32 v96, v96, v219
	v_sub_f32_e32 v95, v95, v219
	v_sub_f32_e32 v94, v94, v219
	v_sub_f32_e32 v93, v93, v219
	v_sub_f32_e32 v92, v92, v219
	v_sub_f32_e32 v91, v91, v219
	v_sub_f32_e32 v90, v90, v219
	v_sub_f32_e32 v89, v89, v219
	v_sub_f32_e32 v88, v88, v219
	v_sub_f32_e32 v87, v87, v219
	v_sub_f32_e32 v86, v86, v219
	v_sub_f32_e32 v85, v85, v219
	v_sub_f32_e32 v84, v84, v219
	v_sub_f32_e32 v83, v83, v219
	v_sub_f32_e32 v82, v82, v219
	s_xor_b64 s[72:73], exec, -1
.LBB0_147:
	s_or_b64 exec, exec, s[70:71]
	s_andn2_b64 s[66:67], s[66:67], exec
	s_and_b64 s[70:71], s[72:73], exec
	v_mov_b32_e32 v231, v161
	s_or_b64 s[66:67], s[66:67], s[70:71]
.LBB0_148:
	s_or_b64 exec, exec, s[68:69]
	s_and_saveexec_b64 s[68:69], s[66:67]
	s_cbranch_execz .LBB0_150
	v_mov_b32_e32 v66, v231
	v_mov_b32_e32 v219, v228
	v_sub_f32_e32 v66, v66, v219
	v_fmamk_f32 v67, v114, 0x3e38aa3b, v66
	v_mov_b32_e32 v114, v66
	v_mov_b32_e32 v225, 1.0
	v_fmamk_f32 v68, v115, 0x3e38aa3b, v66
	v_fmamk_f32 v69, v116, 0x3e38aa3b, v66
	v_fmamk_f32 v70, v117, 0x3e38aa3b, v66
	v_fmamk_f32 v71, v118, 0x3e38aa3b, v66
	v_fmamk_f32 v72, v119, 0x3e38aa3b, v66
	v_fmamk_f32 v73, v120, 0x3e38aa3b, v66
	v_fmamk_f32 v74, v121, 0x3e38aa3b, v66
	v_fmamk_f32 v75, v122, 0x3e38aa3b, v66
	v_fmamk_f32 v76, v123, 0x3e38aa3b, v66
	v_fmamk_f32 v77, v124, 0x3e38aa3b, v66
	v_fmamk_f32 v78, v125, 0x3e38aa3b, v66
	v_fmamk_f32 v79, v126, 0x3e38aa3b, v66
	v_fmamk_f32 v80, v127, 0x3e38aa3b, v66
	v_fmamk_f32 v81, v128, 0x3e38aa3b, v66
	v_fmac_f32_e32 v114, 0x3e38aa3b, v129
	v_fmamk_f32 v97, v113, 0x3e38aa3b, v66
	v_fmamk_f32 v96, v112, 0x3e38aa3b, v66
	v_fmamk_f32 v95, v111, 0x3e38aa3b, v66
	v_fmamk_f32 v94, v110, 0x3e38aa3b, v66
	v_fmamk_f32 v93, v109, 0x3e38aa3b, v66
	v_fmamk_f32 v92, v108, 0x3e38aa3b, v66
	v_fmamk_f32 v91, v107, 0x3e38aa3b, v66
	v_fmamk_f32 v90, v106, 0x3e38aa3b, v66
	v_fmamk_f32 v89, v105, 0x3e38aa3b, v66
	v_fmamk_f32 v88, v104, 0x3e38aa3b, v66
	v_fmamk_f32 v87, v103, 0x3e38aa3b, v66
	v_fmamk_f32 v86, v102, 0x3e38aa3b, v66
	v_fmamk_f32 v85, v101, 0x3e38aa3b, v66
	v_fmamk_f32 v84, v100, 0x3e38aa3b, v66
	v_fmamk_f32 v83, v99, 0x3e38aa3b, v66
	v_fmamk_f32 v82, v98, 0x3e38aa3b, v66
	v_exp_f32_e32 v66, v67
	v_exp_f32_e32 v67, v68
	v_exp_f32_e32 v68, v69
	v_exp_f32_e32 v69, v70
	v_exp_f32_e32 v70, v71
	v_exp_f32_e32 v71, v72
	v_exp_f32_e32 v72, v73
	v_exp_f32_e32 v73, v74
	v_exp_f32_e32 v74, v75
	v_exp_f32_e32 v75, v76
	v_exp_f32_e32 v76, v77
	v_exp_f32_e32 v77, v78
	v_exp_f32_e32 v78, v79
	v_exp_f32_e32 v79, v80
	v_exp_f32_e32 v80, v81
	v_exp_f32_e32 v81, v114

; #define SBAR() __builtin_amdgcn_sched_barrier(0)
; #define RESC(a) do { if (__any((a) < 1.f)) { if (hi == 0) al_l[r32] = (a); asm volatile("s_waitcnt lgkmcnt(0)" ::: "memory"); \
;     _Pragma("unroll") for (int d = 0; d < 4; ++d) _Pragma("unroll") for (int r = 0; r < 16; ++r) o[d][r] *= al_l[crow(r, hi)]; } } while (0)
; #define PSM(P0, P1, MN, AL, J) partialSM<MODE>(P0, P1, m_reg, MN, AL, relq + 64 * (J), relwmin + 64 * (J), relwmax + 64 * (J), lut)
; __device__ __forceinline__ void finishSM(f32x16& p0, f32x16& p1, float alpha, float& l_reg, bf16x8& pa0, bf16x8& pa1, bf16x8& pa2, bf16x8& pa3) {
; #pragma unroll
;   for (int r = 0; r < 16; ++r) p1[r] = __builtin_amdgcn_exp2f(p1[r]);
;   float ps = 0;
; #pragma unroll
;   for (int r = 0; r < 16; ++r) ps += p0[r];
; #pragma unroll
;   for (int r = 0; r < 16; ++r) ps += p1[r];
;   { auto rr = __builtin_amdgcn_permlane32_swap(__float_as_uint(ps), __float_as_uint(ps), false, false);
;     ps = __uint_as_float(rr[0]) + __uint_as_float(rr[1]); }
;   l_reg = l_reg * alpha + ps;
;     ...
;   PK4(p0, 0, pa0); PK4(p0, 8, pa1); PK4(p1, 0, pa2); PK4(p1, 8, pa3);
; template <int MODE>
; __device__ __forceinline__ void attn_body(const bf16_t* __restrict__ Qb, const bf16_t* __restrict__ Kh, const bf16_t* __restrict__ Vh, int NT, int krel0,
;                                           char* lds, const float* __restrict__ lutg, const AttnEpi& E) {
;     ...
;   __syncthreads();
;   SBAR(); qkt<ND0, DOFF>(pB0, pB1, K_lds + oq, qr, r32, hi);
;   finishSM(pA0, pA1, alA, l_reg, pa0, pa1, pa2, pa3); SBAR();
;   pv_d0(o, vb0 + op, pa0, pa1, pa2, pa3); PSM(pB0, pB1, mnB, alB, NT - 1);
;   RESC(alB);
;   finishSM(pB0, pB1, alB, l_reg, pa0, pa1, pa2, pa3); SBAR();
;   pv_d0(o, vb0 + oq, pa0, pa1, pa2, pa3);
.Ldp_2:
	v_add_u32_e32 v102, s68, v213
	ds_read_b128 v[98:101], v102 offset:49152
	ds_read_b128 v[102:105], v102 offset:57344
	v_add_u32_e32 v146, s68, v214
	v_exp_f32_e32 v82, v82
	v_exp_f32_e32 v83, v83
	s_waitcnt lgkmcnt(1)
	v_mfma_f32_32x32x16_bf16 v[114:129], v[98:101], v[142:145], 0
	v_exp_f32_e32 v84, v84
	v_exp_f32_e32 v85, v85
	v_exp_f32_e32 v86, v86
	v_exp_f32_e32 v87, v87
	v_exp_f32_e32 v88, v88
	v_exp_f32_e32 v89, v89
	v_exp_f32_e32 v90, v90
	s_waitcnt lgkmcnt(0)
	v_mfma_f32_32x32x16_bf16 v[98:113], v[102:105], v[142:145], 0
	ds_read_b128 v[142:145], v146 offset:49152
	ds_read_b128 v[146:149], v146 offset:57344
	v_exp_f32_e32 v91, v91
	v_exp_f32_e32 v92, v92
	v_exp_f32_e32 v93, v93
	v_exp_f32_e32 v94, v94
	v_exp_f32_e32 v95, v95
	v_exp_f32_e32 v96, v96
	s_waitcnt lgkmcnt(1)
	v_mfma_f32_32x32x16_bf16 v[114:129], v[142:145], v[138:141], v[114:129]
	v_add_u32_e32 v142, s68, v215
	v_exp_f32_e32 v97, v97
	s_waitcnt lgkmcnt(0)
	v_mfma_f32_32x32x16_bf16 v[98:113], v[146:149], v[138:141], v[98:113]
	ds_read_b128 v[138:141], v142 offset:49152
	ds_read_b128 v[142:145], v142 offset:57344
	s_waitcnt lgkmcnt(1)
	v_mfma_f32_32x32x16_bf16 v[114:129], v[138:141], v[134:137], v[114:129]
	v_add_u32_e32 v138, s68, v216
	s_waitcnt lgkmcnt(0)
	v_mfma_f32_32x32x16_bf16 v[98:113], v[142:145], v[134:137], v[98:113]
	ds_read_b128 v[134:137], v138 offset:49152
	ds_read_b128 v[138:141], v138 offset:57344
	s_waitcnt lgkmcnt(1)
	v_mfma_f32_32x32x16_bf16 v[114:129], v[134:137], v[130:133], v[114:129]
	s_waitcnt lgkmcnt(0)
	v_mfma_f32_32x32x16_bf16 v[98:113], v[138:141], v[130:133], v[98:113]
	s_cmp_lt_u32 s31, 4
	s_cbranch_scc1 .Ldp_1
	s_waitcnt vmcnt(0) lgkmcnt(0)
	s_barrier
.Ldp_1:
	v_add_f32_e32 v130, 0, v66
	v_add_f32_e32 v130, v67, v130
	v_add_f32_e32 v130, v68, v130
	v_add_f32_e32 v130, v69, v130
	v_add_f32_e32 v130, v70, v130
	v_add_f32_e32 v130, v71, v130
	v_add_f32_e32 v130, v72, v130
	v_add_f32_e32 v130, v73, v130
	v_add_f32_e32 v130, v74, v130
	v_add_f32_e32 v130, v75, v130
	v_add_f32_e32 v130, v76, v130
	v_add_f32_e32 v130, v77, v130
	v_add_f32_e32 v130, v78, v130
	v_add_f32_e32 v130, v79, v130
	v_add_f32_e32 v130, v80, v130
	v_add_f32_e32 v130, v81, v130
	v_add_f32_e32 v130, v82, v130
	v_add_f32_e32 v130, v83, v130
	v_add_f32_e32 v130, v84, v130
	v_add_f32_e32 v130, v85, v130
	v_add_f32_e32 v130, v86, v130
	v_add_f32_e32 v130, v87, v130
	v_add_f32_e32 v130, v88, v130
	v_add_f32_e32 v130, v89, v130
	v_add_f32_e32 v130, v90, v130
	v_add_f32_e32 v130, v91, v130
	v_add_f32_e32 v130, v92, v130
	v_add_f32_e32 v130, v93, v130
	v_add_f32_e32 v130, v94, v130
	v_add_f32_e32 v130, v95, v130
	v_add_f32_e32 v130, v96, v130
	v_add_f32_e32 v130, v97, v130
	v_mov_b32_e32 v131, v130
	v_cvt_pk_bf16_f32 v66, v66, v67
	v_cvt_pk_bf16_f32 v67, v68, v69
	v_cvt_pk_bf16_f32 v68, v70, v71
	v_cvt_pk_bf16_f32 v69, v72, v73
	v_cvt_pk_bf16_f32 v70, v74, v75
	v_cvt_pk_bf16_f32 v71, v76, v77
	v_cvt_pk_bf16_f32 v72, v78, v79
	v_cvt_pk_bf16_f32 v73, v80, v81
	v_cvt_pk_bf16_f32 v74, v82, v83
	v_cvt_pk_bf16_f32 v75, v84, v85
	v_cvt_pk_bf16_f32 v76, v86, v87
	v_cvt_pk_bf16_f32 v77, v88, v89
	v_cvt_pk_bf16_f32 v78, v90, v91
	v_cvt_pk_bf16_f32 v79, v92, v93
	v_cvt_pk_bf16_f32 v80, v94, v95
	v_cvt_pk_bf16_f32 v81, v96, v97
	v_permlane32_swap_b32_e32 v130, v131
	v_permlane32_swap_b32_e32 v66, v68
	v_permlane32_swap_b32_e32 v67, v69
	v_permlane32_swap_b32_e32 v70, v72
	v_permlane32_swap_b32_e32 v71, v73
	v_permlane32_swap_b32_e32 v74, v76
	v_permlane32_swap_b32_e32 v75, v77
	v_permlane32_swap_b32_e32 v78, v80
	v_permlane32_swap_b32_e32 v79, v81
	v_add_u32_e32 v132, s79, v218
	ds_read_b64_tr_b16 v[82:83], v132 offset:0
	ds_read_b64_tr_b16 v[84:85], v132 offset:0x800
	ds_read_b64_tr_b16 v[86:87], v132 offset:0x1000
	ds_read_b64_tr_b16 v[88:89], v132 offset:0x1800
	ds_read_b64_tr_b16 v[90:91], v132 offset:0x2000
	ds_read_b64_tr_b16 v[92:93], v132 offset:0x2800
	ds_read_b64_tr_b16 v[94:95], v132 offset:0x3000
	ds_read_b64_tr_b16 v[96:97], v132 offset:0x3800
	s_waitcnt lgkmcnt(0)
	s_nop 0
	v_mfma_f32_32x32x16_bf16 v[50:65], v[66:69], v[82:85], v[50:65]
	ds_read_b64_tr_b16 v[82:83], v132 offset:0x200
	ds_read_b64_tr_b16 v[84:85], v132 offset:0xa00
	v_mfma_f32_32x32x16_bf16 v[50:65], v[70:73], v[86:89], v[50:65]
	ds_read_b64_tr_b16 v[86:87], v132 offset:0x1200
	ds_read_b64_tr_b16 v[88:89], v132 offset:0x1a00
	v_mfma_f32_32x32x16_bf16 v[50:65], v[74:77], v[90:93], v[50:65]
	ds_read_b64_tr_b16 v[90:91], v132 offset:0x2200
	ds_read_b64_tr_b16 v[92:93], v132 offset:0x2a00
	v_mfma_f32_32x32x16_bf16 v[50:65], v[78:81], v[94:97], v[50:65]
	ds_read_b64_tr_b16 v[94:95], v132 offset:0x3200
	ds_read_b64_tr_b16 v[96:97], v132 offset:0x3a00
	s_waitcnt lgkmcnt(0)
	v_mfma_f32_32x32x16_bf16 v[34:49], v[66:69], v[82:85], v[34:49]
	ds_read_b64_tr_b16 v[82:83], v132 offset:0x400
	ds_read_b64_tr_b16 v[84:85], v132 offset:0xc00
	v_mfma_f32_32x32x16_bf16 v[34:49], v[70:73], v[86:89], v[34:49]
	ds_read_b64_tr_b16 v[86:87], v132 offset:0x1400
	ds_read_b64_tr_b16 v[88:89], v132 offset:0x1c00
	v_mfma_f32_32x32x16_bf16 v[34:49], v[74:77], v[90:93], v[34:49]
	ds_read_b64_tr_b16 v[90:91], v132 offset:0x2400
	ds_read_b64_tr_b16 v[92:93], v132 offset:0x2c00
	v_mfma_f32_32x32x16_bf16 v[34:49], v[78:81], v[94:97], v[34:49]
	ds_read_b64_tr_b16 v[94:95], v132 offset:0x3400
	ds_read_b64_tr_b16 v[96:97], v132 offset:0x3c00
	s_waitcnt lgkmcnt(0)
	v_mfma_f32_32x32x16_bf16 v[18:33], v[66:69], v[82:85], v[18:33]
	ds_read_b64_tr_b16 v[82:83], v132 offset:0x600
	ds_read_b64_tr_b16 v[84:85], v132 offset:0xe00
	v_mfma_f32_32x32x16_bf16 v[18:33], v[70:73], v[86:89], v[18:33]
	ds_read_b64_tr_b16 v[86:87], v132 offset:0x1600
	ds_read_b64_tr_b16 v[88:89], v132 offset:0x1e00
	v_mfma_f32_32x32x16_bf16 v[18:33], v[74:77], v[90:93], v[18:33]
	ds_read_b64_tr_b16 v[90:91], v132 offset:0x2600
	ds_read_b64_tr_b16 v[92:93], v132 offset:0x2e00
	v_mfma_f32_32x32x16_bf16 v[18:33], v[78:81], v[94:97], v[18:33]
	ds_read_b64_tr_b16 v[94:95], v132 offset:0x3600
	ds_read_b64_tr_b16 v[96:97], v132 offset:0x3e00
	s_waitcnt lgkmcnt(0)
	v_mfma_f32_32x32x16_bf16 v[2:17], v[66:69], v[82:85], v[2:17]
	s_lshl_b32 s64, s11, 6
	s_sub_i32 s72, s64, 64
	v_add_u32_e32 v66, s72, v205
	v_cmp_gt_i32_e64 s[64:65], s95, v66
	v_cmp_lt_i32_e32 vcc, s15, v66
	v_mov_b32_e32 v133, s76
	v_mfma_f32_32x32x16_bf16 v[2:17], v[70:73], v[86:89], v[2:17]
	v_mfma_f32_32x32x16_bf16 v[2:17], v[74:77], v[90:93], v[2:17]
	v_mfma_f32_32x32x16_bf16 v[2:17], v[78:81], v[94:97], v[2:17]
	s_and_saveexec_b64 s[66:67], vcc
	v_readlane_b32 s79, v254, 57
	s_cbranch_execz .LBB0_160
; template <int MODE>
; __device__ __forceinline__ void partialSM(f32x16& p0, f32x16& p1, float& m_reg, float& mn, float& alpha, int relh, int relw_min, int relw_max, const float* lut) {
;     ...
;     if (nearT) {
; #pragma unroll
;       for (int r = 0; r < 16; ++r) { const int i0 = relh + (r & 3) + 8 * (r >> 2);
;         const int a0 = min(max(i0, -129), 129) + 129, a1 = min(max(i0 + 32, -129), 129) + 129;
;         p0[r] = fmaf(p0[r], C, lut[a0]); p1[r] = fmaf(p1[r], C, lut[a1]); }
;     } else {
; #pragma unroll
;       for (int r = 0; r < 16; ++r) { p0[r] = fmaf(p0[r], C, cfar); p1[r] = fmaf(p1[r], C, cfar); }
;     }
;     float pmax = p0[0];
; #pragma unroll
;     for (int r = 1; r < 16; ++r) pmax = fmaxf(pmax, p0[r]);
; #pragma unroll
;     for (int r = 0; r < 16; ++r) pmax = fmaxf(pmax, p1[r]);
	v_add_u32_e32 v66, s72, v204
	v_cmp_gt_i32_e32 vcc, s91, v66
	s_mov_b64 s[70:71], -1
	s_and_saveexec_b64 s[68:69], vcc
	s_cbranch_execz .LBB0_159
	v_add_u32_e32 v78, s72, v184
	v_add_u32_e32 v68, 1, v78
	v_add_u32_e32 v70, 2, v78
	v_add_u32_e32 v72, 3, v78
	v_med3_i32 v66, v78, s39, v198
	v_med3_i32 v67, v78, s33, v199
	v_med3_i32 v69, v68, s39, v198
	v_med3_i32 v68, v68, s33, v199
	v_med3_i32 v71, v70, s39, v198
	v_med3_i32 v70, v70, s33, v199
	v_med3_i32 v73, v72, s39, v198
	v_med3_i32 v72, v72, s33, v199
	v_lshl_add_u32 v66, v66, 2, s76
	v_lshl_add_u32 v67, v67, 2, s76
	v_lshl_add_u32 v69, v69, 2, s76
	v_lshl_add_u32 v68, v68, 2, s76
	v_lshl_add_u32 v70, v70, 2, s76
	v_lshl_add_u32 v72, v72, 2, s76
	v_lshl_add_u32 v71, v71, 2, s76
	v_lshl_add_u32 v73, v73, 2, s76
	ds_read_b32 v133, v66 offset:516
	ds_read_b32 v66, v67 offset:644
	ds_read_b32 v134, v69 offset:516
	ds_read_b32 v67, v68 offset:644
	ds_read_b32 v135, v71 offset:516
	ds_read_b32 v68, v70 offset:644
	ds_read_b32 v136, v73 offset:516
	ds_read_b32 v69, v72 offset:644
	v_add_u32_e32 v70, 8, v78
	v_add_u32_e32 v72, 9, v78
	v_add_u32_e32 v74, 10, v78
	v_add_u32_e32 v76, 11, v78
	v_med3_i32 v71, v70, s39, v198
	v_med3_i32 v70, v70, s33, v199
	v_med3_i32 v73, v72, s39, v198
	v_med3_i32 v72, v72, s33, v199
	v_med3_i32 v75, v74, s39, v198
	v_med3_i32 v74, v74, s33, v199
	v_med3_i32 v77, v76, s39, v198
	v_med3_i32 v76, v76, s33, v199
	v_lshl_add_u32 v71, v71, 2, s76
	v_lshl_add_u32 v70, v70, 2, s76
	v_lshl_add_u32 v73, v73, 2, s76
	v_lshl_add_u32 v72, v72, 2, s76
	v_lshl_add_u32 v74, v74, 2, s76
	v_lshl_add_u32 v76, v76, 2, s76
	v_lshl_add_u32 v75, v75, 2, s76
	v_lshl_add_u32 v77, v77, 2, s76
	ds_read_b32 v137, v71 offset:516
	ds_read_b32 v70, v70 offset:644
	ds_read_b32 v138, v73 offset:516
	ds_read_b32 v71, v72 offset:644
	ds_read_b32 v139, v75 offset:516
	ds_read_b32 v72, v74 offset:644
	ds_read_b32 v140, v77 offset:516
	ds_read_b32 v73, v76 offset:644
	v_add_u32_e32 v74, 16, v78
	v_add_u32_e32 v76, 17, v78
	v_add_u32_e32 v79, 18, v78
	v_add_u32_e32 v81, 19, v78
	v_med3_i32 v75, v74, s39, v198
	v_med3_i32 v74, v74, s33, v199
	v_med3_i32 v77, v76, s39, v198
	v_med3_i32 v76, v76, s33, v199
	v_med3_i32 v80, v79, s39, v198
	v_med3_i32 v79, v79, s33, v199
	v_med3_i32 v82, v81, s39, v198
	v_med3_i32 v81, v81, s33, v199
	v_lshl_add_u32 v75, v75, 2, s76
	v_lshl_add_u32 v74, v74, 2, s76
	v_lshl_add_u32 v77, v77, 2, s76
	v_lshl_add_u32 v76, v76, 2, s76
	v_lshl_add_u32 v79, v79, 2, s76
	v_lshl_add_u32 v81, v81, 2, s76
	v_lshl_add_u32 v80, v80, 2, s76
	v_lshl_add_u32 v82, v82, 2, s76
	ds_read_b32 v141, v75 offset:516
	ds_read_b32 v74, v74 offset:644
	ds_read_b32 v142, v77 offset:516
	ds_read_b32 v75, v76 offset:644
	ds_read_b32 v143, v80 offset:516
	ds_read_b32 v76, v79 offset:644
	ds_read_b32 v144, v82 offset:516
	ds_read_b32 v77, v81 offset:644
	v_add_u32_e32 v79, 24, v78
	v_add_u32_e32 v81, 25, v78
	v_med3_i32 v80, v79, s39, v198
	v_med3_i32 v79, v79, s33, v199
	v_med3_i32 v82, v81, s39, v198
	v_med3_i32 v81, v81, s33, v199
	v_add_u32_e32 v83, 26, v78
	v_add_u32_e32 v78, 27, v78
	s_waitcnt lgkmcnt(14)
	v_fmac_f32_e32 v133, 0x3e38aa3b, v114
	v_fmac_f32_e32 v134, 0x3e38aa3b, v115
	v_lshl_add_u32 v80, v80, 2, s76
	v_lshl_add_u32 v79, v79, 2, s76
	v_lshl_add_u32 v82, v82, 2, s76
	v_lshl_add_u32 v81, v81, 2, s76
	v_med3_i32 v84, v83, s39, v198
	v_med3_i32 v83, v83, s33, v199
	v_med3_i32 v85, v78, s39, v198
	v_med3_i32 v78, v78, s33, v199
	v_fmac_f32_e32 v135, 0x3e38aa3b, v116
	v_fmac_f32_e32 v136, 0x3e38aa3b, v117
	v_lshl_add_u32 v84, v84, 2, s76
	v_lshl_add_u32 v83, v83, 2, s76
	v_lshl_add_u32 v85, v85, 2, s76
	v_lshl_add_u32 v86, v78, 2, s76
	ds_read_b32 v145, v80 offset:516
	ds_read_b32 v78, v79 offset:644
	ds_read_b32 v146, v82 offset:516
	ds_read_b32 v79, v81 offset:644
	ds_read_b32 v147, v84 offset:516
	ds_read_b32 v80, v83 offset:644
	ds_read_b32 v148, v85 offset:516
	ds_read_b32 v81, v86 offset:644
	v_max_f32_e32 v82, v133, v134
	v_fmac_f32_e32 v137, 0x3e38aa3b, v118
	s_waitcnt lgkmcnt(14)
; template <int MODE>
; __device__ __forceinline__ void partialSM(f32x16& p0, f32x16& p1, float& m_reg, float& mn, float& alpha, int relh, int relw_min, int relw_max, const float* lut) {
;     ...
;     float pmax = p0[0];
; #pragma unroll
;     for (int r = 1; r < 16; ++r) pmax = fmaxf(pmax, p0[r]);
; #pragma unroll
;     for (int r = 0; r < 16; ++r) pmax = fmaxf(pmax, p1[r]);
;     { auto rr = __builtin_amdgcn_permlane32_swap(__float_as_uint(pmax), __float_as_uint(pmax), false, false);
;       pmax = fmaxf(__uint_as_float(rr[0]), __uint_as_float(rr[1])); }
;     if (__builtin_expect(__all(pmax - m_reg <= THR2), 1)) { mn = m_reg; alpha = 1.f; }
;     else { mn = fmaxf(m_reg, pmax); alpha = __builtin_amdgcn_exp2f(m_reg - mn); m_reg = mn; }
; #pragma unroll
;     for (int r = 0; r < 16; ++r) p0[r] = __builtin_amdgcn_exp2f(p0[r] - mn);
; #pragma unroll
;     for (int r = 0; r < 16; ++r) p1[r] = p1[r] - mn;
	v_fmac_f32_e32 v138, 0x3e38aa3b, v119
	v_max3_f32 v82, v82, v135, v136
	v_fmac_f32_e32 v139, 0x3e38aa3b, v120
	v_fmac_f32_e32 v140, 0x3e38aa3b, v121
	v_max3_f32 v82, v82, v137, v138
	v_fmac_f32_e32 v141, 0x3e38aa3b, v122
	s_waitcnt lgkmcnt(13)
	v_fmac_f32_e32 v142, 0x3e38aa3b, v123
	v_max3_f32 v82, v82, v139, v140
	s_waitcnt lgkmcnt(11)
	v_fmac_f32_e32 v143, 0x3e38aa3b, v124
	s_waitcnt lgkmcnt(9)
	v_fmac_f32_e32 v144, 0x3e38aa3b, v125
	v_max3_f32 v82, v82, v141, v142
	s_waitcnt lgkmcnt(7)
	v_fmac_f32_e32 v145, 0x3e38aa3b, v126
	s_waitcnt lgkmcnt(5)
	v_fmac_f32_e32 v146, 0x3e38aa3b, v127
	v_max3_f32 v82, v82, v143, v144
	s_waitcnt lgkmcnt(3)
	v_fmac_f32_e32 v147, 0x3e38aa3b, v128
	s_waitcnt lgkmcnt(1)
	v_fmac_f32_e32 v148, 0x3e38aa3b, v129
	v_max3_f32 v82, v82, v145, v146
	v_max3_f32 v84, v82, v147, v148
	v_pk_fma_f32 v[82:83], v[98:99], s[48:49], v[66:67] op_sel_hi:[1,0,1]
	v_pk_fma_f32 v[86:87], v[102:103], s[48:49], v[70:71] op_sel_hi:[1,0,1]
	v_max3_f32 v66, v84, v82, v83
	v_pk_fma_f32 v[84:85], v[100:101], s[48:49], v[68:69] op_sel_hi:[1,0,1]
	v_pk_fma_f32 v[88:89], v[104:105], s[48:49], v[72:73] op_sel_hi:[1,0,1]
	v_max3_f32 v66, v66, v84, v85
	v_max3_f32 v66, v66, v86, v87
	v_max3_f32 v66, v66, v88, v89
	v_pk_fma_f32 v[90:91], v[106:107], s[48:49], v[74:75] op_sel_hi:[1,0,1]
	v_pk_fma_f32 v[92:93], v[108:109], s[48:49], v[76:77] op_sel_hi:[1,0,1]
	v_max3_f32 v66, v66, v90, v91
	v_max3_f32 v66, v66, v92, v93
	v_pk_fma_f32 v[94:95], v[110:111], s[48:49], v[78:79] op_sel_hi:[1,0,1]
	s_waitcnt lgkmcnt(0)
	v_pk_fma_f32 v[96:97], v[112:113], s[48:49], v[80:81] op_sel_hi:[1,0,1]
	v_max3_f32 v66, v66, v94, v95
	v_max3_f32 v66, v66, v96, v97
	v_mov_b32_e32 v67, v66
	s_nop 1
	v_permlane32_swap_b32_e32 v66, v67
	v_max_f32_e32 v67, v67, v67
	v_max_f32_e32 v66, v66, v66
	v_max_f32_e32 v66, v66, v67
	v_sub_f32_e32 v67, v66, v219
	v_cmp_ge_f32_e32 vcc, s94, v67
	v_max_f32_e32 v67, v219, v219
	v_max_f32_e32 v66, v67, v66
	v_sub_f32_e32 v67, v219, v66
	v_exp_f32_e32 v67, v67
	s_cmp_eq_u64 vcc, exec
	s_cselect_b64 vcc, -1, 0
	v_cndmask_b32_e32 v149, v66, v219, vcc
	v_cndmask_b32_e64 v132, v67, 1.0, vcc
	v_sub_f32_e32 v66, v133, v149
	v_sub_f32_e32 v67, v134, v149
	v_sub_f32_e32 v68, v135, v149
	v_sub_f32_e32 v69, v136, v149
	v_sub_f32_e32 v70, v137, v149
	v_sub_f32_e32 v71, v138, v149
	v_sub_f32_e32 v72, v139, v149
	v_sub_f32_e32 v73, v140, v149
	v_sub_f32_e32 v74, v141, v149
	v_sub_f32_e32 v75, v142, v149
	v_sub_f32_e32 v76, v143, v149
	v_sub_f32_e32 v77, v144, v149
	v_sub_f32_e32 v78, v145, v149
	v_sub_f32_e32 v79, v146, v149
	v_sub_f32_e32 v80, v147, v149
	v_sub_f32_e32 v81, v148, v149
	v_exp_f32_e32 v66, v66
	v_exp_f32_e32 v67, v67
	v_exp_f32_e32 v68, v68
	v_exp_f32_e32 v69, v69
	v_exp_f32_e32 v70, v70
	v_exp_f32_e32 v71, v71
	v_exp_f32_e32 v72, v72
	v_exp_f32_e32 v73, v73
	v_exp_f32_e32 v74, v74
	v_exp_f32_e32 v75, v75
	v_exp_f32_e32 v76, v76
	v_exp_f32_e32 v77, v77
	v_exp_f32_e32 v78, v78
	v_exp_f32_e32 v79, v79
	v_exp_f32_e32 v80, v80
	v_exp_f32_e32 v81, v81
	v_sub_f32_e32 v97, v97, v149
	v_sub_f32_e32 v96, v96, v149
	v_sub_f32_e32 v95, v95, v149
	v_sub_f32_e32 v94, v94, v149
	v_sub_f32_e32 v93, v93, v149
	v_sub_f32_e32 v92, v92, v149
	v_sub_f32_e32 v91, v91, v149
	v_sub_f32_e32 v90, v90, v149
	v_sub_f32_e32 v89, v89, v149
	v_sub_f32_e32 v88, v88, v149
	v_sub_f32_e32 v87, v87, v149
	v_sub_f32_e32 v86, v86, v149
	v_sub_f32_e32 v85, v85, v149
	v_sub_f32_e32 v84, v84, v149
	v_sub_f32_e32 v83, v83, v149
	v_sub_f32_e32 v82, v82, v149
	s_xor_b64 s[70:71], exec, -1

; __device__ __forceinline__ int v_st(int k, int c) { const int kk = (k & ~0xC) | ((k & 4) << 1) | ((k & 8) >> 1); return ((kk >> 3) * 4 + (c >> 5)) * 512 + ((kk & 7) * 32 + (c & 31)) * 2; }
; __device__ __forceinline__ int v_rd_base(int lane) { return ((lane & 3) << 3) | (((lane >> 2) & 3) << 6) | (((lane >> 4) & 1) << 5) | (((lane >> 5) & 1) << 8); }
; #define SLOAD(i, k0) do { sr_[i].vs0 = *reinterpret_cast<const bf16x8*>(&Vh[(size_t)((k0) + sr) * LDQK + sc]); sr_[i].vs1 = *reinterpret_cast<const bf16x8*>(&Vh[(size_t)((k0) + 32 + sr) * LDQK + sc]); \
;     sr_[i].ks0 = *reinterpret_cast<const bf16x8*>(&Kh[(size_t)((k0) + sr) * LDQK + sc]); sr_[i].ks1 = *reinterpret_cast<const bf16x8*>(&Kh[(size_t)((k0) + 32 + sr) * LDQK + sc]); } while (0)
; #define SWAIT() asm volatile("s_waitcnt vmcnt(4)" ::: "memory")
; #define PSM(P0, P1, MN, AL, J) partialSM<MODE>(P0, P1, m_reg, MN, AL, relq + 64 * (J), relwmin + 64 * (J), relwmax + 64 * (J), lut)
; template <int MODE>
; __device__ __forceinline__ void partialSM(f32x16& p0, f32x16& p1, float& m_reg, float& mn, float& alpha, int relh, int relw_min, int relw_max, const float* lut) {
;     ...
;       if (relw_max <= -128) { nearT = false; cfar = lut[0]; }
;       else if (relw_min >= 128) { nearT = false; cfar = lut[258]; }
; template <int MODE>
; __device__ __forceinline__ void attn_body(const bf16_t* __restrict__ Qb, const bf16_t* __restrict__ Kh, const bf16_t* __restrict__ Vh, int NT, int krel0,
;                                           char* lds, const float* __restrict__ lutg, const AttnEpi& E) {
;     ...
;   const int sr = tid >> 4, sc = (tid & 15) * 8, vst0 = v_st(sr, sc), vst1 = v_st(32 + sr, sc);
;   const int vb0 = (int)(uintptr_t)V_lds + v_rd_base(lane);
;   struct { bf16x8 vs0, vs1, ks0, ks1; } sr_[2];
;     ...
;   const int relq = krel0 - (wid * 32 + r32) + 4 * hi, relwmin = krel0 - (wid * 32 + 31), relwmax = krel0 + 63 - wid * 32;
;     ...
;   f32x16 pA0, pA1, pB0, pB1; float mnA, mnB, alA, alB; bf16x8 pa0, pa1, pa2, pa3;
;   constexpr int SE = 0, SO = 1;
;   SLOAD(SE, 0); SLOAD(SO, 64); asm volatile("s_waitcnt vmcnt(4)" ::: "memory"); SWRITE(0, SE); __syncthreads();
;   qkt<ND0, DOFF>(pA0, pA1, K_lds, qr, r32, hi); PSM(pA0, pA1, mnA, alA, 0);
;   if (2 < NT) SLOAD(SE, 2 * 64);
;   SWAIT(); SWRITE(SHM_V, SO);
;   int op = 0, oq = SHM_V, ow = 2 * SHM_V;
;   for (int j = 1; j + 1 < NT; j += 2) {
;     __syncthreads();
.LBB0_176:
	s_or_b64 exec, exec, s[60:61]
	v_add_u32_e32 v0, 0xa0, v50
	s_movk_i32 s60, 0x1200
	s_nop 3
	v_mad_i64_i32 v[2:3], s[6:7], v0, s60, 0
	v_add_u32_e32 v0, 0x80, v50
	v_or_b32_e32 v2, v2, v51
	v_mad_i64_i32 v[6:7], s[6:7], v0, s60, 0
	v_lshlrev_b64 v[2:3], 1, v[2:3]
	v_or_b32_e32 v6, v6, v51
	v_lshl_add_u64 v[4:5], s[58:59], 0, v[2:3]
	v_lshlrev_b64 v[6:7], 1, v[6:7]
	v_lshl_add_u64 v[2:3], s[0:1], 0, v[2:3]
	v_lshl_add_u64 v[8:9], s[58:59], 0, v[6:7]
	global_load_dwordx4 v[150:153], v[4:5], off
	global_load_dwordx4 v[146:149], v[8:9], off
	v_lshl_add_u64 v[4:5], s[0:1], 0, v[6:7]
	global_load_dwordx4 v[158:161], v[2:3], off
	global_load_dwordx4 v[154:157], v[4:5], off
	v_and_b32_e32 v0, 63, v188
	v_lshlrev_b32_e32 v3, 4, v0
	v_lshlrev_b32_e32 v2, 3, v0
	v_and_b32_e32 v3, 0xc0, v3
	v_lshlrev_b32_e32 v4, 1, v0
	v_and_or_b32 v3, v2, 24, v3
	v_and_b32_e32 v4, 32, v4
	v_and_b32_e32 v2, 0x100, v2
	s_cmp_lg_u32 0, -1
	v_or3_b32 v2, v3, v4, v2
	s_cselect_b32 s0, 0, 0
	v_add_u32_e32 v221, s0, v2
	v_and_b32_e32 v2, 0x3fffffc0, v188
	v_add_u32_e32 v3, s75, v214
	v_ashrrev_i32_e32 v51, 31, v50
	v_lshl_add_u32 v2, v2, 2, s89
	s_waitcnt vmcnt(4)
	s_waitcnt vmcnt(7)
	ds_write_b128 v53, v[34:37] offset:16384
	s_waitcnt vmcnt(5)
	ds_write_b128 v54, v[38:41] offset:16384
	ds_write_b128 v3, v[42:45]
	v_add_u32_e32 v3, s75, v215
	s_waitcnt vmcnt(4)
	ds_write_b128 v3, v[46:49]
	v_cmp_gt_u32_e64 s[6:7], 32, v0
	v_lshl_add_u32 v212, v184, 2, v2
	v_lshl_add_u32 v210, v205, 2, v2
	v_sub_u32_e32 v0, v205, v184
	v_lshl_add_u64 v[2:3], v[50:51], 0, s[2:3]
	s_movk_i32 s2, 0x2400
	v_sub_u32_e32 v225, v0, v204
	v_mad_u64_u32 v[4:5], s[0:1], v2, s2, 0
	v_and_b32_e32 v0, 15, v188
	v_mad_i32_i24 v3, v3, s2, v5
	v_or_b32_e32 v2, s74, v4
	v_lshlrev_b32_e32 v0, 4, v0
	v_readlane_b32 s0, v254, 14
	v_lshl_add_u64 v[2:3], v[2:3], 0, v[0:1]
	v_readlane_b32 s1, v254, 15
	v_mov_b32_e32 v14, v1
	v_mov_b32_e32 v15, v1
	v_sub_u32_e32 v223, 0, v52
	v_lshl_add_u64 v[190:191], s[0:1], 0, v[2:3]
	v_mov_b32_e32 v0, v1
	v_mov_b32_e32 v2, v1
	v_mov_b32_e32 v3, v1
	v_mov_b32_e32 v4, v1
	v_mov_b32_e32 v5, v1
	v_mov_b32_e32 v6, v1
	v_mov_b32_e32 v7, v1
	v_mov_b32_e32 v8, v1
	v_mov_b32_e32 v9, v1
	v_mov_b32_e32 v10, v1
	v_mov_b32_e32 v11, v1
	v_mov_b32_e32 v12, v1
	v_mov_b32_e32 v13, v1
	v_mov_b64_e32 v[64:65], v[14:15]
	v_mov_b64_e32 v[48:49], v[14:15]
	v_mov_b64_e32 v[32:33], v[14:15]
	v_mov_b64_e32 v[62:63], v[12:13]
	v_mov_b64_e32 v[60:61], v[10:11]
	v_mov_b64_e32 v[58:59], v[8:9]
	v_mov_b64_e32 v[56:57], v[6:7]
	v_mov_b64_e32 v[54:55], v[4:5]
	v_mov_b64_e32 v[52:53], v[2:3]
	v_mov_b64_e32 v[50:51], v[0:1]
	v_mov_b64_e32 v[46:47], v[12:13]
	v_mov_b64_e32 v[44:45], v[10:11]
	v_mov_b64_e32 v[42:43], v[8:9]
	v_mov_b64_e32 v[40:41], v[6:7]
	v_mov_b64_e32 v[38:39], v[4:5]
	v_mov_b64_e32 v[36:37], v[2:3]
	v_mov_b64_e32 v[34:35], v[0:1]
	v_mov_b64_e32 v[30:31], v[12:13]
	v_mov_b64_e32 v[28:29], v[10:11]
	v_mov_b64_e32 v[26:27], v[8:9]
	v_mov_b64_e32 v[24:25], v[6:7]
	v_mov_b64_e32 v[22:23], v[4:5]
	v_mov_b64_e32 v[20:21], v[2:3]
	v_mov_b64_e32 v[18:19], v[0:1]
	v_mov_b64_e32 v[16:17], v[14:15]
	s_mov_b32 s66, 0
	s_mov_b32 s67, 2
	v_sub_u32_e32 v224, 0, v204
	v_mov_b32_e32 v213, 0
	s_movk_i32 s68, 0x4000
	s_mov_b32 s0, 0x8000
	v_mov_b64_e32 v[14:15], v[12:13]
	v_mov_b64_e32 v[12:13], v[10:11]
	v_mov_b64_e32 v[10:11], v[8:9]
	v_mov_b64_e32 v[8:9], v[6:7]
	v_mov_b64_e32 v[6:7], v[4:5]
	v_mov_b64_e32 v[4:5], v[2:3]
	v_mov_b64_e32 v[2:3], v[0:1]
	s_waitcnt vmcnt(0)
	v_readfirstlane_b32 s31, v179
	s_nop 3
	s_lshr_b32 s31, s31, 6
	s_lshl_b32 s30, s31, 11
	v_and_b32_e32 v150, 63, v179
	v_bfe_u32 v151, v150, 2, 3
	s_lshl_b32 s29, s31, 3
	v_or_b32_e32 v151, s29, v151
	v_and_b32_e32 v152, 4, v151
	v_lshlrev_b32_e32 v152, 1, v152
	v_and_b32_e32 v153, 8, v151
	v_lshrrev_b32_e32 v153, 1, v153
	v_and_b32_e32 v151, 0xfffffff3, v151
	v_or3_b32 v151, v151, v152, v153
	v_mul_u32_u24_e32 v151, 0x2400, v151
	v_lshrrev_b32_e32 v152, 5, v150
	v_lshlrev_b32_e32 v152, 6, v152
	v_and_b32_e32 v153, 3, v150
	v_lshlrev_b32_e32 v153, 4, v153
	v_add3_u32 v248, v151, v152, v153
	v_add_u32_e32 v249, 0x80, v248
	v_lshrrev_b32_e32 v151, 4, v150
	v_add_u32_e32 v151, s29, v151
	v_and_b32_e32 v152, 15, v150
	v_and_b32_e32 v153, 15, v151
	v_xor_b32_e32 v153, v152, v153
	v_mul_u32_u24_e32 v154, 0x2400, v151
	v_lshl_add_u32 v250, v153, 4, v154
	v_add_u32_e32 v151, 4, v151
	v_and_b32_e32 v153, 15, v151
	v_xor_b32_e32 v153, v152, v153
	v_mul_u32_u24_e32 v154, 0x2400, v151
	v_lshl_add_u32 v251, v153, 4, v154
	v_readfirstlane_b32 s26, v190
	v_readfirstlane_b32 s27, v191
	s_mul_i32 s29, s31, 0x9000
	s_add_u32 s29, s29, 0x168000
	s_sub_u32 s26, s26, s29
	s_subb_u32 s27, s27, 0
	s_sub_u32 s28, s26, 0x200
	s_subb_u32 s29, s27, 0
	s_add_i32 m0, s0, s30
	s_add_i32 m0, m0, 0xc000
	s_nop 0
	global_load_lds_dwordx4 v250, s[28:29]
	s_add_i32 m0, m0, 0x400
	s_nop 0
	global_load_lds_dwordx4 v251, s[28:29]
	s_add_u32 s28, s28, 0x90000
	s_addc_u32 s29, s29, 0
	s_waitcnt lgkmcnt(0)
	s_barrier
	v_mov_b32_e32 v160, s76
	ds_read_b32 v160, v160
	v_mov_b32_e32 v161, s41
	ds_read_b32 v161, v161
	s_waitcnt lgkmcnt(0)
.LBB0_177:
	v_readfirstlane_b32 s20, v224
	v_readfirstlane_b32 s21, v223
	s_nop 3
	s_add_i32 s22, s20, s77
	s_addk_i32 s22, 0x7f
	s_add_i32 s23, s21, s77
	s_addk_i32 s23, 0x40
	s_add_i32 s24, s22, 64
	s_add_i32 s25, s23, 64
	s_mov_b32 s2, s0
	s_cmp_lt_u32 s31, 4
	s_cbranch_scc0 .Ldp_12
	s_waitcnt vmcnt(0) lgkmcnt(0)
	s_barrier
; #define SBAR() __builtin_amdgcn_sched_barrier(0)
; __device__ __forceinline__ void finishSM(f32x16& p0, f32x16& p1, float alpha, float& l_reg, bf16x8& pa0, bf16x8& pa1, bf16x8& pa2, bf16x8& pa3) {
; #pragma unroll
;   for (int r = 0; r < 16; ++r) p1[r] = __builtin_amdgcn_exp2f(p1[r]);
;   float ps = 0;
; #pragma unroll
;   for (int r = 0; r < 16; ++r) ps += p0[r];
; #pragma unroll
;   for (int r = 0; r < 16; ++r) ps += p1[r];
;   { auto rr = __builtin_amdgcn_permlane32_swap(__float_as_uint(ps), __float_as_uint(ps), false, false);
;     ps = __uint_as_float(rr[0]) + __uint_as_float(rr[1]); }
;   l_reg = l_reg * alpha + ps;
;     ...
;   PK4(p0, 0, pa0); PK4(p0, 8, pa1); PK4(p1, 0, pa2); PK4(p1, 8, pa3);
;     ...
; }
; template <int ND0, int DOFF>
; __device__ __forceinline__ void qkt(f32x16& p0, f32x16& p1, const char* Ks, const bf16x8* qr, int r32, int hi) {
;   p0 = f32x16{}; p1 = f32x16{};
; #pragma unroll
;   for (int d0 = 0; d0 < ND0; ++d0) { const int cb = ((d0 + DOFF) * 16 + hi * 8) * 2;
;     bf16x8 b0 = *reinterpret_cast<const bf16x8*>(Ks + KSWZ(r32, cb));
;     bf16x8 b1 = *reinterpret_cast<const bf16x8*>(Ks + KSWZ(32 + r32, cb));
;     p0 = __builtin_amdgcn_mfma_f32_32x32x16_bf16(b0, qr[d0], p0, 0, 0, 0);
;     p1 = __builtin_amdgcn_mfma_f32_32x32x16_bf16(b1, qr[d0], p1, 0, 0, 0); }
; }
; __device__ __forceinline__ int v_st(int k, int c) { const int kk = (k & ~0xC) | ((k & 4) << 1) | ((k & 8) >> 1); return ((kk >> 3) * 4 + (c >> 5)) * 512 + ((kk & 7) * 32 + (c & 31)) * 2; }
; __device__ __forceinline__ int v_rd_base(int lane) { return ((lane & 3) << 3) | (((lane >> 2) & 3) << 6) | (((lane >> 4) & 1) << 5) | (((lane >> 5) & 1) << 8); }
; template <int OFF> __device__ __forceinline__ s16x4 tr_read(int vb) {
;   s16x4 r; asm volatile("ds_read_b64_tr_b16 %0, %1 offset:%2" : "=&v"(r) : "v"(vb), "i"(OFF) : "memory"); return r;
; }
; template <int D0> __device__ __forceinline__ void pv_one(f32x16& od, int vb, bf16x8 pa0, bf16x8 pa1, bf16x8 pa2, bf16x8 pa3) {
;   const s16x4 l0 = tr_read<v_rd_off(D0, 0, 0)>(vb), h0 = tr_read<v_rd_off(D0, 0, 1)>(vb), l1 = tr_read<v_rd_off(D0, 1, 0)>(vb), h1 = tr_read<v_rd_off(D0, 1, 1)>(vb);
;   const s16x4 l2 = tr_read<v_rd_off(D0, 2, 0)>(vb), h2 = tr_read<v_rd_off(D0, 2, 1)>(vb), l3 = tr_read<v_rd_off(D0, 3, 0)>(vb), h3 = tr_read<v_rd_off(D0, 3, 1)>(vb);
;   asm volatile("s_waitcnt lgkmcnt(0)" ::: "memory"); SBAR();
.Ldp_12:
	s_add_i32 s0, s68, 0
	v_add_u32_e32 v0, s0, v216
	ds_read_b128 v[98:101], v0 offset:49152
	ds_read_b128 v[102:105], v0 offset:57344
	v_add_u32_e32 v0, s0, v217
	ds_read_b128 v[162:165], v0 offset:49152
	ds_read_b128 v[166:169], v0 offset:57344
	v_add_u32_e32 v0, s0, v218
	s_waitcnt lgkmcnt(3)
	v_mfma_f32_32x32x16_bf16 v[114:129], v[98:101], v[142:145], 0
	s_waitcnt lgkmcnt(2)
	v_mfma_f32_32x32x16_bf16 v[98:113], v[102:105], v[142:145], 0
	s_waitcnt lgkmcnt(1)
	v_mfma_f32_32x32x16_bf16 v[114:129], v[162:165], v[138:141], v[114:129]
	s_waitcnt lgkmcnt(0)
	v_mfma_f32_32x32x16_bf16 v[98:113], v[166:169], v[138:141], v[98:113]
	ds_read_b128 v[162:165], v0 offset:49152
	ds_read_b128 v[166:169], v0 offset:57344
	v_add_u32_e32 v0, s0, v219
	s_waitcnt lgkmcnt(1)
	v_mfma_f32_32x32x16_bf16 v[114:129], v[162:165], v[134:137], v[114:129]
	s_waitcnt lgkmcnt(0)
	v_mfma_f32_32x32x16_bf16 v[98:113], v[166:169], v[134:137], v[98:113]
	ds_read_b128 v[162:165], v0 offset:49152
	ds_read_b128 v[166:169], v0 offset:57344
	v_exp_f32_e32 v0, v82
	v_exp_f32_e32 v82, v83
	v_exp_f32_e32 v83, v84
	v_exp_f32_e32 v84, v85
	v_exp_f32_e32 v85, v86
	v_exp_f32_e32 v86, v87
	v_exp_f32_e32 v87, v88
	v_exp_f32_e32 v88, v89
	v_exp_f32_e32 v89, v90
	v_exp_f32_e32 v90, v91
	v_exp_f32_e32 v91, v92
	v_exp_f32_e32 v92, v93
	v_exp_f32_e32 v93, v94
	v_exp_f32_e32 v94, v95
	v_exp_f32_e32 v95, v96
	v_exp_f32_e32 v96, v97
	v_add_f32_e32 v97, v67, v66
	v_add_f32_e32 v97, v68, v97
	v_add_f32_e32 v97, v69, v97
	v_add_f32_e32 v97, v70, v97
	v_add_f32_e32 v97, v71, v97
	v_add_f32_e32 v97, v72, v97
	v_add_f32_e32 v97, v73, v97
	v_add_f32_e32 v97, v74, v97
	v_add_f32_e32 v97, v75, v97
	v_add_f32_e32 v97, v76, v97
	v_add_f32_e32 v97, v77, v97
	v_add_f32_e32 v97, v78, v97
	v_add_f32_e32 v97, v79, v97
	v_add_f32_e32 v97, v80, v97
	v_add_f32_e32 v97, v81, v97
	v_add_f32_e32 v97, v0, v97
	v_add_f32_e32 v97, v82, v97
	v_add_f32_e32 v97, v83, v97
	v_add_f32_e32 v97, v84, v97
	v_add_f32_e32 v97, v85, v97
	v_add_f32_e32 v97, v86, v97
	v_add_f32_e32 v97, v87, v97
	v_add_f32_e32 v97, v88, v97
	v_add_f32_e32 v97, v89, v97
	v_add_f32_e32 v97, v90, v97
	s_waitcnt lgkmcnt(1)
	v_mfma_f32_32x32x16_bf16 v[114:129], v[162:165], v[130:133], v[114:129]
	v_add_f32_e32 v97, v91, v97
	v_add_f32_e32 v97, v92, v97
	v_add_f32_e32 v97, v93, v97
	v_add_f32_e32 v97, v94, v97
	v_add_f32_e32 v97, v95, v97
	v_add_f32_e32 v226, v96, v97
	v_mov_b32_e32 v227, v226
	s_waitcnt lgkmcnt(0)
	v_mfma_f32_32x32x16_bf16 v[98:113], v[166:169], v[130:133], v[98:113]
	v_cvt_pk_bf16_f32 v66, v66, v67
	v_cvt_pk_bf16_f32 v67, v68, v69
	v_cvt_pk_bf16_f32 v68, v70, v71
	v_cvt_pk_bf16_f32 v69, v72, v73
	v_cvt_pk_bf16_f32 v70, v74, v75
	v_cvt_pk_bf16_f32 v71, v76, v77
	v_cvt_pk_bf16_f32 v72, v78, v79
	v_cvt_pk_bf16_f32 v73, v80, v81
	v_cvt_pk_bf16_f32 v74, v0, v82
	v_cvt_pk_bf16_f32 v75, v83, v84
	v_cvt_pk_bf16_f32 v76, v85, v86
	v_cvt_pk_bf16_f32 v77, v87, v88
	v_cvt_pk_bf16_f32 v78, v89, v90
	v_cvt_pk_bf16_f32 v79, v91, v92
	v_cvt_pk_bf16_f32 v80, v93, v94
	v_cvt_pk_bf16_f32 v81, v95, v96
	v_permlane32_swap_b32_e32 v226, v227
	v_permlane32_swap_b32_e32 v66, v68
	v_permlane32_swap_b32_e32 v67, v69
	v_permlane32_swap_b32_e32 v70, v72
	v_permlane32_swap_b32_e32 v71, v73
	v_permlane32_swap_b32_e32 v74, v76
	v_permlane32_swap_b32_e32 v75, v77
	v_permlane32_swap_b32_e32 v78, v80
	v_permlane32_swap_b32_e32 v79, v81
	s_cmp_lt_u32 s31, 4
	s_cbranch_scc1 .Ldp_11
	s_waitcnt vmcnt(0) lgkmcnt(0)
	s_barrier
.Ldp_11:
	s_add_i32 m0, s2, s30
	s_nop 0
	global_load_lds_dwordx4 v248, s[26:27]
	s_add_i32 m0, m0, 0x400
	s_nop 0
	global_load_lds_dwordx4 v249, s[26:27]
	s_add_i32 m0, s66, s30
	s_add_i32 m0, m0, 0xc000
	s_nop 0
	global_load_lds_dwordx4 v250, s[28:29]
	s_add_i32 m0, m0, 0x400
	s_nop 0
	global_load_lds_dwordx4 v251, s[28:29]
	s_add_u32 s26, s26, 0x90000
	s_addc_u32 s27, s27, 0
	s_add_u32 s28, s28, 0x90000
	s_addc_u32 s29, s29, 0
	v_add_u32_e32 v0, s66, v221
	ds_read_b64_tr_b16 v[82:83], v0 offset:0
	ds_read_b64_tr_b16 v[84:85], v0 offset:0x800
	ds_read_b64_tr_b16 v[86:87], v0 offset:0x1000
	ds_read_b64_tr_b16 v[88:89], v0 offset:0x1800
	ds_read_b64_tr_b16 v[90:91], v0 offset:0x2000
	ds_read_b64_tr_b16 v[92:93], v0 offset:0x2800
	ds_read_b64_tr_b16 v[94:95], v0 offset:0x3000
	ds_read_b64_tr_b16 v[96:97], v0 offset:0x3800
	s_waitcnt lgkmcnt(0)
	s_nop 0
	v_mfma_f32_32x32x16_bf16 v[50:65], v[66:69], v[82:85], v[50:65]
	ds_read_b64_tr_b16 v[82:83], v0 offset:0x200
	ds_read_b64_tr_b16 v[84:85], v0 offset:0xa00
	v_mfma_f32_32x32x16_bf16 v[50:65], v[70:73], v[86:89], v[50:65]
	ds_read_b64_tr_b16 v[86:87], v0 offset:0x1200
	ds_read_b64_tr_b16 v[88:89], v0 offset:0x1a00
	v_mfma_f32_32x32x16_bf16 v[50:65], v[74:77], v[90:93], v[50:65]
	ds_read_b64_tr_b16 v[90:91], v0 offset:0x2200
	ds_read_b64_tr_b16 v[92:93], v0 offset:0x2a00
	v_mfma_f32_32x32x16_bf16 v[50:65], v[78:81], v[94:97], v[50:65]
	ds_read_b64_tr_b16 v[94:95], v0 offset:0x3200
	ds_read_b64_tr_b16 v[96:97], v0 offset:0x3a00
	s_waitcnt lgkmcnt(0)
	v_mfma_f32_32x32x16_bf16 v[34:49], v[66:69], v[82:85], v[34:49]
	ds_read_b64_tr_b16 v[82:83], v0 offset:0x400
	ds_read_b64_tr_b16 v[84:85], v0 offset:0xc00
	v_mfma_f32_32x32x16_bf16 v[34:49], v[70:73], v[86:89], v[34:49]
	ds_read_b64_tr_b16 v[86:87], v0 offset:0x1400
	ds_read_b64_tr_b16 v[88:89], v0 offset:0x1c00
	v_mfma_f32_32x32x16_bf16 v[34:49], v[74:77], v[90:93], v[34:49]
	ds_read_b64_tr_b16 v[90:91], v0 offset:0x2400
	ds_read_b64_tr_b16 v[92:93], v0 offset:0x2c00
	v_mfma_f32_32x32x16_bf16 v[34:49], v[78:81], v[94:97], v[34:49]
	ds_read_b64_tr_b16 v[94:95], v0 offset:0x3400
	ds_read_b64_tr_b16 v[96:97], v0 offset:0x3c00
	s_waitcnt lgkmcnt(0)
	v_mfma_f32_32x32x16_bf16 v[18:33], v[66:69], v[82:85], v[18:33]
	ds_read_b64_tr_b16 v[82:83], v0 offset:0x600
	ds_read_b64_tr_b16 v[84:85], v0 offset:0xe00
	v_mfma_f32_32x32x16_bf16 v[18:33], v[70:73], v[86:89], v[18:33]
	ds_read_b64_tr_b16 v[86:87], v0 offset:0x1600
	ds_read_b64_tr_b16 v[88:89], v0 offset:0x1e00
	v_mfma_f32_32x32x16_bf16 v[18:33], v[74:77], v[90:93], v[18:33]
	ds_read_b64_tr_b16 v[90:91], v0 offset:0x2600
	ds_read_b64_tr_b16 v[92:93], v0 offset:0x2e00
	v_mfma_f32_32x32x16_bf16 v[18:33], v[78:81], v[94:97], v[18:33]
	ds_read_b64_tr_b16 v[94:95], v0 offset:0x3600
	ds_read_b64_tr_b16 v[96:97], v0 offset:0x3e00
	s_waitcnt lgkmcnt(0)
	v_mfma_f32_32x32x16_bf16 v[2:17], v[66:69], v[82:85], v[2:17]
	s_cmp_gt_i32 s95, s22
	s_cselect_b64 s[0:1], -1, 0
	s_cmp_lt_i32 s15, s22
	s_cselect_b64 vcc, -1, 0
	v_mov_b32_e32 v232, v160
	v_mfma_f32_32x32x16_bf16 v[2:17], v[70:73], v[86:89], v[2:17]
	v_mfma_f32_32x32x16_bf16 v[2:17], v[74:77], v[90:93], v[2:17]
	v_mfma_f32_32x32x16_bf16 v[2:17], v[78:81], v[94:97], v[2:17]
	s_and_saveexec_b64 s[58:59], vcc
	s_cbranch_execz .LBB0_181
; template <int MODE>
; __device__ __forceinline__ void partialSM(f32x16& p0, f32x16& p1, float& m_reg, float& mn, float& alpha, int relh, int relw_min, int relw_max, const float* lut) {
;     ...
;     if (nearT) {
; #pragma unroll
;       for (int r = 0; r < 16; ++r) { const int i0 = relh + (r & 3) + 8 * (r >> 2);
;         const int a0 = min(max(i0, -129), 129) + 129, a1 = min(max(i0 + 32, -129), 129) + 129;
;         p0[r] = fmaf(p0[r], C, lut[a0]); p1[r] = fmaf(p1[r], C, lut[a1]); }
;     } else {
; #pragma unroll
;       for (int r = 0; r < 16; ++r) { p0[r] = fmaf(p0[r], C, cfar); p1[r] = fmaf(p1[r], C, cfar); }
;     }
;     float pmax = p0[0];
; #pragma unroll
;     for (int r = 1; r < 16; ++r) pmax = fmaxf(pmax, p0[r]);
; #pragma unroll
;     for (int r = 0; r < 16; ++r) pmax = fmaxf(pmax, p1[r]);
	s_cmp_gt_i32 s91, s23
	s_cselect_b64 vcc, -1, 0
	s_mov_b64 s[62:63], -1
	s_and_saveexec_b64 s[60:61], vcc
	s_cbranch_execz .LBB0_180
	v_add_u32_e32 v230, s77, v225
	v_add_u32_e32 v66, 64, v230
	v_add_u32_e32 v68, 0x41, v230
	v_add_u32_e32 v70, 0x42, v230
	v_add_u32_e32 v72, 0x43, v230
	v_med3_i32 v67, v66, s39, v198
	v_med3_i32 v66, v66, s33, v199
	v_med3_i32 v69, v68, s39, v198
	v_med3_i32 v68, v68, s33, v199
	v_med3_i32 v71, v70, s39, v198
	v_med3_i32 v70, v70, s33, v199
	v_med3_i32 v73, v72, s39, v198
	v_med3_i32 v72, v72, s33, v199
	v_lshl_add_u32 v67, v67, 2, s76
	v_lshl_add_u32 v66, v66, 2, s76
	v_lshl_add_u32 v69, v69, 2, s76
	v_lshl_add_u32 v68, v68, 2, s76
	v_lshl_add_u32 v70, v70, 2, s76
	v_lshl_add_u32 v72, v72, 2, s76
	v_lshl_add_u32 v71, v71, 2, s76
	v_lshl_add_u32 v73, v73, 2, s76
	ds_read_b32 v194, v67 offset:516
	ds_read_b32 v66, v66 offset:644
	ds_read_b32 v195, v69 offset:516
	ds_read_b32 v67, v68 offset:644
	ds_read_b32 v232, v71 offset:516
	ds_read_b32 v68, v70 offset:644
	ds_read_b32 v233, v73 offset:516
	ds_read_b32 v69, v72 offset:644
	v_add_u32_e32 v70, 0x48, v230
	v_add_u32_e32 v72, 0x49, v230
	v_add_u32_e32 v74, 0x4a, v230
	v_add_u32_e32 v76, 0x4b, v230
	v_med3_i32 v71, v70, s39, v198
	v_med3_i32 v70, v70, s33, v199
	v_med3_i32 v73, v72, s39, v198
	v_med3_i32 v72, v72, s33, v199
	v_med3_i32 v75, v74, s39, v198
	v_med3_i32 v74, v74, s33, v199
	v_med3_i32 v77, v76, s39, v198
	v_med3_i32 v76, v76, s33, v199
	v_lshl_add_u32 v71, v71, 2, s76
	v_lshl_add_u32 v70, v70, 2, s76
	v_lshl_add_u32 v73, v73, 2, s76
	v_lshl_add_u32 v72, v72, 2, s76
	v_lshl_add_u32 v74, v74, 2, s76
	v_lshl_add_u32 v76, v76, 2, s76
	v_lshl_add_u32 v75, v75, 2, s76
	v_lshl_add_u32 v77, v77, 2, s76
	ds_read_b32 v234, v71 offset:516
	ds_read_b32 v70, v70 offset:644
	ds_read_b32 v235, v73 offset:516
	ds_read_b32 v71, v72 offset:644
	ds_read_b32 v236, v75 offset:516
	ds_read_b32 v72, v74 offset:644
	ds_read_b32 v237, v77 offset:516
	ds_read_b32 v73, v76 offset:644
	v_add_u32_e32 v74, 0x50, v230
	v_add_u32_e32 v76, 0x51, v230
	v_add_u32_e32 v78, 0x52, v230
	v_add_u32_e32 v80, 0x53, v230
	v_med3_i32 v75, v74, s39, v198
	v_med3_i32 v74, v74, s33, v199
	v_med3_i32 v77, v76, s39, v198
	v_med3_i32 v76, v76, s33, v199
	v_med3_i32 v79, v78, s39, v198
	v_med3_i32 v78, v78, s33, v199
	v_med3_i32 v81, v80, s39, v198
	v_med3_i32 v80, v80, s33, v199
	v_lshl_add_u32 v75, v75, 2, s76
	v_lshl_add_u32 v74, v74, 2, s76
	v_lshl_add_u32 v77, v77, 2, s76
	v_lshl_add_u32 v76, v76, 2, s76
	v_lshl_add_u32 v78, v78, 2, s76
	v_lshl_add_u32 v80, v80, 2, s76
	v_lshl_add_u32 v79, v79, 2, s76
	v_lshl_add_u32 v81, v81, 2, s76
	ds_read_b32 v238, v75 offset:516
	ds_read_b32 v74, v74 offset:644
	ds_read_b32 v239, v77 offset:516
	ds_read_b32 v75, v76 offset:644
	ds_read_b32 v240, v79 offset:516
	ds_read_b32 v76, v78 offset:644
	ds_read_b32 v241, v81 offset:516
	ds_read_b32 v77, v80 offset:644
	v_add_u32_e32 v78, 0x58, v230
	v_add_u32_e32 v80, 0x59, v230
	v_add_u32_e32 v82, 0x5a, v230
	v_med3_i32 v79, v78, s39, v198
	v_med3_i32 v78, v78, s33, v199
	v_med3_i32 v81, v80, s39, v198
	v_med3_i32 v80, v80, s33, v199
	v_med3_i32 v83, v82, s39, v198
	v_med3_i32 v82, v82, s33, v199
	v_add_u32_e32 v84, 0x5b, v230
	s_waitcnt lgkmcnt(14)
	v_fmac_f32_e32 v194, 0x3e38aa3b, v114
	v_fmac_f32_e32 v195, 0x3e38aa3b, v115
	v_lshl_add_u32 v79, v79, 2, s76
	v_lshl_add_u32 v78, v78, 2, s76
	v_lshl_add_u32 v81, v81, 2, s76
	v_lshl_add_u32 v80, v80, 2, s76
	v_lshl_add_u32 v82, v82, 2, s76
	v_med3_i32 v85, v84, s39, v198
	v_med3_i32 v84, v84, s33, v199
	v_fmac_f32_e32 v232, 0x3e38aa3b, v116
	v_fmac_f32_e32 v233, 0x3e38aa3b, v117
	v_lshl_add_u32 v83, v83, 2, s76
	v_lshl_add_u32 v85, v85, 2, s76
	v_lshl_add_u32 v84, v84, 2, s76
	ds_read_b32 v242, v79 offset:516
	ds_read_b32 v78, v78 offset:644
	ds_read_b32 v243, v81 offset:516
	ds_read_b32 v79, v80 offset:644
	ds_read_b32 v244, v83 offset:516
	ds_read_b32 v80, v82 offset:644
	ds_read_b32 v245, v85 offset:516
	ds_read_b32 v81, v84 offset:644
	v_max_f32_e32 v82, v194, v195
	v_fmac_f32_e32 v234, 0x3e38aa3b, v118
	s_waitcnt lgkmcnt(14)
	v_fmac_f32_e32 v235, 0x3e38aa3b, v119
	v_max3_f32 v82, v82, v232, v233
	v_fmac_f32_e32 v236, 0x3e38aa3b, v120
	v_fmac_f32_e32 v237, 0x3e38aa3b, v121
	v_max3_f32 v82, v82, v234, v235
	v_fmac_f32_e32 v238, 0x3e38aa3b, v122
	s_waitcnt lgkmcnt(13)
	v_fmac_f32_e32 v239, 0x3e38aa3b, v123
	v_max3_f32 v82, v82, v236, v237
	s_waitcnt lgkmcnt(11)
	v_fmac_f32_e32 v240, 0x3e38aa3b, v124
	s_waitcnt lgkmcnt(9)
	v_fmac_f32_e32 v241, 0x3e38aa3b, v125
	v_max3_f32 v82, v82, v238, v239
	s_waitcnt lgkmcnt(7)
	v_fmac_f32_e32 v242, 0x3e38aa3b, v126
	s_waitcnt lgkmcnt(5)
	v_fmac_f32_e32 v243, 0x3e38aa3b, v127
	v_max3_f32 v82, v82, v240, v241
	s_waitcnt lgkmcnt(3)
	v_fmac_f32_e32 v244, 0x3e38aa3b, v128
	s_waitcnt lgkmcnt(1)
; template <int MODE>
; __device__ __forceinline__ void partialSM(f32x16& p0, f32x16& p1, float& m_reg, float& mn, float& alpha, int relh, int relw_min, int relw_max, const float* lut) {
;     ...
;       if (!nearT) {
;         float pmax = p0[0];
; #pragma unroll
;         for (int r = 1; r < 16; ++r) pmax = fmaxf(pmax, p0[r]);
; #pragma unroll
;         for (int r = 0; r < 16; ++r) pmax = fmaxf(pmax, p1[r]);
;         { auto rr = __builtin_amdgcn_permlane32_swap(__float_as_uint(pmax), __float_as_uint(pmax), false, false);
;           pmax = fmaxf(__uint_as_float(rr[0]), __uint_as_float(rr[1])); }
;         const float tmax = fmaf(pmax, C, cfar);
;         if (__builtin_expect(__all(tmax - m_reg <= THR2), 1)) { mn = m_reg; alpha = 1.f; }
;         else { mn = fmaxf(m_reg, tmax); alpha = __builtin_amdgcn_exp2f(m_reg - mn); m_reg = mn; }
;         const float off = cfar - mn;
; #pragma unroll
;         for (int r = 0; r < 16; ++r) p0[r] = fmaf(p0[r], C, off);
; #pragma unroll
;         for (int r = 0; r < 16; ++r) p1[r] = fmaf(p1[r], C, off);
; #pragma unroll
;         for (int r = 0; r < 16; ++r) p0[r] = __builtin_amdgcn_exp2f(p0[r]);
;     ...
;     { auto rr = __builtin_amdgcn_permlane32_swap(__float_as_uint(pmax), __float_as_uint(pmax), false, false);
;       pmax = fmaxf(__uint_as_float(rr[0]), __uint_as_float(rr[1])); }
;     if (__builtin_expect(__all(pmax - m_reg <= THR2), 1)) { mn = m_reg; alpha = 1.f; }
;     else { mn = fmaxf(m_reg, pmax); alpha = __builtin_amdgcn_exp2f(m_reg - mn); m_reg = mn; }
; #pragma unroll
;     for (int r = 0; r < 16; ++r) p0[r] = __builtin_amdgcn_exp2f(p0[r] - mn);
; #pragma unroll
;     for (int r = 0; r < 16; ++r) p1[r] = p1[r] - mn;
	v_fmac_f32_e32 v245, 0x3e38aa3b, v129
	v_max3_f32 v82, v82, v242, v243
	v_max3_f32 v84, v82, v244, v245
	v_pk_fma_f32 v[82:83], v[98:99], s[48:49], v[66:67] op_sel_hi:[1,0,1]
	v_pk_fma_f32 v[86:87], v[102:103], s[48:49], v[70:71] op_sel_hi:[1,0,1]
	v_max3_f32 v66, v84, v82, v83
	v_pk_fma_f32 v[84:85], v[100:101], s[48:49], v[68:69] op_sel_hi:[1,0,1]
	v_pk_fma_f32 v[88:89], v[104:105], s[48:49], v[72:73] op_sel_hi:[1,0,1]
	v_max3_f32 v66, v66, v84, v85
	v_max3_f32 v66, v66, v86, v87
	v_max3_f32 v66, v66, v88, v89
	v_pk_fma_f32 v[90:91], v[106:107], s[48:49], v[74:75] op_sel_hi:[1,0,1]
	v_pk_fma_f32 v[92:93], v[108:109], s[48:49], v[76:77] op_sel_hi:[1,0,1]
	v_max3_f32 v66, v66, v90, v91
	v_max3_f32 v66, v66, v92, v93
	v_pk_fma_f32 v[94:95], v[110:111], s[48:49], v[78:79] op_sel_hi:[1,0,1]
	s_waitcnt lgkmcnt(0)
	v_pk_fma_f32 v[96:97], v[112:113], s[48:49], v[80:81] op_sel_hi:[1,0,1]
	v_max3_f32 v66, v66, v94, v95
	v_max3_f32 v66, v66, v96, v97
	v_mov_b32_e32 v67, v66
	s_nop 1
	v_permlane32_swap_b32_e32 v66, v67
	v_max_f32_e32 v66, v66, v67
	v_sub_f32_e32 v67, v66, v222
	v_cmp_ge_f32_e32 vcc, s94, v67
	v_max_f32_e32 v66, v222, v66
	v_sub_f32_e32 v67, v222, v66
	v_exp_f32_e32 v67, v67
	s_cmp_eq_u64 vcc, exec
	s_cselect_b64 vcc, -1, 0
	v_cndmask_b32_e32 v231, v66, v222, vcc
	v_cndmask_b32_e64 v229, v67, 1.0, vcc
	v_sub_f32_e32 v66, v194, v231
	v_sub_f32_e32 v67, v195, v231
	v_sub_f32_e32 v68, v232, v231
	v_sub_f32_e32 v69, v233, v231
	v_sub_f32_e32 v70, v234, v231
	v_sub_f32_e32 v71, v235, v231
	v_sub_f32_e32 v72, v236, v231
	v_sub_f32_e32 v73, v237, v231
	v_sub_f32_e32 v74, v238, v231
	v_sub_f32_e32 v75, v239, v231
	v_sub_f32_e32 v76, v240, v231
	v_sub_f32_e32 v77, v241, v231
	v_sub_f32_e32 v78, v242, v231
	v_sub_f32_e32 v79, v243, v231
	v_sub_f32_e32 v80, v244, v231
	v_sub_f32_e32 v81, v245, v231
	v_exp_f32_e32 v66, v66
	v_exp_f32_e32 v67, v67
	v_exp_f32_e32 v68, v68
	v_exp_f32_e32 v69, v69
	v_exp_f32_e32 v70, v70
	v_exp_f32_e32 v71, v71
	v_exp_f32_e32 v72, v72
	v_exp_f32_e32 v73, v73
	v_exp_f32_e32 v74, v74
	v_exp_f32_e32 v75, v75
	v_exp_f32_e32 v76, v76
	v_exp_f32_e32 v77, v77
	v_exp_f32_e32 v78, v78
	v_exp_f32_e32 v79, v79
	v_exp_f32_e32 v80, v80
	v_exp_f32_e32 v81, v81
	v_sub_f32_e32 v97, v97, v231
	v_sub_f32_e32 v96, v96, v231
	v_sub_f32_e32 v95, v95, v231
	v_sub_f32_e32 v94, v94, v231
	v_sub_f32_e32 v93, v93, v231
	v_sub_f32_e32 v92, v92, v231
	v_sub_f32_e32 v91, v91, v231
	v_sub_f32_e32 v90, v90, v231
	v_sub_f32_e32 v89, v89, v231
	v_sub_f32_e32 v88, v88, v231
	v_sub_f32_e32 v87, v87, v231
	v_sub_f32_e32 v86, v86, v231
	v_sub_f32_e32 v85, v85, v231
	v_sub_f32_e32 v84, v84, v231
	v_sub_f32_e32 v83, v83, v231
	v_sub_f32_e32 v82, v82, v231
	s_xor_b64 s[62:63], exec, -1
.LBB0_180:
	s_or_b64 exec, exec, s[60:61]
	s_andn2_b64 s[0:1], s[0:1], exec
	s_and_b64 s[60:61], s[62:63], exec
	v_mov_b32_e32 v232, v161
	s_or_b64 s[0:1], s[0:1], s[60:61]
.LBB0_181:
	s_or_b64 exec, exec, s[58:59]
	s_and_saveexec_b64 s[58:59], s[0:1]
	s_cbranch_execz .LBB0_183
	v_mov_b32_e32 v66, v232
	v_mov_b32_e32 v231, v222
	v_sub_f32_e32 v66, v66, v231
	v_fmamk_f32 v67, v114, 0x3e38aa3b, v66
	v_mov_b32_e32 v114, v66
	v_mov_b32_e32 v229, 1.0
	v_fmamk_f32 v68, v115, 0x3e38aa3b, v66
	v_fmamk_f32 v69, v116, 0x3e38aa3b, v66
	v_fmamk_f32 v70, v117, 0x3e38aa3b, v66
	v_fmamk_f32 v71, v118, 0x3e38aa3b, v66
	v_fmamk_f32 v72, v119, 0x3e38aa3b, v66
	v_fmamk_f32 v73, v120, 0x3e38aa3b, v66
	v_fmamk_f32 v74, v121, 0x3e38aa3b, v66
	v_fmamk_f32 v75, v122, 0x3e38aa3b, v66
	v_fmamk_f32 v76, v123, 0x3e38aa3b, v66
	v_fmamk_f32 v77, v124, 0x3e38aa3b, v66
	v_fmamk_f32 v78, v125, 0x3e38aa3b, v66
	v_fmamk_f32 v79, v126, 0x3e38aa3b, v66
	v_fmamk_f32 v80, v127, 0x3e38aa3b, v66
	v_fmamk_f32 v81, v128, 0x3e38aa3b, v66
	v_fmac_f32_e32 v114, 0x3e38aa3b, v129
	v_fmamk_f32 v97, v113, 0x3e38aa3b, v66
	v_fmamk_f32 v96, v112, 0x3e38aa3b, v66
	v_fmamk_f32 v95, v111, 0x3e38aa3b, v66
	v_fmamk_f32 v94, v110, 0x3e38aa3b, v66
	v_fmamk_f32 v93, v109, 0x3e38aa3b, v66
	v_fmamk_f32 v92, v108, 0x3e38aa3b, v66
	v_fmamk_f32 v91, v107, 0x3e38aa3b, v66
	v_fmamk_f32 v90, v106, 0x3e38aa3b, v66
	v_fmamk_f32 v89, v105, 0x3e38aa3b, v66
	v_fmamk_f32 v88, v104, 0x3e38aa3b, v66
	v_fmamk_f32 v87, v103, 0x3e38aa3b, v66
	v_fmamk_f32 v86, v102, 0x3e38aa3b, v66
	v_fmamk_f32 v85, v101, 0x3e38aa3b, v66
	v_fmamk_f32 v84, v100, 0x3e38aa3b, v66
	v_fmamk_f32 v83, v99, 0x3e38aa3b, v66
	v_fmamk_f32 v82, v98, 0x3e38aa3b, v66
	v_exp_f32_e32 v66, v67
	v_exp_f32_e32 v67, v68
	v_exp_f32_e32 v68, v69
	v_exp_f32_e32 v69, v70
	v_exp_f32_e32 v70, v71
	v_exp_f32_e32 v71, v72
	v_exp_f32_e32 v72, v73
	v_exp_f32_e32 v73, v74
	v_exp_f32_e32 v74, v75
	v_exp_f32_e32 v75, v76
	v_exp_f32_e32 v76, v77
	v_exp_f32_e32 v77, v78
	v_exp_f32_e32 v78, v79
	v_exp_f32_e32 v79, v80
	v_exp_f32_e32 v80, v81
	v_exp_f32_e32 v81, v114

; __device__ __forceinline__ void finishSM(f32x16& p0, f32x16& p1, float alpha, float& l_reg, bf16x8& pa0, bf16x8& pa1, bf16x8& pa2, bf16x8& pa3) {
; #pragma unroll
;   for (int r = 0; r < 16; ++r) p1[r] = __builtin_amdgcn_exp2f(p1[r]);
;   float ps = 0;
; #pragma unroll
;   for (int r = 0; r < 16; ++r) ps += p0[r];
; #pragma unroll
;   for (int r = 0; r < 16; ++r) ps += p1[r];
;   { auto rr = __builtin_amdgcn_permlane32_swap(__float_as_uint(ps), __float_as_uint(ps), false, false);
;     ps = __uint_as_float(rr[0]) + __uint_as_float(rr[1]); }
;   l_reg = l_reg * alpha + ps;
;     ...
;   PK4(p0, 0, pa0); PK4(p0, 8, pa1); PK4(p1, 0, pa2); PK4(p1, 8, pa3);
;     ...
; }
; template <int ND0, int DOFF>
; __device__ __forceinline__ void qkt(f32x16& p0, f32x16& p1, const char* Ks, const bf16x8* qr, int r32, int hi) {
;   p0 = f32x16{}; p1 = f32x16{};
; #pragma unroll
;   for (int d0 = 0; d0 < ND0; ++d0) { const int cb = ((d0 + DOFF) * 16 + hi * 8) * 2;
;     bf16x8 b0 = *reinterpret_cast<const bf16x8*>(Ks + KSWZ(r32, cb));
;     bf16x8 b1 = *reinterpret_cast<const bf16x8*>(Ks + KSWZ(32 + r32, cb));
;     p0 = __builtin_amdgcn_mfma_f32_32x32x16_bf16(b0, qr[d0], p0, 0, 0, 0);
;     p1 = __builtin_amdgcn_mfma_f32_32x32x16_bf16(b1, qr[d0], p1, 0, 0, 0); }
; }
; __device__ __forceinline__ int v_st(int k, int c) { const int kk = (k & ~0xC) | ((k & 4) << 1) | ((k & 8) >> 1); return ((kk >> 3) * 4 + (c >> 5)) * 512 + ((kk & 7) * 32 + (c & 31)) * 2; }
; __device__ __forceinline__ int v_rd_base(int lane) { return ((lane & 3) << 3) | (((lane >> 2) & 3) << 6) | (((lane >> 4) & 1) << 5) | (((lane >> 5) & 1) << 8); }
; template <int OFF> __device__ __forceinline__ s16x4 tr_read(int vb) {
;   s16x4 r; asm volatile("ds_read_b64_tr_b16 %0, %1 offset:%2" : "=&v"(r) : "v"(vb), "i"(OFF) : "memory"); return r;
; template <int MODE>
; __device__ __forceinline__ void attn_body(const bf16_t* __restrict__ Qb, const bf16_t* __restrict__ Kh, const bf16_t* __restrict__ Vh, int NT, int krel0,
;                                           char* lds, const float* __restrict__ lutg, const AttnEpi& E) {
;     ...
;     __syncthreads();
;     SBAR(); qkt<ND0, DOFF>(pA0, pA1, K_lds + oq, qr, r32, hi);
;     finishSM(pB0, pB1, alB, l_reg, pa0, pa1, pa2, pa3); SBAR();
;     if (j + 3 < NT) SLOAD(SE, (j + 3) * 64); SBAR();
;     pv_d0(o, vb0 + op, pa0, pa1, pa2, pa3); PSM(pA0, pA1, mnA, alA, j + 1);
;     SWAIT(); SWRITE(ow, SO);
.Ldp_10:
	v_add_u32_e32 v102, s58, v216
	ds_read_b128 v[98:101], v102 offset:49152
	ds_read_b128 v[102:105], v102 offset:57344
	v_add_u32_e32 v194, s58, v217
	ds_read_b128 v[232:235], v194 offset:49152
	ds_read_b128 v[236:239], v194 offset:57344
	v_add_u32_e32 v194, s58, v218
	s_waitcnt lgkmcnt(3)
	v_mfma_f32_32x32x16_bf16 v[114:129], v[98:101], v[142:145], 0
	v_exp_f32_e32 v82, v82
	v_exp_f32_e32 v83, v83
	v_exp_f32_e32 v84, v84
	v_exp_f32_e32 v85, v85
	v_exp_f32_e32 v86, v86
	v_exp_f32_e32 v87, v87
	v_exp_f32_e32 v88, v88
	s_waitcnt lgkmcnt(2)
	v_mfma_f32_32x32x16_bf16 v[98:113], v[102:105], v[142:145], 0
	v_exp_f32_e32 v89, v89
	v_exp_f32_e32 v90, v90
	v_exp_f32_e32 v91, v91
	v_exp_f32_e32 v92, v92
	v_exp_f32_e32 v93, v93
	v_exp_f32_e32 v94, v94
	v_exp_f32_e32 v95, v95
	s_waitcnt lgkmcnt(1)
	v_mfma_f32_32x32x16_bf16 v[114:129], v[232:235], v[138:141], v[114:129]
	v_exp_f32_e32 v96, v96
	v_exp_f32_e32 v97, v97
	s_waitcnt lgkmcnt(0)
	v_mfma_f32_32x32x16_bf16 v[98:113], v[236:239], v[138:141], v[98:113]
	ds_read_b128 v[232:235], v194 offset:49152
	ds_read_b128 v[236:239], v194 offset:57344
	v_add_u32_e32 v194, s58, v219
	s_waitcnt lgkmcnt(1)
	v_mfma_f32_32x32x16_bf16 v[114:129], v[232:235], v[134:137], v[114:129]
	s_waitcnt lgkmcnt(0)
	v_mfma_f32_32x32x16_bf16 v[98:113], v[236:239], v[134:137], v[98:113]
	ds_read_b128 v[232:235], v194 offset:49152
	ds_read_b128 v[236:239], v194 offset:57344
	v_add_f32_e32 v194, v67, v66
	v_add_f32_e32 v194, v68, v194
	v_add_f32_e32 v194, v69, v194
	v_add_f32_e32 v194, v70, v194
	v_add_f32_e32 v194, v71, v194
	v_add_f32_e32 v194, v72, v194
	v_add_f32_e32 v194, v73, v194
	v_add_f32_e32 v194, v74, v194
	v_add_f32_e32 v194, v75, v194
	v_add_f32_e32 v194, v76, v194
	v_add_f32_e32 v194, v77, v194
	v_add_f32_e32 v194, v78, v194
	v_add_f32_e32 v194, v79, v194
	v_add_f32_e32 v194, v80, v194
	v_add_f32_e32 v194, v81, v194
	v_add_f32_e32 v194, v82, v194
	v_add_f32_e32 v194, v83, v194
	v_add_f32_e32 v194, v84, v194
	v_add_f32_e32 v194, v85, v194
	v_add_f32_e32 v194, v86, v194
	v_add_f32_e32 v194, v87, v194
	v_add_f32_e32 v194, v88, v194
	v_add_f32_e32 v194, v89, v194
	v_add_f32_e32 v194, v90, v194
	v_add_f32_e32 v194, v91, v194
	s_waitcnt lgkmcnt(1)
	v_mfma_f32_32x32x16_bf16 v[114:129], v[232:235], v[130:133], v[114:129]
	v_add_f32_e32 v194, v92, v194
	v_add_f32_e32 v194, v93, v194
	v_add_f32_e32 v194, v94, v194
	v_add_f32_e32 v194, v95, v194
	v_add_f32_e32 v194, v96, v194
	v_add_f32_e32 v232, v97, v194
	v_mov_b32_e32 v233, v232
	s_waitcnt lgkmcnt(0)
	v_mfma_f32_32x32x16_bf16 v[98:113], v[236:239], v[130:133], v[98:113]
	v_cvt_pk_bf16_f32 v66, v66, v67
	v_cvt_pk_bf16_f32 v67, v68, v69
	v_cvt_pk_bf16_f32 v68, v70, v71
	v_cvt_pk_bf16_f32 v69, v72, v73
	v_cvt_pk_bf16_f32 v70, v74, v75
	v_cvt_pk_bf16_f32 v71, v76, v77
	v_cvt_pk_bf16_f32 v72, v78, v79
	v_cvt_pk_bf16_f32 v73, v80, v81
	v_cvt_pk_bf16_f32 v74, v82, v83
	v_cvt_pk_bf16_f32 v75, v84, v85
	v_cvt_pk_bf16_f32 v76, v86, v87
	v_cvt_pk_bf16_f32 v77, v88, v89
	v_cvt_pk_bf16_f32 v78, v90, v91
	v_cvt_pk_bf16_f32 v79, v92, v93
	v_cvt_pk_bf16_f32 v80, v94, v95
	v_cvt_pk_bf16_f32 v81, v96, v97
	v_permlane32_swap_b32_e32 v232, v233
	v_permlane32_swap_b32_e32 v66, v68
	v_permlane32_swap_b32_e32 v67, v69
	v_permlane32_swap_b32_e32 v70, v72
	v_permlane32_swap_b32_e32 v71, v73
	v_permlane32_swap_b32_e32 v74, v76
	v_permlane32_swap_b32_e32 v75, v77
	v_permlane32_swap_b32_e32 v78, v80
	v_permlane32_swap_b32_e32 v79, v81
	s_add_i32 s67, s67, 2
	s_cmp_ge_u32 s67, s11
	s_cselect_b64 s[0:1], -1, 0
	s_cmp_lt_u32 s31, 4
	s_cbranch_scc1 .Ldp_9
	s_waitcnt vmcnt(0) lgkmcnt(0)
	s_barrier
.Ldp_9:
	s_add_i32 m0, s66, s30
	s_nop 0
	global_load_lds_dwordx4 v248, s[26:27]
	s_add_i32 m0, m0, 0x400
	s_nop 0
	global_load_lds_dwordx4 v249, s[26:27]
	s_add_i32 m0, s68, s30
	s_add_i32 m0, m0, 0xc000
	s_nop 0
	global_load_lds_dwordx4 v250, s[28:29]
	s_add_i32 m0, m0, 0x400
	s_nop 0
	global_load_lds_dwordx4 v251, s[28:29]
	s_add_u32 s26, s26, 0x90000
	s_addc_u32 s27, s27, 0
	s_add_u32 s28, s28, 0x90000
	s_addc_u32 s29, s29, 0
.LBB0_189:
	v_add_u32_e32 v194, s68, v221
	ds_read_b64_tr_b16 v[82:83], v194 offset:0
	ds_read_b64_tr_b16 v[84:85], v194 offset:0x800
	ds_read_b64_tr_b16 v[86:87], v194 offset:0x1000
	ds_read_b64_tr_b16 v[88:89], v194 offset:0x1800
	ds_read_b64_tr_b16 v[90:91], v194 offset:0x2000
	ds_read_b64_tr_b16 v[92:93], v194 offset:0x2800
	ds_read_b64_tr_b16 v[94:95], v194 offset:0x3000
	ds_read_b64_tr_b16 v[96:97], v194 offset:0x3800
	s_waitcnt lgkmcnt(0)
	s_nop 0
	v_mfma_f32_32x32x16_bf16 v[50:65], v[66:69], v[82:85], v[50:65]
	ds_read_b64_tr_b16 v[82:83], v194 offset:0x200
	ds_read_b64_tr_b16 v[84:85], v194 offset:0xa00
	v_mfma_f32_32x32x16_bf16 v[50:65], v[70:73], v[86:89], v[50:65]
	ds_read_b64_tr_b16 v[86:87], v194 offset:0x1200
	ds_read_b64_tr_b16 v[88:89], v194 offset:0x1a00
	v_mfma_f32_32x32x16_bf16 v[50:65], v[74:77], v[90:93], v[50:65]
	ds_read_b64_tr_b16 v[90:91], v194 offset:0x2200
	ds_read_b64_tr_b16 v[92:93], v194 offset:0x2a00
	v_mfma_f32_32x32x16_bf16 v[50:65], v[78:81], v[94:97], v[50:65]
	ds_read_b64_tr_b16 v[94:95], v194 offset:0x3200
	ds_read_b64_tr_b16 v[96:97], v194 offset:0x3a00
	s_waitcnt lgkmcnt(0)
	v_mfma_f32_32x32x16_bf16 v[34:49], v[66:69], v[82:85], v[34:49]
	ds_read_b64_tr_b16 v[82:83], v194 offset:0x400
	ds_read_b64_tr_b16 v[84:85], v194 offset:0xc00
	v_mfma_f32_32x32x16_bf16 v[34:49], v[70:73], v[86:89], v[34:49]
	ds_read_b64_tr_b16 v[86:87], v194 offset:0x1400
	ds_read_b64_tr_b16 v[88:89], v194 offset:0x1c00
	v_mfma_f32_32x32x16_bf16 v[34:49], v[74:77], v[90:93], v[34:49]
	ds_read_b64_tr_b16 v[90:91], v194 offset:0x2400
	ds_read_b64_tr_b16 v[92:93], v194 offset:0x2c00
	v_mfma_f32_32x32x16_bf16 v[34:49], v[78:81], v[94:97], v[34:49]
	ds_read_b64_tr_b16 v[94:95], v194 offset:0x3400
	ds_read_b64_tr_b16 v[96:97], v194 offset:0x3c00
	s_waitcnt lgkmcnt(0)
	v_mfma_f32_32x32x16_bf16 v[18:33], v[66:69], v[82:85], v[18:33]
	ds_read_b64_tr_b16 v[82:83], v194 offset:0x600
	ds_read_b64_tr_b16 v[84:85], v194 offset:0xe00
	v_mfma_f32_32x32x16_bf16 v[18:33], v[70:73], v[86:89], v[18:33]
	ds_read_b64_tr_b16 v[86:87], v194 offset:0x1600
	ds_read_b64_tr_b16 v[88:89], v194 offset:0x1e00
	v_mfma_f32_32x32x16_bf16 v[18:33], v[74:77], v[90:93], v[18:33]
	ds_read_b64_tr_b16 v[90:91], v194 offset:0x2600
	ds_read_b64_tr_b16 v[92:93], v194 offset:0x2e00
	v_mfma_f32_32x32x16_bf16 v[18:33], v[78:81], v[94:97], v[18:33]
	ds_read_b64_tr_b16 v[94:95], v194 offset:0x3600
	ds_read_b64_tr_b16 v[96:97], v194 offset:0x3e00
	s_waitcnt lgkmcnt(0)
	v_mfma_f32_32x32x16_bf16 v[2:17], v[66:69], v[82:85], v[2:17]
	s_cmp_gt_i32 s95, s24
	s_cselect_b64 s[58:59], -1, 0
	s_cmp_lt_i32 s15, s24
	s_cselect_b64 vcc, -1, 0
	v_mov_b32_e32 v234, v160
	v_mfma_f32_32x32x16_bf16 v[2:17], v[70:73], v[86:89], v[2:17]
	v_mfma_f32_32x32x16_bf16 v[2:17], v[74:77], v[90:93], v[2:17]
	v_mfma_f32_32x32x16_bf16 v[2:17], v[78:81], v[94:97], v[2:17]
	s_and_saveexec_b64 s[60:61], vcc
	s_cbranch_execz .LBB0_193
; template <int MODE>
; __device__ __forceinline__ void partialSM(f32x16& p0, f32x16& p1, float& m_reg, float& mn, float& alpha, int relh, int relw_min, int relw_max, const float* lut) {
;     ...
;     if (nearT) {
; #pragma unroll
;       for (int r = 0; r < 16; ++r) { const int i0 = relh + (r & 3) + 8 * (r >> 2);
;         const int a0 = min(max(i0, -129), 129) + 129, a1 = min(max(i0 + 32, -129), 129) + 129;
;         p0[r] = fmaf(p0[r], C, lut[a0]); p1[r] = fmaf(p1[r], C, lut[a1]); }
;     } else {
; #pragma unroll
;       for (int r = 0; r < 16; ++r) { p0[r] = fmaf(p0[r], C, cfar); p1[r] = fmaf(p1[r], C, cfar); }
;     }
;     float pmax = p0[0];
; #pragma unroll
;     for (int r = 1; r < 16; ++r) pmax = fmaxf(pmax, p0[r]);
; #pragma unroll
;     for (int r = 0; r < 16; ++r) pmax = fmaxf(pmax, p1[r]);
	s_cmp_gt_i32 s91, s25
	s_cselect_b64 vcc, -1, 0
	s_mov_b64 s[64:65], -1
	s_and_saveexec_b64 s[62:63], vcc
	s_cbranch_execz .LBB0_192
	v_add_u32_e32 v230, s77, v225
	v_add_u32_e32 v66, 0x80, v230
	v_add_u32_e32 v68, 0x81, v230
	v_add_u32_e32 v70, 0x82, v230
	v_add_u32_e32 v72, 0x83, v230
	v_med3_i32 v67, v66, s39, v198
	v_med3_i32 v66, v66, s33, v199
	v_med3_i32 v69, v68, s39, v198
	v_med3_i32 v68, v68, s33, v199
	v_med3_i32 v71, v70, s39, v198
	v_med3_i32 v70, v70, s33, v199
	v_med3_i32 v73, v72, s39, v198
	v_med3_i32 v72, v72, s33, v199
	v_lshl_add_u32 v67, v67, 2, s76
	v_lshl_add_u32 v66, v66, 2, s76
	v_lshl_add_u32 v69, v69, 2, s76
	v_lshl_add_u32 v68, v68, 2, s76
	v_lshl_add_u32 v70, v70, 2, s76
	v_lshl_add_u32 v72, v72, 2, s76
	v_lshl_add_u32 v71, v71, 2, s76
	v_lshl_add_u32 v73, v73, 2, s76
	ds_read_b32 v194, v67 offset:516
	ds_read_b32 v66, v66 offset:644
	ds_read_b32 v195, v69 offset:516
	ds_read_b32 v67, v68 offset:644
	ds_read_b32 v234, v71 offset:516
	ds_read_b32 v68, v70 offset:644
	ds_read_b32 v235, v73 offset:516
	ds_read_b32 v69, v72 offset:644
	v_add_u32_e32 v70, 0x88, v230
	v_add_u32_e32 v72, 0x89, v230
	v_add_u32_e32 v74, 0x8a, v230
	v_add_u32_e32 v76, 0x8b, v230
	v_med3_i32 v71, v70, s39, v198
	v_med3_i32 v70, v70, s33, v199
	v_med3_i32 v73, v72, s39, v198
	v_med3_i32 v72, v72, s33, v199
	v_med3_i32 v75, v74, s39, v198
	v_med3_i32 v74, v74, s33, v199
	v_med3_i32 v77, v76, s39, v198
	v_med3_i32 v76, v76, s33, v199
	v_lshl_add_u32 v71, v71, 2, s76
	v_lshl_add_u32 v70, v70, 2, s76
	v_lshl_add_u32 v73, v73, 2, s76
	v_lshl_add_u32 v72, v72, 2, s76
	v_lshl_add_u32 v74, v74, 2, s76
	v_lshl_add_u32 v76, v76, 2, s76
	v_lshl_add_u32 v75, v75, 2, s76
	v_lshl_add_u32 v77, v77, 2, s76
	ds_read_b32 v236, v71 offset:516
	ds_read_b32 v70, v70 offset:644
	ds_read_b32 v237, v73 offset:516
	ds_read_b32 v71, v72 offset:644
	ds_read_b32 v238, v75 offset:516
	ds_read_b32 v72, v74 offset:644
	ds_read_b32 v239, v77 offset:516
	ds_read_b32 v73, v76 offset:644
	v_add_u32_e32 v74, 0x90, v230
	v_add_u32_e32 v76, 0x91, v230
	v_add_u32_e32 v78, 0x92, v230
	v_add_u32_e32 v80, 0x93, v230
	v_med3_i32 v75, v74, s39, v198
	v_med3_i32 v74, v74, s33, v199
	v_med3_i32 v77, v76, s39, v198
	v_med3_i32 v76, v76, s33, v199
	v_med3_i32 v79, v78, s39, v198
	v_med3_i32 v78, v78, s33, v199
	v_med3_i32 v81, v80, s39, v198
	v_med3_i32 v80, v80, s33, v199
	v_lshl_add_u32 v75, v75, 2, s76
	v_lshl_add_u32 v74, v74, 2, s76
	v_lshl_add_u32 v77, v77, 2, s76
	v_lshl_add_u32 v76, v76, 2, s76
	v_lshl_add_u32 v78, v78, 2, s76
	v_lshl_add_u32 v80, v80, 2, s76
	v_lshl_add_u32 v79, v79, 2, s76
	v_lshl_add_u32 v81, v81, 2, s76
	ds_read_b32 v240, v75 offset:516
	ds_read_b32 v74, v74 offset:644
	ds_read_b32 v241, v77 offset:516
	ds_read_b32 v75, v76 offset:644
	ds_read_b32 v242, v79 offset:516
	ds_read_b32 v76, v78 offset:644
	ds_read_b32 v243, v81 offset:516
	ds_read_b32 v77, v80 offset:644
	v_add_u32_e32 v78, 0x98, v230
	v_add_u32_e32 v80, 0x99, v230
	v_add_u32_e32 v82, 0x9a, v230
	v_med3_i32 v79, v78, s39, v198
	v_med3_i32 v78, v78, s33, v199
	v_med3_i32 v81, v80, s39, v198
	v_med3_i32 v80, v80, s33, v199
	v_med3_i32 v83, v82, s39, v198
	v_med3_i32 v82, v82, s33, v199
	v_add_u32_e32 v84, 0x9b, v230
	s_waitcnt lgkmcnt(14)
	v_fmac_f32_e32 v194, 0x3e38aa3b, v114
	v_fmac_f32_e32 v195, 0x3e38aa3b, v115
	v_lshl_add_u32 v79, v79, 2, s76
	v_lshl_add_u32 v78, v78, 2, s76
	v_lshl_add_u32 v81, v81, 2, s76
	v_lshl_add_u32 v80, v80, 2, s76
	v_lshl_add_u32 v82, v82, 2, s76
	v_med3_i32 v85, v84, s39, v198
	v_med3_i32 v84, v84, s33, v199
	v_fmac_f32_e32 v234, 0x3e38aa3b, v116
	v_fmac_f32_e32 v235, 0x3e38aa3b, v117
	v_lshl_add_u32 v83, v83, 2, s76
	v_lshl_add_u32 v85, v85, 2, s76
	v_lshl_add_u32 v84, v84, 2, s76
	ds_read_b32 v230, v79 offset:516
	ds_read_b32 v78, v78 offset:644
	ds_read_b32 v244, v81 offset:516
	ds_read_b32 v79, v80 offset:644
	ds_read_b32 v245, v83 offset:516
	ds_read_b32 v80, v82 offset:644
	ds_read_b32 v246, v85 offset:516
	ds_read_b32 v81, v84 offset:644
	v_max_f32_e32 v82, v194, v195
	v_fmac_f32_e32 v236, 0x3e38aa3b, v118
	s_waitcnt lgkmcnt(14)
	v_fmac_f32_e32 v237, 0x3e38aa3b, v119
	v_max3_f32 v82, v82, v234, v235
	v_fmac_f32_e32 v238, 0x3e38aa3b, v120
	v_fmac_f32_e32 v239, 0x3e38aa3b, v121
	v_max3_f32 v82, v82, v236, v237
	v_fmac_f32_e32 v240, 0x3e38aa3b, v122
	s_waitcnt lgkmcnt(13)
	v_fmac_f32_e32 v241, 0x3e38aa3b, v123
	v_max3_f32 v82, v82, v238, v239
	s_waitcnt lgkmcnt(11)
	v_fmac_f32_e32 v242, 0x3e38aa3b, v124
	s_waitcnt lgkmcnt(9)
	v_fmac_f32_e32 v243, 0x3e38aa3b, v125
	v_max3_f32 v82, v82, v240, v241
	s_waitcnt lgkmcnt(7)
	v_fmac_f32_e32 v230, 0x3e38aa3b, v126
	s_waitcnt lgkmcnt(5)
	v_fmac_f32_e32 v244, 0x3e38aa3b, v127
	v_max3_f32 v82, v82, v242, v243
	s_waitcnt lgkmcnt(3)
	v_fmac_f32_e32 v245, 0x3e38aa3b, v128
	s_waitcnt lgkmcnt(1)
; template <int MODE>
; __device__ __forceinline__ void partialSM(f32x16& p0, f32x16& p1, float& m_reg, float& mn, float& alpha, int relh, int relw_min, int relw_max, const float* lut) {
;     ...
;       if (!nearT) {
;         float pmax = p0[0];
; #pragma unroll
;         for (int r = 1; r < 16; ++r) pmax = fmaxf(pmax, p0[r]);
; #pragma unroll
;         for (int r = 0; r < 16; ++r) pmax = fmaxf(pmax, p1[r]);
;         { auto rr = __builtin_amdgcn_permlane32_swap(__float_as_uint(pmax), __float_as_uint(pmax), false, false);
;           pmax = fmaxf(__uint_as_float(rr[0]), __uint_as_float(rr[1])); }
;         const float tmax = fmaf(pmax, C, cfar);
;         if (__builtin_expect(__all(tmax - m_reg <= THR2), 1)) { mn = m_reg; alpha = 1.f; }
;         else { mn = fmaxf(m_reg, tmax); alpha = __builtin_amdgcn_exp2f(m_reg - mn); m_reg = mn; }
;         const float off = cfar - mn;
; #pragma unroll
;         for (int r = 0; r < 16; ++r) p0[r] = fmaf(p0[r], C, off);
; #pragma unroll
;         for (int r = 0; r < 16; ++r) p1[r] = fmaf(p1[r], C, off);
; #pragma unroll
;         for (int r = 0; r < 16; ++r) p0[r] = __builtin_amdgcn_exp2f(p0[r]);
;     ...
;     { auto rr = __builtin_amdgcn_permlane32_swap(__float_as_uint(pmax), __float_as_uint(pmax), false, false);
;       pmax = fmaxf(__uint_as_float(rr[0]), __uint_as_float(rr[1])); }
;     if (__builtin_expect(__all(pmax - m_reg <= THR2), 1)) { mn = m_reg; alpha = 1.f; }
;     else { mn = fmaxf(m_reg, pmax); alpha = __builtin_amdgcn_exp2f(m_reg - mn); m_reg = mn; }
; #pragma unroll
;     for (int r = 0; r < 16; ++r) p0[r] = __builtin_amdgcn_exp2f(p0[r] - mn);
; #pragma unroll
;     for (int r = 0; r < 16; ++r) p1[r] = p1[r] - mn;
	v_fmac_f32_e32 v246, 0x3e38aa3b, v129
	v_max3_f32 v82, v82, v230, v244
	v_max3_f32 v84, v82, v245, v246
	v_pk_fma_f32 v[82:83], v[98:99], s[48:49], v[66:67] op_sel_hi:[1,0,1]
	v_pk_fma_f32 v[86:87], v[102:103], s[48:49], v[70:71] op_sel_hi:[1,0,1]
	v_max3_f32 v66, v84, v82, v83
	v_pk_fma_f32 v[84:85], v[100:101], s[48:49], v[68:69] op_sel_hi:[1,0,1]
	v_pk_fma_f32 v[88:89], v[104:105], s[48:49], v[72:73] op_sel_hi:[1,0,1]
	v_max3_f32 v66, v66, v84, v85
	v_max3_f32 v66, v66, v86, v87
	v_max3_f32 v66, v66, v88, v89
	v_pk_fma_f32 v[90:91], v[106:107], s[48:49], v[74:75] op_sel_hi:[1,0,1]
	v_pk_fma_f32 v[92:93], v[108:109], s[48:49], v[76:77] op_sel_hi:[1,0,1]
	v_max3_f32 v66, v66, v90, v91
	v_max3_f32 v66, v66, v92, v93
	v_pk_fma_f32 v[94:95], v[110:111], s[48:49], v[78:79] op_sel_hi:[1,0,1]
	s_waitcnt lgkmcnt(0)
	v_pk_fma_f32 v[96:97], v[112:113], s[48:49], v[80:81] op_sel_hi:[1,0,1]
	v_max3_f32 v66, v66, v94, v95
	v_max3_f32 v66, v66, v96, v97
	v_mov_b32_e32 v67, v66
	s_nop 1
	v_permlane32_swap_b32_e32 v66, v67
	v_max_f32_e32 v66, v66, v67
	v_sub_f32_e32 v67, v66, v231
	v_cmp_ge_f32_e32 vcc, s94, v67
	v_max_f32_e32 v66, v231, v66
	v_sub_f32_e32 v67, v231, v66
	v_exp_f32_e32 v67, v67
	s_cmp_eq_u64 vcc, exec
	s_cselect_b64 vcc, -1, 0
	v_cndmask_b32_e32 v222, v66, v231, vcc
	v_cndmask_b32_e64 v228, v67, 1.0, vcc
	v_sub_f32_e32 v66, v194, v222
	v_sub_f32_e32 v67, v195, v222
	v_sub_f32_e32 v68, v234, v222
	v_sub_f32_e32 v69, v235, v222
	v_sub_f32_e32 v70, v236, v222
	v_sub_f32_e32 v71, v237, v222
	v_sub_f32_e32 v72, v238, v222
	v_sub_f32_e32 v73, v239, v222
	v_sub_f32_e32 v74, v240, v222
	v_sub_f32_e32 v75, v241, v222
	v_sub_f32_e32 v76, v242, v222
	v_sub_f32_e32 v77, v243, v222
	v_sub_f32_e32 v78, v230, v222
	v_sub_f32_e32 v79, v244, v222
	v_sub_f32_e32 v80, v245, v222
	v_sub_f32_e32 v81, v246, v222
	v_exp_f32_e32 v66, v66
	v_exp_f32_e32 v67, v67
	v_exp_f32_e32 v68, v68
	v_exp_f32_e32 v69, v69
	v_exp_f32_e32 v70, v70
	v_exp_f32_e32 v71, v71
	v_exp_f32_e32 v72, v72
	v_exp_f32_e32 v73, v73
	v_exp_f32_e32 v74, v74
	v_exp_f32_e32 v75, v75
	v_exp_f32_e32 v76, v76
	v_exp_f32_e32 v77, v77
	v_exp_f32_e32 v78, v78
	v_exp_f32_e32 v79, v79
	v_exp_f32_e32 v80, v80
	v_exp_f32_e32 v81, v81
	v_sub_f32_e32 v97, v97, v222
	v_sub_f32_e32 v96, v96, v222
	v_sub_f32_e32 v95, v95, v222
	v_sub_f32_e32 v94, v94, v222
	v_sub_f32_e32 v93, v93, v222
	v_sub_f32_e32 v92, v92, v222
	v_sub_f32_e32 v91, v91, v222
	v_sub_f32_e32 v90, v90, v222
	v_sub_f32_e32 v89, v89, v222
	v_sub_f32_e32 v88, v88, v222
	v_sub_f32_e32 v87, v87, v222
	v_sub_f32_e32 v86, v86, v222
	v_sub_f32_e32 v85, v85, v222
	v_sub_f32_e32 v84, v84, v222
	v_sub_f32_e32 v83, v83, v222
	v_sub_f32_e32 v82, v82, v222
	s_xor_b64 s[64:65], exec, -1
.LBB0_192:
	s_or_b64 exec, exec, s[62:63]
	s_andn2_b64 s[58:59], s[58:59], exec
	s_and_b64 s[62:63], s[64:65], exec
	v_mov_b32_e32 v234, v161
	s_or_b64 s[58:59], s[58:59], s[62:63]
.LBB0_193:
	s_or_b64 exec, exec, s[60:61]
	s_and_saveexec_b64 s[60:61], s[58:59]
	s_cbranch_execz .LBB0_195
	v_mov_b32_e32 v66, v234
	v_mov_b32_e32 v222, v231
	v_sub_f32_e32 v66, v66, v222
	v_fmamk_f32 v67, v114, 0x3e38aa3b, v66
	v_mov_b32_e32 v114, v66
	v_mov_b32_e32 v228, 1.0
	v_fmamk_f32 v68, v115, 0x3e38aa3b, v66
	v_fmamk_f32 v69, v116, 0x3e38aa3b, v66
	v_fmamk_f32 v70, v117, 0x3e38aa3b, v66
	v_fmamk_f32 v71, v118, 0x3e38aa3b, v66
	v_fmamk_f32 v72, v119, 0x3e38aa3b, v66
	v_fmamk_f32 v73, v120, 0x3e38aa3b, v66
	v_fmamk_f32 v74, v121, 0x3e38aa3b, v66
	v_fmamk_f32 v75, v122, 0x3e38aa3b, v66
	v_fmamk_f32 v76, v123, 0x3e38aa3b, v66
	v_fmamk_f32 v77, v124, 0x3e38aa3b, v66
	v_fmamk_f32 v78, v125, 0x3e38aa3b, v66
	v_fmamk_f32 v79, v126, 0x3e38aa3b, v66
	v_fmamk_f32 v80, v127, 0x3e38aa3b, v66
	v_fmamk_f32 v81, v128, 0x3e38aa3b, v66
	v_fmac_f32_e32 v114, 0x3e38aa3b, v129
	v_fmamk_f32 v97, v113, 0x3e38aa3b, v66
	v_fmamk_f32 v96, v112, 0x3e38aa3b, v66
	v_fmamk_f32 v95, v111, 0x3e38aa3b, v66
	v_fmamk_f32 v94, v110, 0x3e38aa3b, v66
	v_fmamk_f32 v93, v109, 0x3e38aa3b, v66
	v_fmamk_f32 v92, v108, 0x3e38aa3b, v66
	v_fmamk_f32 v91, v107, 0x3e38aa3b, v66
	v_fmamk_f32 v90, v106, 0x3e38aa3b, v66
	v_fmamk_f32 v89, v105, 0x3e38aa3b, v66
	v_fmamk_f32 v88, v104, 0x3e38aa3b, v66
	v_fmamk_f32 v87, v103, 0x3e38aa3b, v66
	v_fmamk_f32 v86, v102, 0x3e38aa3b, v66
	v_fmamk_f32 v85, v101, 0x3e38aa3b, v66
	v_fmamk_f32 v84, v100, 0x3e38aa3b, v66
	v_fmamk_f32 v83, v99, 0x3e38aa3b, v66
	v_fmamk_f32 v82, v98, 0x3e38aa3b, v66
	v_exp_f32_e32 v66, v67
	v_exp_f32_e32 v67, v68
	v_exp_f32_e32 v68, v69
	v_exp_f32_e32 v69, v70
	v_exp_f32_e32 v70, v71
	v_exp_f32_e32 v71, v72
	v_exp_f32_e32 v72, v73
	v_exp_f32_e32 v73, v74
	v_exp_f32_e32 v74, v75
	v_exp_f32_e32 v75, v76
	v_exp_f32_e32 v76, v77
	v_exp_f32_e32 v77, v78
	v_exp_f32_e32 v78, v79
	v_exp_f32_e32 v79, v80
	v_exp_f32_e32 v80, v81
	v_exp_f32_e32 v81, v114

; #define SBAR() __builtin_amdgcn_sched_barrier(0)
; #define RESC(a) do { if (__any((a) < 1.f)) { if (hi == 0) al_l[r32] = (a); asm volatile("s_waitcnt lgkmcnt(0)" ::: "memory"); \
;     _Pragma("unroll") for (int d = 0; d < 4; ++d) _Pragma("unroll") for (int r = 0; r < 16; ++r) o[d][r] *= al_l[crow(r, hi)]; } } while (0)
; #define PSM(P0, P1, MN, AL, J) partialSM<MODE>(P0, P1, m_reg, MN, AL, relq + 64 * (J), relwmin + 64 * (J), relwmax + 64 * (J), lut)
; __device__ __forceinline__ void finishSM(f32x16& p0, f32x16& p1, float alpha, float& l_reg, bf16x8& pa0, bf16x8& pa1, bf16x8& pa2, bf16x8& pa3) {
; #pragma unroll
;   for (int r = 0; r < 16; ++r) p1[r] = __builtin_amdgcn_exp2f(p1[r]);
;   float ps = 0;
; #pragma unroll
;   for (int r = 0; r < 16; ++r) ps += p0[r];
; #pragma unroll
;   for (int r = 0; r < 16; ++r) ps += p1[r];
;   { auto rr = __builtin_amdgcn_permlane32_swap(__float_as_uint(ps), __float_as_uint(ps), false, false);
;     ps = __uint_as_float(rr[0]) + __uint_as_float(rr[1]); }
;   l_reg = l_reg * alpha + ps;
;     ...
;   PK4(p0, 0, pa0); PK4(p0, 8, pa1); PK4(p1, 0, pa2); PK4(p1, 8, pa3);
; template <int MODE>
; __device__ __forceinline__ void attn_body(const bf16_t* __restrict__ Qb, const bf16_t* __restrict__ Kh, const bf16_t* __restrict__ Vh, int NT, int krel0,
;                                           char* lds, const float* __restrict__ lutg, const AttnEpi& E) {
;     ...
;   __syncthreads();
;   SBAR(); qkt<ND0, DOFF>(pB0, pB1, K_lds + oq, qr, r32, hi);
;   finishSM(pA0, pA1, alA, l_reg, pa0, pa1, pa2, pa3); SBAR();
;   pv_d0(o, vb0 + op, pa0, pa1, pa2, pa3); PSM(pB0, pB1, mnB, alB, NT - 1);
;   RESC(alB);
;   finishSM(pB0, pB1, alB, l_reg, pa0, pa1, pa2, pa3); SBAR();
;   pv_d0(o, vb0 + oq, pa0, pa1, pa2, pa3);
.Ldp_8:
	v_add_u32_e32 v102, s60, v216
	ds_read_b128 v[98:101], v102 offset:49152
	ds_read_b128 v[102:105], v102 offset:57344
	v_add_u32_e32 v146, s60, v217
	v_exp_f32_e32 v82, v82
	v_exp_f32_e32 v83, v83
	s_waitcnt lgkmcnt(1)
	v_mfma_f32_32x32x16_bf16 v[114:129], v[98:101], v[142:145], 0
	v_exp_f32_e32 v84, v84
	v_exp_f32_e32 v85, v85
	v_exp_f32_e32 v86, v86
	v_exp_f32_e32 v87, v87
	v_exp_f32_e32 v88, v88
	v_exp_f32_e32 v89, v89
	v_exp_f32_e32 v90, v90
	s_waitcnt lgkmcnt(0)
	v_mfma_f32_32x32x16_bf16 v[98:113], v[102:105], v[142:145], 0
	ds_read_b128 v[142:145], v146 offset:49152
	ds_read_b128 v[146:149], v146 offset:57344
	v_exp_f32_e32 v91, v91
	v_exp_f32_e32 v92, v92
	v_exp_f32_e32 v93, v93
	v_exp_f32_e32 v94, v94
	v_exp_f32_e32 v95, v95
	v_exp_f32_e32 v96, v96
	s_waitcnt lgkmcnt(1)
	v_mfma_f32_32x32x16_bf16 v[114:129], v[142:145], v[138:141], v[114:129]
	v_add_u32_e32 v142, s60, v218
	v_exp_f32_e32 v97, v97
	s_waitcnt lgkmcnt(0)
	v_mfma_f32_32x32x16_bf16 v[98:113], v[146:149], v[138:141], v[98:113]
	ds_read_b128 v[138:141], v142 offset:49152
	ds_read_b128 v[142:145], v142 offset:57344
	s_waitcnt lgkmcnt(1)
	v_mfma_f32_32x32x16_bf16 v[114:129], v[138:141], v[134:137], v[114:129]
	v_add_u32_e32 v138, s60, v219
	s_waitcnt lgkmcnt(0)
	v_mfma_f32_32x32x16_bf16 v[98:113], v[142:145], v[134:137], v[98:113]
	ds_read_b128 v[134:137], v138 offset:49152
	ds_read_b128 v[138:141], v138 offset:57344
	s_waitcnt lgkmcnt(1)
	v_mfma_f32_32x32x16_bf16 v[114:129], v[134:137], v[130:133], v[114:129]
	s_waitcnt lgkmcnt(0)
	v_mfma_f32_32x32x16_bf16 v[98:113], v[138:141], v[130:133], v[98:113]
	s_cmp_lt_u32 s31, 4
	s_cbranch_scc1 .Ldp_7
	s_waitcnt vmcnt(0) lgkmcnt(0)
	s_barrier
.Ldp_7:
	v_add_f32_e32 v130, 0, v66
	v_add_f32_e32 v130, v67, v130
	v_add_f32_e32 v130, v68, v130
	v_add_f32_e32 v130, v69, v130
	v_add_f32_e32 v130, v70, v130
	v_add_f32_e32 v130, v71, v130
	v_add_f32_e32 v130, v72, v130
	v_add_f32_e32 v130, v73, v130
	v_add_f32_e32 v130, v74, v130
	v_add_f32_e32 v130, v75, v130
	v_add_f32_e32 v130, v76, v130
	v_add_f32_e32 v130, v77, v130
	v_add_f32_e32 v130, v78, v130
	v_add_f32_e32 v130, v79, v130
	v_add_f32_e32 v130, v80, v130
	v_add_f32_e32 v130, v81, v130
	v_add_f32_e32 v130, v82, v130
	v_add_f32_e32 v130, v83, v130
	v_add_f32_e32 v130, v84, v130
	v_add_f32_e32 v130, v85, v130
	v_add_f32_e32 v130, v86, v130
	v_add_f32_e32 v130, v87, v130
	v_add_f32_e32 v130, v88, v130
	v_add_f32_e32 v130, v89, v130
	v_add_f32_e32 v130, v90, v130
	v_add_f32_e32 v130, v91, v130
	v_add_f32_e32 v130, v92, v130
	v_add_f32_e32 v130, v93, v130
	v_add_f32_e32 v130, v94, v130
	v_add_f32_e32 v130, v95, v130
	v_add_f32_e32 v130, v96, v130
	v_add_f32_e32 v130, v97, v130
	v_mov_b32_e32 v131, v130
	v_cvt_pk_bf16_f32 v66, v66, v67
	v_cvt_pk_bf16_f32 v67, v68, v69
	v_cvt_pk_bf16_f32 v68, v70, v71
	v_cvt_pk_bf16_f32 v69, v72, v73
	v_cvt_pk_bf16_f32 v70, v74, v75
	v_cvt_pk_bf16_f32 v71, v76, v77
	v_cvt_pk_bf16_f32 v72, v78, v79
	v_cvt_pk_bf16_f32 v73, v80, v81
	v_cvt_pk_bf16_f32 v74, v82, v83
	v_cvt_pk_bf16_f32 v75, v84, v85
	v_cvt_pk_bf16_f32 v76, v86, v87
	v_cvt_pk_bf16_f32 v77, v88, v89
	v_cvt_pk_bf16_f32 v78, v90, v91
	v_cvt_pk_bf16_f32 v79, v92, v93
	v_cvt_pk_bf16_f32 v80, v94, v95
	v_cvt_pk_bf16_f32 v81, v96, v97
	v_permlane32_swap_b32_e32 v130, v131
	v_permlane32_swap_b32_e32 v66, v68
	v_permlane32_swap_b32_e32 v67, v69
	v_permlane32_swap_b32_e32 v70, v72
	v_permlane32_swap_b32_e32 v71, v73
	v_permlane32_swap_b32_e32 v74, v76
	v_permlane32_swap_b32_e32 v75, v77
	v_permlane32_swap_b32_e32 v78, v80
	v_permlane32_swap_b32_e32 v79, v81
	v_add_u32_e32 v132, s2, v221
	ds_read_b64_tr_b16 v[82:83], v132 offset:0
	ds_read_b64_tr_b16 v[84:85], v132 offset:0x800
	ds_read_b64_tr_b16 v[86:87], v132 offset:0x1000
	ds_read_b64_tr_b16 v[88:89], v132 offset:0x1800
	ds_read_b64_tr_b16 v[90:91], v132 offset:0x2000
	ds_read_b64_tr_b16 v[92:93], v132 offset:0x2800
	ds_read_b64_tr_b16 v[94:95], v132 offset:0x3000
	ds_read_b64_tr_b16 v[96:97], v132 offset:0x3800
	s_waitcnt lgkmcnt(0)
	s_nop 0
	v_mfma_f32_32x32x16_bf16 v[50:65], v[66:69], v[82:85], v[50:65]
	ds_read_b64_tr_b16 v[82:83], v132 offset:0x200
	ds_read_b64_tr_b16 v[84:85], v132 offset:0xa00
	v_mfma_f32_32x32x16_bf16 v[50:65], v[70:73], v[86:89], v[50:65]
	ds_read_b64_tr_b16 v[86:87], v132 offset:0x1200
	ds_read_b64_tr_b16 v[88:89], v132 offset:0x1a00
	v_mfma_f32_32x32x16_bf16 v[50:65], v[74:77], v[90:93], v[50:65]
	ds_read_b64_tr_b16 v[90:91], v132 offset:0x2200
	ds_read_b64_tr_b16 v[92:93], v132 offset:0x2a00
	v_mfma_f32_32x32x16_bf16 v[50:65], v[78:81], v[94:97], v[50:65]
	ds_read_b64_tr_b16 v[94:95], v132 offset:0x3200
	ds_read_b64_tr_b16 v[96:97], v132 offset:0x3a00
	s_waitcnt lgkmcnt(0)
	v_mfma_f32_32x32x16_bf16 v[34:49], v[66:69], v[82:85], v[34:49]
	ds_read_b64_tr_b16 v[82:83], v132 offset:0x400
	ds_read_b64_tr_b16 v[84:85], v132 offset:0xc00
	v_mfma_f32_32x32x16_bf16 v[34:49], v[70:73], v[86:89], v[34:49]
	ds_read_b64_tr_b16 v[86:87], v132 offset:0x1400
	ds_read_b64_tr_b16 v[88:89], v132 offset:0x1c00
	v_mfma_f32_32x32x16_bf16 v[34:49], v[74:77], v[90:93], v[34:49]
	ds_read_b64_tr_b16 v[90:91], v132 offset:0x2400
	ds_read_b64_tr_b16 v[92:93], v132 offset:0x2c00
	v_mfma_f32_32x32x16_bf16 v[34:49], v[78:81], v[94:97], v[34:49]
	ds_read_b64_tr_b16 v[94:95], v132 offset:0x3400
	ds_read_b64_tr_b16 v[96:97], v132 offset:0x3c00
	s_waitcnt lgkmcnt(0)
	v_mfma_f32_32x32x16_bf16 v[18:33], v[66:69], v[82:85], v[18:33]
	ds_read_b64_tr_b16 v[82:83], v132 offset:0x600
	ds_read_b64_tr_b16 v[84:85], v132 offset:0xe00
	v_mfma_f32_32x32x16_bf16 v[18:33], v[70:73], v[86:89], v[18:33]
	ds_read_b64_tr_b16 v[86:87], v132 offset:0x1600
	ds_read_b64_tr_b16 v[88:89], v132 offset:0x1e00
	v_mfma_f32_32x32x16_bf16 v[18:33], v[74:77], v[90:93], v[18:33]
	ds_read_b64_tr_b16 v[90:91], v132 offset:0x2600
	ds_read_b64_tr_b16 v[92:93], v132 offset:0x2e00
	v_mfma_f32_32x32x16_bf16 v[18:33], v[78:81], v[94:97], v[18:33]
	ds_read_b64_tr_b16 v[94:95], v132 offset:0x3600
	ds_read_b64_tr_b16 v[96:97], v132 offset:0x3e00
	s_waitcnt lgkmcnt(0)
	v_mfma_f32_32x32x16_bf16 v[2:17], v[66:69], v[82:85], v[2:17]
	v_add_u32_e32 v66, s72, v208
	v_cmp_gt_i32_e64 s[0:1], s95, v66
	v_cmp_lt_i32_e32 vcc, s15, v66
	v_mov_b32_e32 v133, s76
	v_mfma_f32_32x32x16_bf16 v[2:17], v[70:73], v[86:89], v[2:17]
	v_mfma_f32_32x32x16_bf16 v[2:17], v[74:77], v[90:93], v[2:17]
	v_mfma_f32_32x32x16_bf16 v[2:17], v[78:81], v[94:97], v[2:17]
	s_and_saveexec_b64 s[58:59], vcc
	s_cbranch_execz .LBB0_206
; template <int MODE>
; __device__ __forceinline__ void partialSM(f32x16& p0, f32x16& p1, float& m_reg, float& mn, float& alpha, int relh, int relw_min, int relw_max, const float* lut) {
;     ...
;     if (nearT) {
; #pragma unroll
;       for (int r = 0; r < 16; ++r) { const int i0 = relh + (r & 3) + 8 * (r >> 2);
;         const int a0 = min(max(i0, -129), 129) + 129, a1 = min(max(i0 + 32, -129), 129) + 129;
;         p0[r] = fmaf(p0[r], C, lut[a0]); p1[r] = fmaf(p1[r], C, lut[a1]); }
;     } else {
; #pragma unroll
;       for (int r = 0; r < 16; ++r) { p0[r] = fmaf(p0[r], C, cfar); p1[r] = fmaf(p1[r], C, cfar); }
;     }
;     float pmax = p0[0];
; #pragma unroll
;     for (int r = 1; r < 16; ++r) pmax = fmaxf(pmax, p0[r]);
; #pragma unroll
;     for (int r = 0; r < 16; ++r) pmax = fmaxf(pmax, p1[r]);
	v_add_u32_e32 v66, s72, v207
	v_cmp_gt_i32_e32 vcc, s91, v66
	s_mov_b64 s[62:63], -1
	s_and_saveexec_b64 s[60:61], vcc
	s_cbranch_execz .LBB0_204
	v_add_u32_e32 v78, s72, v206
	v_add_u32_e32 v68, 1, v78
	v_add_u32_e32 v70, 2, v78
	v_add_u32_e32 v72, 3, v78
	v_med3_i32 v66, v78, s39, v198
	v_med3_i32 v67, v78, s33, v199
	v_med3_i32 v69, v68, s39, v198
	v_med3_i32 v68, v68, s33, v199
	v_med3_i32 v71, v70, s39, v198
	v_med3_i32 v70, v70, s33, v199
	v_med3_i32 v73, v72, s39, v198
	v_med3_i32 v72, v72, s33, v199
	v_lshl_add_u32 v66, v66, 2, s76
	v_lshl_add_u32 v67, v67, 2, s76
	v_lshl_add_u32 v69, v69, 2, s76
	v_lshl_add_u32 v68, v68, 2, s76
	v_lshl_add_u32 v70, v70, 2, s76
	v_lshl_add_u32 v72, v72, 2, s76
	v_lshl_add_u32 v71, v71, 2, s76
	v_lshl_add_u32 v73, v73, 2, s76
	ds_read_b32 v133, v66 offset:516
	ds_read_b32 v66, v67 offset:644
	ds_read_b32 v134, v69 offset:516
	ds_read_b32 v67, v68 offset:644
	ds_read_b32 v135, v71 offset:516
	ds_read_b32 v68, v70 offset:644
	ds_read_b32 v136, v73 offset:516
	ds_read_b32 v69, v72 offset:644
	v_add_u32_e32 v70, 8, v78
	v_add_u32_e32 v72, 9, v78
	v_add_u32_e32 v74, 10, v78
	v_add_u32_e32 v76, 11, v78
	v_med3_i32 v71, v70, s39, v198
	v_med3_i32 v70, v70, s33, v199
	v_med3_i32 v73, v72, s39, v198
	v_med3_i32 v72, v72, s33, v199
	v_med3_i32 v75, v74, s39, v198
	v_med3_i32 v74, v74, s33, v199
	v_med3_i32 v77, v76, s39, v198
	v_med3_i32 v76, v76, s33, v199
	v_lshl_add_u32 v71, v71, 2, s76
	v_lshl_add_u32 v70, v70, 2, s76
	v_lshl_add_u32 v73, v73, 2, s76
	v_lshl_add_u32 v72, v72, 2, s76
	v_lshl_add_u32 v74, v74, 2, s76
	v_lshl_add_u32 v76, v76, 2, s76
	v_lshl_add_u32 v75, v75, 2, s76
	v_lshl_add_u32 v77, v77, 2, s76
	ds_read_b32 v137, v71 offset:516
	ds_read_b32 v70, v70 offset:644
	ds_read_b32 v138, v73 offset:516
	ds_read_b32 v71, v72 offset:644
	ds_read_b32 v139, v75 offset:516
	ds_read_b32 v72, v74 offset:644
	ds_read_b32 v140, v77 offset:516
	ds_read_b32 v73, v76 offset:644
	v_add_u32_e32 v74, 16, v78
	v_add_u32_e32 v76, 17, v78
	v_add_u32_e32 v79, 18, v78
	v_add_u32_e32 v81, 19, v78
	v_med3_i32 v75, v74, s39, v198
	v_med3_i32 v74, v74, s33, v199
	v_med3_i32 v77, v76, s39, v198
	v_med3_i32 v76, v76, s33, v199
	v_med3_i32 v80, v79, s39, v198
	v_med3_i32 v79, v79, s33, v199
	v_med3_i32 v82, v81, s39, v198
	v_med3_i32 v81, v81, s33, v199
	v_lshl_add_u32 v75, v75, 2, s76
	v_lshl_add_u32 v74, v74, 2, s76
	v_lshl_add_u32 v77, v77, 2, s76
	v_lshl_add_u32 v76, v76, 2, s76
	v_lshl_add_u32 v79, v79, 2, s76
	v_lshl_add_u32 v81, v81, 2, s76
	v_lshl_add_u32 v80, v80, 2, s76
	v_lshl_add_u32 v82, v82, 2, s76
	ds_read_b32 v141, v75 offset:516
	ds_read_b32 v74, v74 offset:644
	ds_read_b32 v142, v77 offset:516
	ds_read_b32 v75, v76 offset:644
	ds_read_b32 v143, v80 offset:516
	ds_read_b32 v76, v79 offset:644
	ds_read_b32 v144, v82 offset:516
	ds_read_b32 v77, v81 offset:644
	v_add_u32_e32 v79, 24, v78
	v_add_u32_e32 v81, 25, v78
	v_med3_i32 v80, v79, s39, v198
	v_med3_i32 v79, v79, s33, v199
	v_med3_i32 v82, v81, s39, v198
	v_med3_i32 v81, v81, s33, v199
	v_add_u32_e32 v83, 26, v78
	v_add_u32_e32 v78, 27, v78
	s_waitcnt lgkmcnt(14)
	v_fmac_f32_e32 v133, 0x3e38aa3b, v114
	v_fmac_f32_e32 v134, 0x3e38aa3b, v115
	v_lshl_add_u32 v80, v80, 2, s76
	v_lshl_add_u32 v79, v79, 2, s76
	v_lshl_add_u32 v82, v82, 2, s76
	v_lshl_add_u32 v81, v81, 2, s76
	v_med3_i32 v84, v83, s39, v198
	v_med3_i32 v83, v83, s33, v199
	v_med3_i32 v85, v78, s39, v198
	v_med3_i32 v78, v78, s33, v199
	v_fmac_f32_e32 v135, 0x3e38aa3b, v116
	v_fmac_f32_e32 v136, 0x3e38aa3b, v117
	v_lshl_add_u32 v84, v84, 2, s76
	v_lshl_add_u32 v83, v83, 2, s76
	v_lshl_add_u32 v85, v85, 2, s76
	v_lshl_add_u32 v86, v78, 2, s76
	ds_read_b32 v145, v80 offset:516
	ds_read_b32 v78, v79 offset:644
	ds_read_b32 v146, v82 offset:516
	ds_read_b32 v79, v81 offset:644
	ds_read_b32 v147, v84 offset:516
	ds_read_b32 v80, v83 offset:644
	ds_read_b32 v148, v85 offset:516
	ds_read_b32 v81, v86 offset:644
	v_max_f32_e32 v82, v133, v134
	v_fmac_f32_e32 v137, 0x3e38aa3b, v118
	s_waitcnt lgkmcnt(14)
; template <int MODE>
; __device__ __forceinline__ void partialSM(f32x16& p0, f32x16& p1, float& m_reg, float& mn, float& alpha, int relh, int relw_min, int relw_max, const float* lut) {
;     ...
;     float pmax = p0[0];
; #pragma unroll
;     for (int r = 1; r < 16; ++r) pmax = fmaxf(pmax, p0[r]);
; #pragma unroll
;     for (int r = 0; r < 16; ++r) pmax = fmaxf(pmax, p1[r]);
;     { auto rr = __builtin_amdgcn_permlane32_swap(__float_as_uint(pmax), __float_as_uint(pmax), false, false);
;       pmax = fmaxf(__uint_as_float(rr[0]), __uint_as_float(rr[1])); }
;     if (__builtin_expect(__all(pmax - m_reg <= THR2), 1)) { mn = m_reg; alpha = 1.f; }
;     else { mn = fmaxf(m_reg, pmax); alpha = __builtin_amdgcn_exp2f(m_reg - mn); m_reg = mn; }
; #pragma unroll
;     for (int r = 0; r < 16; ++r) p0[r] = __builtin_amdgcn_exp2f(p0[r] - mn);
; #pragma unroll
;     for (int r = 0; r < 16; ++r) p1[r] = p1[r] - mn;
	v_fmac_f32_e32 v138, 0x3e38aa3b, v119
	v_max3_f32 v82, v82, v135, v136
	v_fmac_f32_e32 v139, 0x3e38aa3b, v120
	v_fmac_f32_e32 v140, 0x3e38aa3b, v121
	v_max3_f32 v82, v82, v137, v138
	v_fmac_f32_e32 v141, 0x3e38aa3b, v122
	s_waitcnt lgkmcnt(13)
	v_fmac_f32_e32 v142, 0x3e38aa3b, v123
	v_max3_f32 v82, v82, v139, v140
	s_waitcnt lgkmcnt(11)
	v_fmac_f32_e32 v143, 0x3e38aa3b, v124
	s_waitcnt lgkmcnt(9)
	v_fmac_f32_e32 v144, 0x3e38aa3b, v125
	v_max3_f32 v82, v82, v141, v142
	s_waitcnt lgkmcnt(7)
	v_fmac_f32_e32 v145, 0x3e38aa3b, v126
	s_waitcnt lgkmcnt(5)
	v_fmac_f32_e32 v146, 0x3e38aa3b, v127
	v_max3_f32 v82, v82, v143, v144
	s_waitcnt lgkmcnt(3)
	v_fmac_f32_e32 v147, 0x3e38aa3b, v128
	s_waitcnt lgkmcnt(1)
	v_fmac_f32_e32 v148, 0x3e38aa3b, v129
	v_max3_f32 v82, v82, v145, v146
	v_max3_f32 v84, v82, v147, v148
	v_pk_fma_f32 v[82:83], v[98:99], s[48:49], v[66:67] op_sel_hi:[1,0,1]
	v_pk_fma_f32 v[86:87], v[102:103], s[48:49], v[70:71] op_sel_hi:[1,0,1]
	v_max3_f32 v66, v84, v82, v83
	v_pk_fma_f32 v[84:85], v[100:101], s[48:49], v[68:69] op_sel_hi:[1,0,1]
	v_pk_fma_f32 v[88:89], v[104:105], s[48:49], v[72:73] op_sel_hi:[1,0,1]
	v_max3_f32 v66, v66, v84, v85
	v_max3_f32 v66, v66, v86, v87
	v_max3_f32 v66, v66, v88, v89
	v_pk_fma_f32 v[90:91], v[106:107], s[48:49], v[74:75] op_sel_hi:[1,0,1]
	v_pk_fma_f32 v[92:93], v[108:109], s[48:49], v[76:77] op_sel_hi:[1,0,1]
	v_max3_f32 v66, v66, v90, v91
	v_max3_f32 v66, v66, v92, v93
	v_pk_fma_f32 v[94:95], v[110:111], s[48:49], v[78:79] op_sel_hi:[1,0,1]
	s_waitcnt lgkmcnt(0)
	v_pk_fma_f32 v[96:97], v[112:113], s[48:49], v[80:81] op_sel_hi:[1,0,1]
	v_max3_f32 v66, v66, v94, v95
	v_max3_f32 v66, v66, v96, v97
	v_mov_b32_e32 v67, v66
	s_nop 1
	v_permlane32_swap_b32_e32 v66, v67
	v_max_f32_e32 v67, v67, v67
	v_max_f32_e32 v66, v66, v66
	v_max_f32_e32 v66, v66, v67
	v_sub_f32_e32 v67, v66, v222
	v_cmp_ge_f32_e32 vcc, s94, v67
	v_max_f32_e32 v67, v222, v222
	v_max_f32_e32 v66, v67, v66
	v_sub_f32_e32 v67, v222, v66
	v_exp_f32_e32 v67, v67
	s_cmp_eq_u64 vcc, exec
	s_cselect_b64 vcc, -1, 0
	v_cndmask_b32_e32 v149, v66, v222, vcc
	v_cndmask_b32_e64 v132, v67, 1.0, vcc
	v_sub_f32_e32 v66, v133, v149
	v_sub_f32_e32 v67, v134, v149
	v_sub_f32_e32 v68, v135, v149
	v_sub_f32_e32 v69, v136, v149
	v_sub_f32_e32 v70, v137, v149
	v_sub_f32_e32 v71, v138, v149
	v_sub_f32_e32 v72, v139, v149
	v_sub_f32_e32 v73, v140, v149
	v_sub_f32_e32 v74, v141, v149
	v_sub_f32_e32 v75, v142, v149
	v_sub_f32_e32 v76, v143, v149
	v_sub_f32_e32 v77, v144, v149
	v_sub_f32_e32 v78, v145, v149
	v_sub_f32_e32 v79, v146, v149
	v_sub_f32_e32 v80, v147, v149
	v_sub_f32_e32 v81, v148, v149
	v_exp_f32_e32 v66, v66
	v_exp_f32_e32 v67, v67
	v_exp_f32_e32 v68, v68
	v_exp_f32_e32 v69, v69
	v_exp_f32_e32 v70, v70
	v_exp_f32_e32 v71, v71
	v_exp_f32_e32 v72, v72
	v_exp_f32_e32 v73, v73
	v_exp_f32_e32 v74, v74
	v_exp_f32_e32 v75, v75
	v_exp_f32_e32 v76, v76
	v_exp_f32_e32 v77, v77
	v_exp_f32_e32 v78, v78
	v_exp_f32_e32 v79, v79
	v_exp_f32_e32 v80, v80
	v_exp_f32_e32 v81, v81
	v_sub_f32_e32 v97, v97, v149
	v_sub_f32_e32 v96, v96, v149
	v_sub_f32_e32 v95, v95, v149
	v_sub_f32_e32 v94, v94, v149
	v_sub_f32_e32 v93, v93, v149
	v_sub_f32_e32 v92, v92, v149
	v_sub_f32_e32 v91, v91, v149
	v_sub_f32_e32 v90, v90, v149
	v_sub_f32_e32 v89, v89, v149
	v_sub_f32_e32 v88, v88, v149
	v_sub_f32_e32 v87, v87, v149
	v_sub_f32_e32 v86, v86, v149
	v_sub_f32_e32 v85, v85, v149
	v_sub_f32_e32 v84, v84, v149
	v_sub_f32_e32 v83, v83, v149
	v_sub_f32_e32 v82, v82, v149
	s_xor_b64 s[62:63], exec, -1
